# mid-segment s_setprio 0 / s_setprio 1 pairs between the two 16-MFMA groups removed (32 sites; priority stays 1 through the segment); on top of v67
# speedup vs baseline: 1.0046x; 1.0010x over previous
;     __host__ __device__ __forceinline__ bool next(int i, Unit& u) const { const int vv = vid + (i / 5) * G; if (vv >= 256) return false; u.pm = vv >> 2; u.pn = (vv & 3) + 4 * (i % 5); return true; }
; #define PG8_STAGE(bufoff, gbase, voff) do { _Pragma("unroll") for (int _i = 0; _i < 2; ++_i) \
;         __builtin_amdgcn_global_load_lds((const unsigned*)((const char*)(gbase) + (voff)[_i]), (PG8_LAS unsigned*)(lds + (bufoff) + ldsw + _i * 8192), 16, 0, 0); } while (0)
; #define PG8_LDA(dst, b, h) do { _Pragma("unroll") for (int m = 0; m < 4; ++m) _Pragma("unroll") for (int k = 0; k < 2; ++k) dst[m][k] = *(const PG8_LAS bf16x8*)(lds + PG8_SA(b, h) + aoff + m * 2048 + k * 1024); } while (0)
; #define PG8_LDB(dst, b, h) do { _Pragma("unroll") for (int n = 0; n < 2; ++n) _Pragma("unroll") for (int k = 0; k < 2; ++k) dst[n][k] = *(const PG8_LAS bf16x8*)(lds + PG8_SB(b, h) + boff + n * 2048 + k * 1024); } while (0)
; #define PG8_WAIT_V(n) asm volatile("s_waitcnt vmcnt(" #n ")" ::: "memory")
;     ...
;         const bool has_next = S.next(ui + 1, nxt);
;         const char* nA = has_next ? (const char*)g.A + (size_t)nxt.pm * tstepA + (size_t)nxt.pn * APN + kofA : cA; const char* nB = has_next ? (const char*)g.Bt + (size_t)nxt.pn * tstepB + S.b_off(nxt) + kofB : cB;
;         for (int t = 0; t < nt; t += 2) {
;             const bool last = (t == nt - 2);
;             const char* a1 = cA + (ptrdiff_t)(t + 1) * kstepA;
;             const char* a2 = last ? nA : cA + (ptrdiff_t)(t + 2) * kstepA; const char* b2 = last ? nB : cB + (ptrdiff_t)(t + 2) * kstep;
;             const char* a3 = a2 + kstepA; const char* b3 = b2 + kstep;
;             if (last && has_next) S.a_ready(nxt);
;             if constexpr (SP2) {
;             PG8_LDB(B0, 0, 0); PG8_LDB(B1, 0, 1); PG8_SCHED; PG8_LDA(At, 0, 0); PG8_STAGE(PG8_SA(1, 1), a1 + hstepA, voffA);
;             PG8_WAIT_V(8); PG8_WAIT_L(0); PG8_BAR; PG8_MMA(0, 0, At, B0); PG8_MMA(0, 1, At, B1); PG8_BAR; PG8_SCHED;
;             PG8_LDA(At, 0, 1); PG8_STAGE(PG8_SB(0, 0), b2, voffB); PG8_STAGE(PG8_SB(0, 1), b2 + hstepB, voffB); PG8_STAGE(PG8_SA(0, 0), a2, voffA);
;             PG8_WAIT_V(8); PG8_WAIT_L(0); PG8_BAR; PG8_MMA(1, 0, At, B0); PG8_MMA(1, 1, At, B1); PG8_BAR; PG8_SCHED;
;     __device__ __forceinline__ size_t b_off(const pg8::Unit& u) const { return (size_t)(u.pm >> 3) * 4 * 131072; }
.LBB0_97:
	s_mov_b64 s[30:31], s[6:7]
	s_ashr_i32 s6, s14, 2
	s_and_b32 s6, s6, -8
	s_and_b32 s7, s14, 7
	s_mov_b32 s20, s58
	s_mov_b32 s21, s57
	v_cmp_lt_i64_e64 s[4:5], s[14:15], v[138:139]
	s_bfe_u32 s57, s14, 0x20003
	s_or_b32 s58, s6, s7
	s_and_b64 s[6:7], s[4:5], exec
	s_cselect_b32 s24, s58, s20
	s_cselect_b32 s6, s57, s21
	s_ashr_i32 s25, s24, 31
	s_lshl_b64 s[20:21], s[24:25], 20
	s_add_u32 s20, s2, s20
	s_addc_u32 s21, s3, s21
	s_ashr_i32 s7, s6, 31
	s_lshl_b64 s[6:7], s[6:7], 17
	s_add_u32 s20, s20, s6
	s_addc_u32 s21, s21, s7
	s_and_b64 s[28:29], s[4:5], exec
	ds_read_b128 v[0:3], v141
	ds_read_b128 v[4:7], v141 offset:1024
	ds_read_b128 v[8:11], v141 offset:2048
	ds_read_b128 v[12:15], v141 offset:3072
	ds_read_b128 v[16:19], v142
	ds_read_b128 v[20:23], v142 offset:1024
	ds_read_b128 v[24:27], v142 offset:2048
	ds_read_b128 v[28:31], v142 offset:3072
	s_cselect_b32 s29, s21, s27
	s_cselect_b32 s28, s20, s26
	s_add_u32 s25, s33, s6
	s_addc_u32 s34, s36, s7
	s_ashr_i32 s6, s24, 3
	s_ashr_i32 s7, s6, 31
	s_lshl_b64 s[6:7], s[6:7], 19
	s_add_u32 s6, s25, s6
	s_addc_u32 s7, s34, s7
	s_and_b64 s[24:25], s[4:5], exec
	s_cselect_b32 s25, s7, s31
	s_cselect_b32 s24, s6, s30
	s_add_u32 s60, s26, 0x10000
	s_addc_u32 s61, s27, 0
	s_add_u32 s34, s26, 0x18000
	s_addc_u32 s35, s27, 0
	s_add_u32 s62, s26, 0xc000
	s_addc_u32 s63, s27, 0
	s_mov_b32 m0, s46
	ds_read_b128 v[32:35], v143
	ds_read_b128 v[36:39], v143 offset:1024
	ds_read_b128 v[40:43], v143 offset:2048
	ds_read_b128 v[44:47], v143 offset:3072
	ds_read_b128 v[48:51], v143 offset:4096
	ds_read_b128 v[52:55], v143 offset:5120
	ds_read_b128 v[56:59], v143 offset:6144
	ds_read_b128 v[60:63], v143 offset:7168
	global_load_lds_dwordx4 v134, s[62:63]
	v_lshl_add_u64 v[64:65], s[62:63], 0, v[130:131]
	s_mov_b32 m0, s47
	s_nop 0
	global_load_lds_dwordx4 v[64:65], off
	s_waitcnt vmcnt(8)
	s_waitcnt lgkmcnt(0)
	s_barrier
	s_setprio 1
	v_mfma_f32_16x16x32_bf16 v[64:67], v[0:3], v[32:35], 0
	v_mfma_f32_16x16x32_bf16 v[64:67], v[4:7], v[36:39], v[64:67]
	v_mfma_f32_16x16x32_bf16 v[68:71], v[8:11], v[32:35], 0
	v_mfma_f32_16x16x32_bf16 v[68:71], v[12:15], v[36:39], v[68:71]
	v_mfma_f32_16x16x32_bf16 v[72:75], v[0:3], v[40:43], 0
	v_mfma_f32_16x16x32_bf16 v[72:75], v[4:7], v[44:47], v[72:75]
	v_mfma_f32_16x16x32_bf16 v[76:79], v[8:11], v[40:43], 0
	v_mfma_f32_16x16x32_bf16 v[76:79], v[12:15], v[44:47], v[76:79]
	v_mfma_f32_16x16x32_bf16 v[80:83], v[0:3], v[48:51], 0
	v_mfma_f32_16x16x32_bf16 v[80:83], v[4:7], v[52:55], v[80:83]
	v_mfma_f32_16x16x32_bf16 v[84:87], v[8:11], v[48:51], 0
	v_mfma_f32_16x16x32_bf16 v[84:87], v[12:15], v[52:55], v[84:87]
	v_mfma_f32_16x16x32_bf16 v[88:91], v[0:3], v[56:59], 0
	v_mfma_f32_16x16x32_bf16 v[88:91], v[4:7], v[60:63], v[88:91]
	v_mfma_f32_16x16x32_bf16 v[92:95], v[8:11], v[56:59], 0
	v_mfma_f32_16x16x32_bf16 v[92:95], v[12:15], v[60:63], v[92:95]
	v_mfma_f32_16x16x32_bf16 v[96:99], v[16:19], v[32:35], 0
	v_mfma_f32_16x16x32_bf16 v[96:99], v[20:23], v[36:39], v[96:99]
	v_mfma_f32_16x16x32_bf16 v[32:35], v[24:27], v[32:35], 0
	v_mfma_f32_16x16x32_bf16 v[32:35], v[28:31], v[36:39], v[32:35]
	v_mfma_f32_16x16x32_bf16 v[36:39], v[16:19], v[40:43], 0
	v_mfma_f32_16x16x32_bf16 v[36:39], v[20:23], v[44:47], v[36:39]
	v_mfma_f32_16x16x32_bf16 v[40:43], v[24:27], v[40:43], 0
	v_mfma_f32_16x16x32_bf16 v[40:43], v[28:31], v[44:47], v[40:43]
	v_mfma_f32_16x16x32_bf16 v[44:47], v[16:19], v[48:51], 0
	v_mfma_f32_16x16x32_bf16 v[44:47], v[20:23], v[52:55], v[44:47]
	v_mfma_f32_16x16x32_bf16 v[48:51], v[24:27], v[48:51], 0
	v_mfma_f32_16x16x32_bf16 v[48:51], v[28:31], v[52:55], v[48:51]
	v_mfma_f32_16x16x32_bf16 v[52:55], v[16:19], v[56:59], 0
	v_mfma_f32_16x16x32_bf16 v[52:55], v[20:23], v[60:63], v[52:55]
	v_mfma_f32_16x16x32_bf16 v[56:59], v[24:27], v[56:59], 0
	v_mfma_f32_16x16x32_bf16 v[56:59], v[28:31], v[60:63], v[56:59]
	s_barrier
	s_setprio 0
	v_lshl_add_u64 v[210:211], s[30:31], 0, v[132:133]
	s_mov_b32 m0, s48
	v_lshl_add_u64 v[146:147], v[210:211], 0, s[16:17]
	v_lshl_add_u64 v[212:213], s[30:31], 0, v[128:129]
	s_add_u32 s62, s30, 0x10100
	ds_read_b128 v[60:63], v143 offset:16384
	ds_read_b128 v[100:103], v143 offset:17408
	ds_read_b128 v[104:107], v143 offset:18432
	ds_read_b128 v[108:111], v143 offset:19456
	ds_read_b128 v[112:115], v143 offset:20480
	ds_read_b128 v[116:119], v143 offset:21504
	ds_read_b128 v[120:123], v143 offset:22528
	ds_read_b128 v[124:127], v143 offset:23552
	global_load_lds_dwordx4 v[146:147], off
	v_lshl_add_u64 v[146:147], v[212:213], 0, s[16:17]
	s_mov_b32 m0, s50
	s_addc_u32 s63, s31, 0
	global_load_lds_dwordx4 v[146:147], off
	s_mov_b32 m0, s51
	s_nop 0
	global_load_lds_dwordx4 v132, s[62:63]
	s_mov_b32 m0, s52
	s_nop 0
	global_load_lds_dwordx4 v128, s[62:63]
	s_mov_b32 m0, s23
	s_nop 0
	global_load_lds_dwordx4 v134, s[60:61]
	v_lshl_add_u64 v[146:147], s[60:61], 0, v[130:131]
	s_mov_b32 m0, s37
	s_nop 0
	global_load_lds_dwordx4 v[146:147], off
	s_waitcnt vmcnt(8)
	s_waitcnt lgkmcnt(0)
	s_barrier
; #define PG8_STAGE(bufoff, gbase, voff) do { _Pragma("unroll") for (int _i = 0; _i < 2; ++_i) \
;         __builtin_amdgcn_global_load_lds((const unsigned*)((const char*)(gbase) + (voff)[_i]), (PG8_LAS unsigned*)(lds + (bufoff) + ldsw + _i * 8192), 16, 0, 0); } while (0)
; #define PG8_LDA(dst, b, h) do { _Pragma("unroll") for (int m = 0; m < 4; ++m) _Pragma("unroll") for (int k = 0; k < 2; ++k) dst[m][k] = *(const PG8_LAS bf16x8*)(lds + PG8_SA(b, h) + aoff + m * 2048 + k * 1024); } while (0)
; #define PG8_LDB(dst, b, h) do { _Pragma("unroll") for (int n = 0; n < 2; ++n) _Pragma("unroll") for (int k = 0; k < 2; ++k) dst[n][k] = *(const PG8_LAS bf16x8*)(lds + PG8_SB(b, h) + boff + n * 2048 + k * 1024); } while (0)
; #define PG8_MMA(ai, bj, At, Bt) do { __builtin_amdgcn_s_setprio(1); _Pragma("unroll") for (int m = 0; m < 4; ++m) _Pragma("unroll") for (int n = 0; n < 2; ++n) _Pragma("unroll") for (int k = 0; k < 2; ++k) \
;         acc[ai][bj][m][n] = __builtin_amdgcn_mfma_f32_16x16x32_bf16(Bt[n][k], At[m][k], acc[ai][bj][m][n], 0, 0, 0); __builtin_amdgcn_s_setprio(0); } while (0)
; #define PG8_WAIT_V(n) asm volatile("s_waitcnt vmcnt(" #n ")" ::: "memory")
; #define PG8_WAIT_L(n) asm volatile("s_waitcnt lgkmcnt(" #n ")" ::: "memory")
; #define PG8_BAR __builtin_amdgcn_s_barrier()
; #define PG8_SCHED __builtin_amdgcn_sched_barrier(0)
;     ...
;             PG8_WAIT_V(8); PG8_WAIT_L(0); PG8_BAR; PG8_MMA(1, 0, At, B0); PG8_MMA(1, 1, At, B1); PG8_BAR; PG8_SCHED;
;             PG8_LDB(B0, 1, 0); PG8_LDB(B1, 1, 1); PG8_SCHED; PG8_LDA(At, 1, 0); PG8_STAGE(PG8_SA(0, 1), a2 + hstepA, voffA);
;             PG8_WAIT_V(8); PG8_WAIT_L(0); PG8_BAR; PG8_MMA(0, 0, At, B0); PG8_MMA(0, 1, At, B1); PG8_BAR; PG8_SCHED;
	s_setprio 1
	v_mfma_f32_16x16x32_bf16 v[146:149], v[0:3], v[60:63], 0
	v_mfma_f32_16x16x32_bf16 v[146:149], v[4:7], v[100:103], v[146:149]
	v_mfma_f32_16x16x32_bf16 v[154:157], v[0:3], v[104:107], 0
	v_mfma_f32_16x16x32_bf16 v[154:157], v[4:7], v[108:111], v[154:157]
	v_mfma_f32_16x16x32_bf16 v[162:165], v[0:3], v[112:115], 0
	v_mfma_f32_16x16x32_bf16 v[162:165], v[4:7], v[116:119], v[162:165]
	v_mfma_f32_16x16x32_bf16 v[0:3], v[0:3], v[120:123], 0
	v_mfma_f32_16x16x32_bf16 v[0:3], v[4:7], v[124:127], v[0:3]
	v_mfma_f32_16x16x32_bf16 v[4:7], v[8:11], v[120:123], 0
	v_mfma_f32_16x16x32_bf16 v[4:7], v[12:15], v[124:127], v[4:7]
	v_mfma_f32_16x16x32_bf16 v[150:153], v[8:11], v[60:63], 0
	v_mfma_f32_16x16x32_bf16 v[150:153], v[12:15], v[100:103], v[150:153]
	v_mfma_f32_16x16x32_bf16 v[158:161], v[8:11], v[104:107], 0
	v_mfma_f32_16x16x32_bf16 v[158:161], v[12:15], v[108:111], v[158:161]
	v_mfma_f32_16x16x32_bf16 v[166:169], v[8:11], v[112:115], 0
	v_mfma_f32_16x16x32_bf16 v[166:169], v[12:15], v[116:119], v[166:169]
	v_mfma_f32_16x16x32_bf16 v[8:11], v[16:19], v[60:63], 0
	v_mfma_f32_16x16x32_bf16 v[8:11], v[20:23], v[100:103], v[8:11]
	v_mfma_f32_16x16x32_bf16 v[12:15], v[24:27], v[60:63], 0
	v_mfma_f32_16x16x32_bf16 v[12:15], v[28:31], v[100:103], v[12:15]
	v_mfma_f32_16x16x32_bf16 v[60:63], v[16:19], v[104:107], 0
	v_mfma_f32_16x16x32_bf16 v[60:63], v[20:23], v[108:111], v[60:63]
	v_mfma_f32_16x16x32_bf16 v[100:103], v[24:27], v[104:107], 0
	v_mfma_f32_16x16x32_bf16 v[100:103], v[28:31], v[108:111], v[100:103]
	v_mfma_f32_16x16x32_bf16 v[104:107], v[16:19], v[112:115], 0
	v_mfma_f32_16x16x32_bf16 v[104:107], v[20:23], v[116:119], v[104:107]
	v_mfma_f32_16x16x32_bf16 v[16:19], v[16:19], v[120:123], 0
	v_mfma_f32_16x16x32_bf16 v[16:19], v[20:23], v[124:127], v[16:19]
	v_mfma_f32_16x16x32_bf16 v[108:111], v[24:27], v[112:115], 0
	v_mfma_f32_16x16x32_bf16 v[108:111], v[28:31], v[116:119], v[108:111]
	v_mfma_f32_16x16x32_bf16 v[20:23], v[24:27], v[120:123], 0
	v_mfma_f32_16x16x32_bf16 v[20:23], v[28:31], v[124:127], v[20:23]
	s_barrier
	s_setprio 0
	ds_read_b128 v[24:27], v144
	ds_read_b128 v[28:31], v144 offset:1024
	ds_read_b128 v[112:115], v144 offset:2048
	ds_read_b128 v[116:119], v144 offset:3072
	ds_read_b128 v[120:123], v145
	ds_read_b128 v[124:127], v145 offset:1024
	ds_read_b128 v[170:173], v145 offset:2048
	ds_read_b128 v[174:177], v145 offset:3072
	s_add_u32 s60, s26, 0x14000
	s_addc_u32 s61, s27, 0
	s_mov_b32 m0, s39
	ds_read_b128 v[178:181], v143 offset:32768
	ds_read_b128 v[182:185], v143 offset:33792
	ds_read_b128 v[186:189], v143 offset:34816
	ds_read_b128 v[190:193], v143 offset:35840
	ds_read_b128 v[194:197], v143 offset:36864
	ds_read_b128 v[198:201], v143 offset:37888
	ds_read_b128 v[202:205], v143 offset:38912
	ds_read_b128 v[206:209], v143 offset:39936
	global_load_lds_dwordx4 v134, s[60:61]
	v_lshl_add_u64 v[214:215], s[60:61], 0, v[130:131]
	s_mov_b32 m0, s40
	s_nop 0
	global_load_lds_dwordx4 v[214:215], off
	s_waitcnt vmcnt(8)
	s_waitcnt lgkmcnt(0)
	s_barrier
	s_setprio 1
	v_mfma_f32_16x16x32_bf16 v[64:67], v[24:27], v[178:181], v[64:67]
	v_mfma_f32_16x16x32_bf16 v[64:67], v[28:31], v[182:185], v[64:67]
	v_mfma_f32_16x16x32_bf16 v[68:71], v[116:119], v[182:185], v[68:71]
	v_mfma_f32_16x16x32_bf16 v[68:71], v[112:115], v[178:181], v[68:71]
	v_mfma_f32_16x16x32_bf16 v[76:79], v[112:115], v[186:189], v[76:79]
	v_mfma_f32_16x16x32_bf16 v[76:79], v[116:119], v[190:193], v[76:79]
	v_mfma_f32_16x16x32_bf16 v[72:75], v[28:31], v[190:193], v[72:75]
	v_mfma_f32_16x16x32_bf16 v[72:75], v[24:27], v[186:189], v[72:75]
	v_mfma_f32_16x16x32_bf16 v[80:83], v[24:27], v[194:197], v[80:83]
	v_mfma_f32_16x16x32_bf16 v[80:83], v[28:31], v[198:201], v[80:83]
	v_mfma_f32_16x16x32_bf16 v[84:87], v[116:119], v[198:201], v[84:87]
	v_mfma_f32_16x16x32_bf16 v[84:87], v[112:115], v[194:197], v[84:87]
	v_mfma_f32_16x16x32_bf16 v[92:95], v[112:115], v[202:205], v[92:95]
	v_mfma_f32_16x16x32_bf16 v[92:95], v[116:119], v[206:209], v[92:95]
	v_mfma_f32_16x16x32_bf16 v[88:91], v[28:31], v[206:209], v[88:91]
	v_mfma_f32_16x16x32_bf16 v[88:91], v[24:27], v[202:205], v[88:91]
	v_mfma_f32_16x16x32_bf16 v[96:99], v[120:123], v[178:181], v[96:99]
	v_mfma_f32_16x16x32_bf16 v[96:99], v[124:127], v[182:185], v[96:99]
	v_mfma_f32_16x16x32_bf16 v[32:35], v[174:177], v[182:185], v[32:35]
	v_mfma_f32_16x16x32_bf16 v[32:35], v[170:173], v[178:181], v[32:35]
	v_mfma_f32_16x16x32_bf16 v[40:43], v[170:173], v[186:189], v[40:43]
	v_mfma_f32_16x16x32_bf16 v[40:43], v[174:177], v[190:193], v[40:43]
	v_mfma_f32_16x16x32_bf16 v[36:39], v[124:127], v[190:193], v[36:39]
	v_mfma_f32_16x16x32_bf16 v[36:39], v[120:123], v[186:189], v[36:39]
	v_mfma_f32_16x16x32_bf16 v[44:47], v[120:123], v[194:197], v[44:47]
	v_mfma_f32_16x16x32_bf16 v[44:47], v[124:127], v[198:201], v[44:47]
	v_mfma_f32_16x16x32_bf16 v[48:51], v[174:177], v[198:201], v[48:51]
	v_mfma_f32_16x16x32_bf16 v[48:51], v[170:173], v[194:197], v[48:51]
	v_mfma_f32_16x16x32_bf16 v[56:59], v[170:173], v[202:205], v[56:59]
	v_mfma_f32_16x16x32_bf16 v[56:59], v[174:177], v[206:209], v[56:59]
	v_mfma_f32_16x16x32_bf16 v[52:55], v[124:127], v[206:209], v[52:55]
	v_mfma_f32_16x16x32_bf16 v[52:55], v[120:123], v[202:205], v[52:55]
	s_barrier
; #define PG8_STAGE(bufoff, gbase, voff) do { _Pragma("unroll") for (int _i = 0; _i < 2; ++_i) \
;         __builtin_amdgcn_global_load_lds((const unsigned*)((const char*)(gbase) + (voff)[_i]), (PG8_LAS unsigned*)(lds + (bufoff) + ldsw + _i * 8192), 16, 0, 0); } while (0)
; #define PG8_LDA(dst, b, h) do { _Pragma("unroll") for (int m = 0; m < 4; ++m) _Pragma("unroll") for (int k = 0; k < 2; ++k) dst[m][k] = *(const PG8_LAS bf16x8*)(lds + PG8_SA(b, h) + aoff + m * 2048 + k * 1024); } while (0)
; #define PG8_LDB(dst, b, h) do { _Pragma("unroll") for (int n = 0; n < 2; ++n) _Pragma("unroll") for (int k = 0; k < 2; ++k) dst[n][k] = *(const PG8_LAS bf16x8*)(lds + PG8_SB(b, h) + boff + n * 2048 + k * 1024); } while (0)
; #define PG8_MMA(ai, bj, At, Bt) do { __builtin_amdgcn_s_setprio(1); _Pragma("unroll") for (int m = 0; m < 4; ++m) _Pragma("unroll") for (int n = 0; n < 2; ++n) _Pragma("unroll") for (int k = 0; k < 2; ++k) \
;         acc[ai][bj][m][n] = __builtin_amdgcn_mfma_f32_16x16x32_bf16(Bt[n][k], At[m][k], acc[ai][bj][m][n], 0, 0, 0); __builtin_amdgcn_s_setprio(0); } while (0)
; #define PG8_WAIT_V(n) asm volatile("s_waitcnt vmcnt(" #n ")" ::: "memory")
; #define PG8_WAIT_L(n) asm volatile("s_waitcnt lgkmcnt(" #n ")" ::: "memory")
; #define PG8_BAR __builtin_amdgcn_s_barrier()
; #define PG8_SCHED __builtin_amdgcn_sched_barrier(0)
;     ...
;             PG8_LDB(B0, 0, 0); PG8_LDB(B1, 0, 1); PG8_SCHED; PG8_LDA(At, 0, 0); PG8_STAGE(PG8_SA(1, 1), a1 + hstepA, voffA);
;             PG8_WAIT_V(8); PG8_WAIT_L(0); PG8_BAR; PG8_MMA(0, 0, At, B0); PG8_MMA(0, 1, At, B1); PG8_BAR; PG8_SCHED;
;             PG8_LDA(At, 0, 1); PG8_STAGE(PG8_SB(0, 0), b2, voffB); PG8_STAGE(PG8_SB(0, 1), b2 + hstepB, voffB); PG8_STAGE(PG8_SA(0, 0), a2, voffA);
;             PG8_WAIT_V(8); PG8_WAIT_L(0); PG8_BAR; PG8_MMA(1, 0, At, B0); PG8_MMA(1, 1, At, B1); PG8_BAR; PG8_SCHED;
;             PG8_LDB(B0, 1, 0); PG8_LDB(B1, 1, 1); PG8_SCHED; PG8_LDA(At, 1, 0); PG8_STAGE(PG8_SA(0, 1), a2 + hstepA, voffA);
;             PG8_WAIT_V(8); PG8_WAIT_L(0); PG8_BAR; PG8_MMA(0, 0, At, B0); PG8_MMA(0, 1, At, B1); PG8_BAR; PG8_SCHED;
;             PG8_LDA(At, 1, 1); PG8_STAGE(PG8_SB(1, 0), b3, voffB); PG8_STAGE(PG8_SB(1, 1), b3 + hstepB, voffB); PG8_STAGE(PG8_SA(1, 0), a3, voffA);
;             PG8_WAIT_V(8); PG8_WAIT_L(0); PG8_BAR; PG8_MMA(1, 0, At, B0); PG8_MMA(1, 1, At, B1); PG8_BAR; PG8_SCHED;
	s_setprio 0
	s_mov_b32 m0, s53
	v_lshl_add_u64 v[210:211], v[210:211], 0, s[18:19]
	s_add_u32 s30, s30, 0x10180
	ds_read_b128 v[178:181], v143 offset:49152
	ds_read_b128 v[182:185], v143 offset:50176
	ds_read_b128 v[186:189], v143 offset:51200
	ds_read_b128 v[190:193], v143 offset:52224
	ds_read_b128 v[194:197], v143 offset:53248
	ds_read_b128 v[198:201], v143 offset:54272
	ds_read_b128 v[202:205], v143 offset:55296
	ds_read_b128 v[206:209], v143 offset:56320
	global_load_lds_dwordx4 v[210:211], off
	v_lshl_add_u64 v[210:211], v[212:213], 0, s[18:19]
	s_mov_b32 m0, s54
	s_addc_u32 s31, s31, 0
	global_load_lds_dwordx4 v[210:211], off
	s_mov_b32 m0, s55
	s_nop 0
	global_load_lds_dwordx4 v132, s[30:31]
	s_mov_b32 m0, s56
	s_nop 0
	global_load_lds_dwordx4 v128, s[30:31]
	s_mov_b32 m0, s42
	s_nop 0
	global_load_lds_dwordx4 v134, s[34:35]
	s_mov_b32 m0, s43
	s_nop 0
	global_load_lds_dwordx4 v130, s[34:35]
	s_waitcnt vmcnt(8)
	s_waitcnt lgkmcnt(0)
	s_barrier
	s_setprio 1
	v_mfma_f32_16x16x32_bf16 v[0:3], v[24:27], v[202:205], v[0:3]
	v_mfma_f32_16x16x32_bf16 v[0:3], v[28:31], v[206:209], v[0:3]
	v_mfma_f32_16x16x32_bf16 v[4:7], v[116:119], v[206:209], v[4:7]
	v_mfma_f32_16x16x32_bf16 v[4:7], v[112:115], v[202:205], v[4:7]
	v_mfma_f32_16x16x32_bf16 v[150:153], v[112:115], v[178:181], v[150:153]
	v_mfma_f32_16x16x32_bf16 v[150:153], v[116:119], v[182:185], v[150:153]
	v_mfma_f32_16x16x32_bf16 v[146:149], v[28:31], v[182:185], v[146:149]
	v_mfma_f32_16x16x32_bf16 v[146:149], v[24:27], v[178:181], v[146:149]
	v_mfma_f32_16x16x32_bf16 v[154:157], v[24:27], v[186:189], v[154:157]
	v_mfma_f32_16x16x32_bf16 v[154:157], v[28:31], v[190:193], v[154:157]
	v_mfma_f32_16x16x32_bf16 v[158:161], v[116:119], v[190:193], v[158:161]
	v_mfma_f32_16x16x32_bf16 v[158:161], v[112:115], v[186:189], v[158:161]
	v_mfma_f32_16x16x32_bf16 v[166:169], v[112:115], v[194:197], v[166:169]
	v_mfma_f32_16x16x32_bf16 v[166:169], v[116:119], v[198:201], v[166:169]
	v_mfma_f32_16x16x32_bf16 v[162:165], v[28:31], v[198:201], v[162:165]
	v_mfma_f32_16x16x32_bf16 v[162:165], v[24:27], v[194:197], v[162:165]
	v_mfma_f32_16x16x32_bf16 v[8:11], v[120:123], v[178:181], v[8:11]
	v_mfma_f32_16x16x32_bf16 v[8:11], v[124:127], v[182:185], v[8:11]
	v_mfma_f32_16x16x32_bf16 v[12:15], v[170:173], v[178:181], v[12:15]
	v_mfma_f32_16x16x32_bf16 v[12:15], v[174:177], v[182:185], v[12:15]
	v_mfma_f32_16x16x32_bf16 v[24:27], v[120:123], v[186:189], v[60:63]
	v_mfma_f32_16x16x32_bf16 v[24:27], v[124:127], v[190:193], v[24:27]
	v_mfma_f32_16x16x32_bf16 v[28:31], v[170:173], v[186:189], v[100:103]
	v_mfma_f32_16x16x32_bf16 v[28:31], v[174:177], v[190:193], v[28:31]
	v_mfma_f32_16x16x32_bf16 v[60:63], v[120:123], v[194:197], v[104:107]
	v_mfma_f32_16x16x32_bf16 v[60:63], v[124:127], v[198:201], v[60:63]
	v_mfma_f32_16x16x32_bf16 v[100:103], v[170:173], v[194:197], v[108:111]
	v_mfma_f32_16x16x32_bf16 v[100:103], v[174:177], v[198:201], v[100:103]
	v_mfma_f32_16x16x32_bf16 v[16:19], v[120:123], v[202:205], v[16:19]
	v_mfma_f32_16x16x32_bf16 v[16:19], v[124:127], v[206:209], v[16:19]
	v_mfma_f32_16x16x32_bf16 v[20:23], v[170:173], v[202:205], v[20:23]
	v_mfma_f32_16x16x32_bf16 v[20:23], v[174:177], v[206:209], v[20:23]
	s_barrier
	s_setprio 0
	ds_read_b128 v[104:107], v141
	ds_read_b128 v[108:111], v141 offset:1024
	ds_read_b128 v[112:115], v141 offset:2048
	ds_read_b128 v[116:119], v141 offset:3072
	ds_read_b128 v[120:123], v142
	ds_read_b128 v[124:127], v142 offset:1024
	ds_read_b128 v[170:173], v142 offset:2048
	ds_read_b128 v[174:177], v142 offset:3072
	s_add_u32 s30, s28, 0x8000
	s_addc_u32 s31, s29, 0
	s_add_u32 s26, s26, 0x1c000
	s_addc_u32 s27, s27, 0
	s_mov_b32 m0, s46
	ds_read_b128 v[178:181], v143
	ds_read_b128 v[182:185], v143 offset:1024
	ds_read_b128 v[186:189], v143 offset:2048
	ds_read_b128 v[190:193], v143 offset:3072
	ds_read_b128 v[194:197], v143 offset:4096
	ds_read_b128 v[198:201], v143 offset:5120
	ds_read_b128 v[202:205], v143 offset:6144
	ds_read_b128 v[206:209], v143 offset:7168
	global_load_lds_dwordx4 v134, s[26:27]
	v_lshl_add_u64 v[210:211], s[26:27], 0, v[130:131]
	s_mov_b32 m0, s47
	s_nop 0
	global_load_lds_dwordx4 v[210:211], off
	s_waitcnt vmcnt(8)
	s_waitcnt lgkmcnt(0)
	s_barrier
	s_setprio 1
	v_mfma_f32_16x16x32_bf16 v[64:67], v[104:107], v[178:181], v[64:67]
	v_mfma_f32_16x16x32_bf16 v[64:67], v[108:111], v[182:185], v[64:67]
	v_mfma_f32_16x16x32_bf16 v[68:71], v[112:115], v[178:181], v[68:71]
	v_mfma_f32_16x16x32_bf16 v[68:71], v[116:119], v[182:185], v[68:71]
	v_mfma_f32_16x16x32_bf16 v[72:75], v[104:107], v[186:189], v[72:75]
	v_mfma_f32_16x16x32_bf16 v[72:75], v[108:111], v[190:193], v[72:75]
	v_mfma_f32_16x16x32_bf16 v[76:79], v[112:115], v[186:189], v[76:79]
	v_mfma_f32_16x16x32_bf16 v[76:79], v[116:119], v[190:193], v[76:79]
	v_mfma_f32_16x16x32_bf16 v[80:83], v[104:107], v[194:197], v[80:83]
	v_mfma_f32_16x16x32_bf16 v[80:83], v[108:111], v[198:201], v[80:83]
	v_mfma_f32_16x16x32_bf16 v[84:87], v[112:115], v[194:197], v[84:87]
	v_mfma_f32_16x16x32_bf16 v[84:87], v[116:119], v[198:201], v[84:87]
	v_mfma_f32_16x16x32_bf16 v[88:91], v[104:107], v[202:205], v[88:91]
	v_mfma_f32_16x16x32_bf16 v[210:213], v[108:111], v[206:209], v[88:91]
	v_mfma_f32_16x16x32_bf16 v[88:91], v[112:115], v[202:205], v[92:95]
	v_mfma_f32_16x16x32_bf16 v[214:217], v[116:119], v[206:209], v[88:91]
	v_mfma_f32_16x16x32_bf16 v[88:91], v[120:123], v[178:181], v[96:99]
	v_mfma_f32_16x16x32_bf16 v[96:99], v[124:127], v[182:185], v[88:91]
	v_mfma_f32_16x16x32_bf16 v[32:35], v[170:173], v[178:181], v[32:35]
	v_mfma_f32_16x16x32_bf16 v[32:35], v[174:177], v[182:185], v[32:35]
	v_mfma_f32_16x16x32_bf16 v[36:39], v[120:123], v[186:189], v[36:39]
	v_mfma_f32_16x16x32_bf16 v[36:39], v[124:127], v[190:193], v[36:39]
	v_mfma_f32_16x16x32_bf16 v[40:43], v[170:173], v[186:189], v[40:43]
	v_mfma_f32_16x16x32_bf16 v[40:43], v[174:177], v[190:193], v[40:43]
	v_mfma_f32_16x16x32_bf16 v[44:47], v[120:123], v[194:197], v[44:47]
	v_mfma_f32_16x16x32_bf16 v[44:47], v[124:127], v[198:201], v[44:47]
	v_mfma_f32_16x16x32_bf16 v[48:51], v[170:173], v[194:197], v[48:51]
	v_mfma_f32_16x16x32_bf16 v[48:51], v[174:177], v[198:201], v[48:51]
	v_mfma_f32_16x16x32_bf16 v[52:55], v[120:123], v[202:205], v[52:55]
	v_mfma_f32_16x16x32_bf16 v[52:55], v[124:127], v[206:209], v[52:55]
	v_mfma_f32_16x16x32_bf16 v[56:59], v[170:173], v[202:205], v[56:59]
	v_mfma_f32_16x16x32_bf16 v[56:59], v[174:177], v[206:209], v[56:59]
	s_barrier
; #define PG8_STAGE(bufoff, gbase, voff) do { _Pragma("unroll") for (int _i = 0; _i < 2; ++_i) \
;         __builtin_amdgcn_global_load_lds((const unsigned*)((const char*)(gbase) + (voff)[_i]), (PG8_LAS unsigned*)(lds + (bufoff) + ldsw + _i * 8192), 16, 0, 0); } while (0)
; #define PG8_LDA(dst, b, h) do { _Pragma("unroll") for (int m = 0; m < 4; ++m) _Pragma("unroll") for (int k = 0; k < 2; ++k) dst[m][k] = *(const PG8_LAS bf16x8*)(lds + PG8_SA(b, h) + aoff + m * 2048 + k * 1024); } while (0)
; #define PG8_LDB(dst, b, h) do { _Pragma("unroll") for (int n = 0; n < 2; ++n) _Pragma("unroll") for (int k = 0; k < 2; ++k) dst[n][k] = *(const PG8_LAS bf16x8*)(lds + PG8_SB(b, h) + boff + n * 2048 + k * 1024); } while (0)
; #define PG8_MMA(ai, bj, At, Bt) do { __builtin_amdgcn_s_setprio(1); _Pragma("unroll") for (int m = 0; m < 4; ++m) _Pragma("unroll") for (int n = 0; n < 2; ++n) _Pragma("unroll") for (int k = 0; k < 2; ++k) \
;         acc[ai][bj][m][n] = __builtin_amdgcn_mfma_f32_16x16x32_bf16(Bt[n][k], At[m][k], acc[ai][bj][m][n], 0, 0, 0); __builtin_amdgcn_s_setprio(0); } while (0)
; #define PG8_WAIT_V(n) asm volatile("s_waitcnt vmcnt(" #n ")" ::: "memory")
; #define PG8_WAIT_L(n) asm volatile("s_waitcnt lgkmcnt(" #n ")" ::: "memory")
; #define PG8_BAR __builtin_amdgcn_s_barrier()
; #define PG8_SCHED __builtin_amdgcn_sched_barrier(0)
;     ...
;             PG8_LDA(At, 0, 1); PG8_STAGE(PG8_SB(0, 0), b2, voffB); PG8_STAGE(PG8_SB(0, 1), b2 + hstepB, voffB); PG8_STAGE(PG8_SA(0, 0), a2, voffA);
;             PG8_WAIT_V(8); PG8_WAIT_L(0); PG8_BAR; PG8_MMA(1, 0, At, B0); PG8_MMA(1, 1, At, B1); PG8_BAR; PG8_SCHED;
;             PG8_LDB(B0, 1, 0); PG8_LDB(B1, 1, 1); PG8_SCHED; PG8_LDA(At, 1, 0); PG8_STAGE(PG8_SA(0, 1), a2 + hstepA, voffA);
;             PG8_WAIT_V(8); PG8_WAIT_L(0); PG8_BAR; PG8_MMA(0, 0, At, B0); PG8_MMA(0, 1, At, B1); PG8_BAR; PG8_SCHED;
	s_setprio 0
	s_mov_b32 m0, s48
	v_lshl_add_u64 v[246:247], s[24:25], 0, v[132:133]
	s_add_u32 s26, s24, 0x10000
	ds_read_b128 v[88:91], v143 offset:16384
	ds_read_b128 v[92:95], v143 offset:17408
	ds_read_b128 v[178:181], v143 offset:18432
	ds_read_b128 v[182:185], v143 offset:19456
	ds_read_b128 v[186:189], v143 offset:20480
	ds_read_b128 v[190:193], v143 offset:21504
	ds_read_b128 v[194:197], v143 offset:22528
	ds_read_b128 v[198:201], v143 offset:23552
	global_load_lds_dwordx4 v[246:247], off
	v_lshl_add_u64 v[248:249], s[24:25], 0, v[128:129]
	s_mov_b32 m0, s50
	s_addc_u32 s27, s25, 0
	global_load_lds_dwordx4 v[248:249], off
	s_mov_b32 m0, s51
	s_nop 0
	global_load_lds_dwordx4 v132, s[26:27]
	s_mov_b32 m0, s52
	s_nop 0
	global_load_lds_dwordx4 v128, s[26:27]
	s_mov_b32 m0, s23
	s_nop 0
	global_load_lds_dwordx4 v134, s[28:29]
	v_lshl_add_u64 v[202:203], s[28:29], 0, v[130:131]
	s_mov_b32 m0, s37
	s_nop 0
	global_load_lds_dwordx4 v[202:203], off
	s_waitcnt vmcnt(8)
	s_waitcnt lgkmcnt(0)
	s_barrier
	s_setprio 1
	v_mfma_f32_16x16x32_bf16 v[0:3], v[104:107], v[194:197], v[0:3]
	v_mfma_f32_16x16x32_bf16 v[0:3], v[108:111], v[198:201], v[0:3]
	v_mfma_f32_16x16x32_bf16 v[4:7], v[116:119], v[198:201], v[4:7]
	v_mfma_f32_16x16x32_bf16 v[4:7], v[112:115], v[194:197], v[4:7]
	v_mfma_f32_16x16x32_bf16 v[150:153], v[112:115], v[88:91], v[150:153]
	v_mfma_f32_16x16x32_bf16 v[150:153], v[116:119], v[92:95], v[150:153]
	v_mfma_f32_16x16x32_bf16 v[146:149], v[108:111], v[92:95], v[146:149]
	v_mfma_f32_16x16x32_bf16 v[146:149], v[104:107], v[88:91], v[146:149]
	v_mfma_f32_16x16x32_bf16 v[154:157], v[104:107], v[178:181], v[154:157]
	v_mfma_f32_16x16x32_bf16 v[154:157], v[108:111], v[182:185], v[154:157]
	v_mfma_f32_16x16x32_bf16 v[158:161], v[116:119], v[182:185], v[158:161]
	v_mfma_f32_16x16x32_bf16 v[158:161], v[112:115], v[178:181], v[158:161]
	v_mfma_f32_16x16x32_bf16 v[166:169], v[112:115], v[186:189], v[166:169]
	v_mfma_f32_16x16x32_bf16 v[166:169], v[116:119], v[190:193], v[166:169]
	v_mfma_f32_16x16x32_bf16 v[162:165], v[108:111], v[190:193], v[162:165]
	v_mfma_f32_16x16x32_bf16 v[162:165], v[104:107], v[186:189], v[162:165]
	v_mfma_f32_16x16x32_bf16 v[8:11], v[120:123], v[88:91], v[8:11]
	v_mfma_f32_16x16x32_bf16 v[202:205], v[124:127], v[92:95], v[8:11]
	v_mfma_f32_16x16x32_bf16 v[8:11], v[170:173], v[88:91], v[12:15]
	v_mfma_f32_16x16x32_bf16 v[206:209], v[174:177], v[92:95], v[8:11]
	v_mfma_f32_16x16x32_bf16 v[8:11], v[120:123], v[178:181], v[24:27]
	v_mfma_f32_16x16x32_bf16 v[218:221], v[124:127], v[182:185], v[8:11]
	v_mfma_f32_16x16x32_bf16 v[8:11], v[170:173], v[178:181], v[28:31]
	v_mfma_f32_16x16x32_bf16 v[178:181], v[174:177], v[182:185], v[8:11]
	v_mfma_f32_16x16x32_bf16 v[8:11], v[120:123], v[186:189], v[60:63]
	v_mfma_f32_16x16x32_bf16 v[182:185], v[124:127], v[190:193], v[8:11]
	v_mfma_f32_16x16x32_bf16 v[8:11], v[170:173], v[186:189], v[100:103]
	v_mfma_f32_16x16x32_bf16 v[186:189], v[174:177], v[190:193], v[8:11]
	v_mfma_f32_16x16x32_bf16 v[8:11], v[120:123], v[194:197], v[16:19]
	v_mfma_f32_16x16x32_bf16 v[190:193], v[124:127], v[198:201], v[8:11]
	v_mfma_f32_16x16x32_bf16 v[8:11], v[170:173], v[194:197], v[20:23]
	v_mfma_f32_16x16x32_bf16 v[170:173], v[174:177], v[198:201], v[8:11]
	s_barrier
	s_setprio 0
	s_nop 4
	ds_read_b128 v[8:11], v144
	ds_read_b128 v[12:15], v144 offset:1024
	ds_read_b128 v[16:19], v144 offset:2048
	ds_read_b128 v[20:23], v144 offset:3072
	ds_read_b128 v[174:177], v145
	ds_read_b128 v[194:197], v145 offset:1024
	ds_read_b128 v[198:201], v145 offset:2048
	ds_read_b128 v[222:225], v145 offset:3072
	s_add_u32 s26, s28, 0x4000
	s_addc_u32 s27, s29, 0
	s_mov_b32 m0, s39
	ds_read_b128 v[24:27], v143 offset:32768
	ds_read_b128 v[28:31], v143 offset:33792
	ds_read_b128 v[60:63], v143 offset:34816
	ds_read_b128 v[226:229], v143 offset:35840
	ds_read_b128 v[230:233], v143 offset:36864
	ds_read_b128 v[234:237], v143 offset:37888
	ds_read_b128 v[238:241], v143 offset:38912
	ds_read_b128 v[242:245], v143 offset:39936
	global_load_lds_dwordx4 v134, s[26:27]
	v_lshl_add_u64 v[88:89], s[26:27], 0, v[130:131]
	s_mov_b32 m0, s40
	s_nop 0
	global_load_lds_dwordx4 v[88:89], off
	s_waitcnt vmcnt(8)
	s_waitcnt lgkmcnt(0)
	s_barrier
; __device__ __forceinline__ int lane_id_opaque() { int l; asm volatile("v_mbcnt_lo_u32_b32 %0, -1, 0\n\tv_mbcnt_hi_u32_b32 %0, -1, %0" : "=v"(l)); return l; }
; #define PG8_STAGE(bufoff, gbase, voff) do { _Pragma("unroll") for (int _i = 0; _i < 2; ++_i) \
;         __builtin_amdgcn_global_load_lds((const unsigned*)((const char*)(gbase) + (voff)[_i]), (PG8_LAS unsigned*)(lds + (bufoff) + ldsw + _i * 8192), 16, 0, 0); } while (0)
; #define PG8_LDA(dst, b, h) do { _Pragma("unroll") for (int m = 0; m < 4; ++m) _Pragma("unroll") for (int k = 0; k < 2; ++k) dst[m][k] = *(const PG8_LAS bf16x8*)(lds + PG8_SA(b, h) + aoff + m * 2048 + k * 1024); } while (0)
; #define PG8_MMA(ai, bj, At, Bt) do { __builtin_amdgcn_s_setprio(1); _Pragma("unroll") for (int m = 0; m < 4; ++m) _Pragma("unroll") for (int n = 0; n < 2; ++n) _Pragma("unroll") for (int k = 0; k < 2; ++k) \
;         acc[ai][bj][m][n] = __builtin_amdgcn_mfma_f32_16x16x32_bf16(Bt[n][k], At[m][k], acc[ai][bj][m][n], 0, 0, 0); __builtin_amdgcn_s_setprio(0); } while (0)
; #define PG8_WAIT_V(n) asm volatile("s_waitcnt vmcnt(" #n ")" ::: "memory")
; #define PG8_WAIT_L(n) asm volatile("s_waitcnt lgkmcnt(" #n ")" ::: "memory")
; #define PG8_BAR __builtin_amdgcn_s_barrier()
; #define PG8_SCHED __builtin_amdgcn_sched_barrier(0)
;     ...
;             PG8_WAIT_V(8); PG8_WAIT_L(0); PG8_BAR; PG8_MMA(0, 0, At, B0); PG8_MMA(0, 1, At, B1); PG8_BAR; PG8_SCHED;
;             PG8_LDA(At, 1, 1); PG8_STAGE(PG8_SB(1, 0), b3, voffB); PG8_STAGE(PG8_SB(1, 1), b3 + hstepB, voffB); PG8_STAGE(PG8_SA(1, 0), a3, voffA);
;             PG8_WAIT_V(8); PG8_WAIT_L(0); PG8_BAR; PG8_MMA(1, 0, At, B0); PG8_MMA(1, 1, At, B1); PG8_BAR; PG8_SCHED;
;     ...
;         if constexpr (ALIGN_EPI) { if (wr == 0) PG8_BAR; }
;         { const int l2 = lane_id_opaque(); E(acc, cur, ui, wr, wc, l2 & 15, l2 >> 4); }
;         S.done(cur);
;         if (!has_next) break;
	s_setprio 1
	v_mfma_f32_16x16x32_bf16 v[64:67], v[8:11], v[24:27], v[64:67]
	v_mfma_f32_16x16x32_bf16 v[124:127], v[12:15], v[28:31], v[64:67]
	v_mfma_f32_16x16x32_bf16 v[64:67], v[16:19], v[24:27], v[68:71]
	v_mfma_f32_16x16x32_bf16 v[120:123], v[20:23], v[28:31], v[64:67]
	v_mfma_f32_16x16x32_bf16 v[64:67], v[8:11], v[60:63], v[72:75]
	v_mfma_f32_16x16x32_bf16 v[108:111], v[12:15], v[226:229], v[64:67]
	v_mfma_f32_16x16x32_bf16 v[64:67], v[16:19], v[60:63], v[76:79]
	v_mfma_f32_16x16x32_bf16 v[104:107], v[20:23], v[226:229], v[64:67]
	v_mfma_f32_16x16x32_bf16 v[64:67], v[8:11], v[230:233], v[80:83]
	v_mfma_f32_16x16x32_bf16 v[92:95], v[12:15], v[234:237], v[64:67]
	v_mfma_f32_16x16x32_bf16 v[64:67], v[16:19], v[230:233], v[84:87]
	v_mfma_f32_16x16x32_bf16 v[88:91], v[20:23], v[234:237], v[64:67]
	v_mfma_f32_16x16x32_bf16 v[64:67], v[8:11], v[238:241], v[210:213]
	v_mfma_f32_16x16x32_bf16 v[76:79], v[12:15], v[242:245], v[64:67]
	v_mfma_f32_16x16x32_bf16 v[64:67], v[16:19], v[238:241], v[214:217]
	v_mfma_f32_16x16x32_bf16 v[72:75], v[20:23], v[242:245], v[64:67]
	v_mfma_f32_16x16x32_bf16 v[64:67], v[174:177], v[24:27], v[96:99]
	v_mfma_f32_16x16x32_bf16 v[24:27], v[198:201], v[24:27], v[32:35]
	v_mfma_f32_16x16x32_bf16 v[112:115], v[222:225], v[28:31], v[24:27]
	v_mfma_f32_16x16x32_bf16 v[24:27], v[174:177], v[60:63], v[36:39]
	v_mfma_f32_16x16x32_bf16 v[100:103], v[194:197], v[226:229], v[24:27]
	v_mfma_f32_16x16x32_bf16 v[24:27], v[198:201], v[60:63], v[40:43]
	v_mfma_f32_16x16x32_bf16 v[96:99], v[222:225], v[226:229], v[24:27]
	v_mfma_f32_16x16x32_bf16 v[24:27], v[174:177], v[230:233], v[44:47]
	v_mfma_f32_16x16x32_bf16 v[84:87], v[194:197], v[234:237], v[24:27]
	v_mfma_f32_16x16x32_bf16 v[24:27], v[198:201], v[230:233], v[48:51]
	v_mfma_f32_16x16x32_bf16 v[80:83], v[222:225], v[234:237], v[24:27]
	v_mfma_f32_16x16x32_bf16 v[24:27], v[174:177], v[238:241], v[52:55]
	v_mfma_f32_16x16x32_bf16 v[60:63], v[194:197], v[242:245], v[24:27]
	v_mfma_f32_16x16x32_bf16 v[24:27], v[198:201], v[238:241], v[56:59]
	v_mfma_f32_16x16x32_bf16 v[116:119], v[194:197], v[28:31], v[64:67]
	v_mfma_f32_16x16x32_bf16 v[56:59], v[222:225], v[242:245], v[24:27]
	s_barrier
	s_setprio 0
	s_mov_b32 m0, s53
	s_nop 2
	v_lshl_add_u64 v[24:25], v[246:247], 0, s[12:13]
	s_add_u32 s24, s24, 0x10080
	ds_read_b128 v[32:35], v143 offset:49152
	ds_read_b128 v[36:39], v143 offset:50176
	ds_read_b128 v[210:213], v143 offset:51200
	ds_read_b128 v[214:217], v143 offset:52224
	ds_read_b128 v[226:229], v143 offset:53248
	ds_read_b128 v[230:233], v143 offset:54272
	ds_read_b128 v[234:237], v143 offset:55296
	ds_read_b128 v[238:241], v143 offset:56320
	global_load_lds_dwordx4 v[24:25], off
	v_lshl_add_u64 v[24:25], v[248:249], 0, s[12:13]
	s_mov_b32 m0, s54
	s_addc_u32 s25, s25, 0
	global_load_lds_dwordx4 v[24:25], off
	s_mov_b32 m0, s55
	s_nop 0
	global_load_lds_dwordx4 v132, s[24:25]
	s_mov_b32 m0, s56
	s_nop 0
	global_load_lds_dwordx4 v128, s[24:25]
	s_mov_b32 m0, s42
	s_nop 0
	global_load_lds_dwordx4 v134, s[30:31]
	v_lshl_add_u64 v[24:25], s[30:31], 0, v[130:131]
	s_mov_b32 m0, s43
	s_nop 0
	global_load_lds_dwordx4 v[24:25], off
	s_waitcnt vmcnt(8)
	s_waitcnt lgkmcnt(0)
	s_barrier
	s_setprio 1
	v_mfma_f32_16x16x32_bf16 v[24:27], v[8:11], v[32:35], v[146:149]
	v_mfma_f32_16x16x32_bf16 v[68:71], v[12:15], v[36:39], v[24:27]
	v_mfma_f32_16x16x32_bf16 v[24:27], v[16:19], v[32:35], v[150:153]
	v_mfma_f32_16x16x32_bf16 v[64:67], v[20:23], v[36:39], v[24:27]
	v_mfma_f32_16x16x32_bf16 v[24:27], v[8:11], v[210:213], v[154:157]
	v_mfma_f32_16x16x32_bf16 v[44:47], v[12:15], v[214:217], v[24:27]
	v_mfma_f32_16x16x32_bf16 v[24:27], v[16:19], v[210:213], v[158:161]
	v_mfma_f32_16x16x32_bf16 v[40:43], v[20:23], v[214:217], v[24:27]
	v_mfma_f32_16x16x32_bf16 v[24:27], v[8:11], v[226:229], v[162:165]
	v_mfma_f32_16x16x32_bf16 v[28:31], v[12:15], v[230:233], v[24:27]
	v_mfma_f32_16x16x32_bf16 v[0:3], v[8:11], v[234:237], v[0:3]
	v_mfma_f32_16x16x32_bf16 v[12:15], v[12:15], v[238:241], v[0:3]
	v_mfma_f32_16x16x32_bf16 v[24:27], v[16:19], v[226:229], v[166:169]
	v_mfma_f32_16x16x32_bf16 v[24:27], v[20:23], v[230:233], v[24:27]
	v_mfma_f32_16x16x32_bf16 v[0:3], v[16:19], v[234:237], v[4:7]
	v_mfma_f32_16x16x32_bf16 v[8:11], v[20:23], v[238:241], v[0:3]
	v_mfma_f32_16x16x32_bf16 v[0:3], v[174:177], v[32:35], v[202:205]
	v_mfma_f32_16x16x32_bf16 v[52:55], v[194:197], v[36:39], v[0:3]
	v_mfma_f32_16x16x32_bf16 v[0:3], v[198:201], v[32:35], v[206:209]
	v_mfma_f32_16x16x32_bf16 v[48:51], v[222:225], v[36:39], v[0:3]
	v_mfma_f32_16x16x32_bf16 v[0:3], v[174:177], v[210:213], v[218:221]
	v_mfma_f32_16x16x32_bf16 v[36:39], v[194:197], v[214:217], v[0:3]
	v_mfma_f32_16x16x32_bf16 v[0:3], v[198:201], v[210:213], v[178:181]
	v_mfma_f32_16x16x32_bf16 v[32:35], v[222:225], v[214:217], v[0:3]
	v_mfma_f32_16x16x32_bf16 v[0:3], v[174:177], v[226:229], v[182:185]
	v_mfma_f32_16x16x32_bf16 v[20:23], v[194:197], v[230:233], v[0:3]
	v_mfma_f32_16x16x32_bf16 v[0:3], v[198:201], v[226:229], v[186:189]
	v_mfma_f32_16x16x32_bf16 v[16:19], v[222:225], v[230:233], v[0:3]
	v_mfma_f32_16x16x32_bf16 v[0:3], v[174:177], v[234:237], v[190:193]
	v_mfma_f32_16x16x32_bf16 v[4:7], v[194:197], v[238:241], v[0:3]
	v_mfma_f32_16x16x32_bf16 v[0:3], v[198:201], v[234:237], v[170:173]
	v_mfma_f32_16x16x32_bf16 v[0:3], v[222:225], v[238:241], v[0:3]
	s_barrier
	s_setprio 0
	s_and_b64 vcc, exec, s[0:1]
	s_cbranch_vccnz .LBB0_99
	s_barrier

; #define PG8_STAGE(bufoff, gbase, voff) do { _Pragma("unroll") for (int _i = 0; _i < 2; ++_i) \
;         __builtin_amdgcn_global_load_lds((const unsigned*)((const char*)(gbase) + (voff)[_i]), (PG8_LAS unsigned*)(lds + (bufoff) + ldsw + _i * 8192), 16, 0, 0); } while (0)
; #define PG8_LDA(dst, b, h) do { _Pragma("unroll") for (int m = 0; m < 4; ++m) _Pragma("unroll") for (int k = 0; k < 2; ++k) dst[m][k] = *(const PG8_LAS bf16x8*)(lds + PG8_SA(b, h) + aoff + m * 2048 + k * 1024); } while (0)
; #define PG8_LDB(dst, b, h) do { _Pragma("unroll") for (int n = 0; n < 2; ++n) _Pragma("unroll") for (int k = 0; k < 2; ++k) dst[n][k] = *(const PG8_LAS bf16x8*)(lds + PG8_SB(b, h) + boff + n * 2048 + k * 1024); } while (0)
; #define PG8_MMA(ai, bj, At, Bt) do { __builtin_amdgcn_s_setprio(1); _Pragma("unroll") for (int m = 0; m < 4; ++m) _Pragma("unroll") for (int n = 0; n < 2; ++n) _Pragma("unroll") for (int k = 0; k < 2; ++k) \
;         acc[ai][bj][m][n] = __builtin_amdgcn_mfma_f32_16x16x32_bf16(Bt[n][k], At[m][k], acc[ai][bj][m][n], 0, 0, 0); __builtin_amdgcn_s_setprio(0); } while (0)
; #define PG8_WAIT_V(n) asm volatile("s_waitcnt vmcnt(" #n ")" ::: "memory")
; #define PG8_WAIT_L(n) asm volatile("s_waitcnt lgkmcnt(" #n ")" ::: "memory")
; #define PG8_BAR __builtin_amdgcn_s_barrier()
; #define PG8_SCHED __builtin_amdgcn_sched_barrier(0)
;     ...
;             PG8_LDB(B0, 0, 0); PG8_LDB(B1, 0, 1); PG8_SCHED; PG8_LDA(At, 0, 0); PG8_STAGE(PG8_SA(1, 1), a1 + hstepA, voffA);
;             PG8_WAIT_V(8); PG8_WAIT_L(0); PG8_BAR; PG8_MMA(0, 0, At, B0); PG8_MMA(0, 1, At, B1); PG8_BAR; PG8_SCHED;
;             PG8_LDA(At, 0, 1); PG8_STAGE(PG8_SB(0, 0), b2, voffB); PG8_STAGE(PG8_SB(0, 1), b2 + hstepB, voffB); PG8_STAGE(PG8_SA(0, 0), a2, voffA);
;             PG8_WAIT_V(8); PG8_WAIT_L(0); PG8_BAR; PG8_MMA(1, 0, At, B0); PG8_MMA(1, 1, At, B1); PG8_BAR; PG8_SCHED;
.Lin_nostg:
	s_add_u32 s65, s6, 0x4000
	s_addc_u32 s66, s7, 0
	s_cmp_eq_u32 vcc_lo, 28
	s_cselect_b32 s90, s54, s65
	s_cselect_b32 s91, s29, s66
	s_cselect_b32 s88, s55, s56
	s_cselect_b32 s89, s31, s57
	s_add_u32 s86, s90, 0x8000
	s_addc_u32 s87, s91, 0
	s_add_i32 s65, 0, 0x10000
	s_add_i32 s66, 0, 0x14000
	v_add_u32_e32 v22, s65, v182
	v_add_u32_e32 v54, s66, v182
	ds_read_b128 v[10:13], v22
	ds_read_b128 v[14:17], v22 offset:1024
	ds_read_b128 v[18:21], v22 offset:2048
	ds_read_b128 v[22:25], v22 offset:3072
	ds_read_b128 v[26:29], v54
	ds_read_b128 v[38:41], v54 offset:1024
	ds_read_b128 v[50:53], v54 offset:2048
	ds_read_b128 v[54:57], v54 offset:3072
	s_add_i32 m0, s51, 0xc000
	ds_read_b128 v[172:175], v183
	ds_read_b128 v[176:179], v183 offset:1024
	ds_read_b128 v[184:187], v183 offset:2048
	ds_read_b128 v[188:191], v183 offset:3072
	ds_read_b128 v[192:195], v183 offset:4096
	ds_read_b128 v[196:199], v183 offset:5120
	ds_read_b128 v[200:203], v183 offset:6144
	ds_read_b128 v[204:207], v183 offset:7168
	global_load_lds_dwordx4 v168, s[6:7]
	s_add_i32 m0, s51, 0xe000
	s_nop 0
	global_load_lds_dwordx4 v170, s[6:7]
	s_waitcnt vmcnt(8)
	s_waitcnt lgkmcnt(0)
	s_barrier
	s_setprio 1
	v_mfma_f32_16x16x32_bf16 v[158:161], v[10:13], v[172:175], 0
	v_mfma_f32_16x16x32_bf16 v[158:161], v[14:17], v[176:179], v[158:161]
	v_mfma_f32_16x16x32_bf16 v[154:157], v[22:25], v[176:179], 0
	v_mfma_f32_16x16x32_bf16 v[154:157], v[18:21], v[172:175], v[154:157]
	v_mfma_f32_16x16x32_bf16 v[138:141], v[18:21], v[184:187], 0
	v_mfma_f32_16x16x32_bf16 v[138:141], v[22:25], v[188:191], v[138:141]
	v_mfma_f32_16x16x32_bf16 v[142:145], v[14:17], v[188:191], 0
	v_mfma_f32_16x16x32_bf16 v[142:145], v[10:13], v[184:187], v[142:145]
	v_mfma_f32_16x16x32_bf16 v[126:129], v[10:13], v[192:195], 0
	v_mfma_f32_16x16x32_bf16 v[126:129], v[14:17], v[196:199], v[126:129]
	v_mfma_f32_16x16x32_bf16 v[122:125], v[22:25], v[196:199], 0
	v_mfma_f32_16x16x32_bf16 v[122:125], v[18:21], v[192:195], v[122:125]
	v_mfma_f32_16x16x32_bf16 v[106:109], v[18:21], v[200:203], 0
	v_mfma_f32_16x16x32_bf16 v[106:109], v[22:25], v[204:207], v[106:109]
	v_mfma_f32_16x16x32_bf16 v[110:113], v[14:17], v[204:207], 0
	v_mfma_f32_16x16x32_bf16 v[110:113], v[10:13], v[200:203], v[110:113]
	v_mfma_f32_16x16x32_bf16 v[150:153], v[26:29], v[172:175], 0
	v_mfma_f32_16x16x32_bf16 v[150:153], v[38:41], v[176:179], v[150:153]
	v_mfma_f32_16x16x32_bf16 v[146:149], v[54:57], v[176:179], 0
	v_mfma_f32_16x16x32_bf16 v[146:149], v[50:53], v[172:175], v[146:149]
	v_mfma_f32_16x16x32_bf16 v[130:133], v[50:53], v[184:187], 0
	v_mfma_f32_16x16x32_bf16 v[130:133], v[54:57], v[188:191], v[130:133]
	v_mfma_f32_16x16x32_bf16 v[134:137], v[38:41], v[188:191], 0
	v_mfma_f32_16x16x32_bf16 v[134:137], v[26:29], v[184:187], v[134:137]
	v_mfma_f32_16x16x32_bf16 v[118:121], v[26:29], v[192:195], 0
	v_mfma_f32_16x16x32_bf16 v[118:121], v[38:41], v[196:199], v[118:121]
	v_mfma_f32_16x16x32_bf16 v[114:117], v[54:57], v[196:199], 0
	v_mfma_f32_16x16x32_bf16 v[114:117], v[50:53], v[192:195], v[114:117]
	v_mfma_f32_16x16x32_bf16 v[98:101], v[50:53], v[200:203], 0
	v_mfma_f32_16x16x32_bf16 v[98:101], v[54:57], v[204:207], v[98:101]
	v_mfma_f32_16x16x32_bf16 v[102:105], v[38:41], v[204:207], 0
	v_mfma_f32_16x16x32_bf16 v[102:105], v[26:29], v[200:203], v[102:105]
	s_barrier
	s_setprio 0
	s_add_i32 s65, s65, s2
	s_mov_b32 m0, s65
	ds_read_b128 v[172:175], v183 offset:16384
	ds_read_b128 v[176:179], v183 offset:17408
	ds_read_b128 v[184:187], v183 offset:18432
	ds_read_b128 v[188:191], v183 offset:19456
	ds_read_b128 v[192:195], v183 offset:20480
	ds_read_b128 v[196:199], v183 offset:21504
	ds_read_b128 v[200:203], v183 offset:22528
	ds_read_b128 v[204:207], v183 offset:23552
	global_load_lds_dwordx4 v0, s[88:89]
	s_add_i32 m0, s65, 0x2000
	s_add_u32 s96, s88, 0x4000
	s_addc_u32 s97, s89, 0
	s_add_i32 s65, s66, s2
	global_load_lds_dwordx4 v162, s[88:89]
	s_mov_b32 m0, s65
	s_nop 0
	global_load_lds_dwordx4 v0, s[96:97]
	s_add_i32 m0, s65, 0x2000
	s_nop 0
	global_load_lds_dwordx4 v162, s[96:97]
	s_mov_b32 m0, s51
	s_nop 0
	global_load_lds_dwordx4 v166, s[90:91]
	s_mov_b32 m0, s92
	s_nop 0
	global_load_lds_dwordx4 v164, s[90:91]
	s_waitcnt vmcnt(8)
	s_waitcnt lgkmcnt(0)
	s_barrier
	s_setprio 1
	v_mfma_f32_16x16x32_bf16 v[94:97], v[10:13], v[172:175], 0
	v_mfma_f32_16x16x32_bf16 v[94:97], v[14:17], v[176:179], v[94:97]
	v_mfma_f32_16x16x32_bf16 v[90:93], v[18:21], v[172:175], 0
	v_mfma_f32_16x16x32_bf16 v[90:93], v[22:25], v[176:179], v[90:93]
	v_mfma_f32_16x16x32_bf16 v[78:81], v[10:13], v[184:187], 0
	v_mfma_f32_16x16x32_bf16 v[78:81], v[14:17], v[188:191], v[78:81]
	v_mfma_f32_16x16x32_bf16 v[74:77], v[18:21], v[184:187], 0
	v_mfma_f32_16x16x32_bf16 v[74:77], v[22:25], v[188:191], v[74:77]
	v_mfma_f32_16x16x32_bf16 v[62:65], v[10:13], v[192:195], 0
	v_mfma_f32_16x16x32_bf16 v[62:65], v[14:17], v[196:199], v[62:65]
	v_mfma_f32_16x16x32_bf16 v[58:61], v[18:21], v[192:195], 0
	v_mfma_f32_16x16x32_bf16 v[58:61], v[22:25], v[196:199], v[58:61]
	v_mfma_f32_16x16x32_bf16 v[10:13], v[10:13], v[200:203], 0
	v_mfma_f32_16x16x32_bf16 v[10:13], v[14:17], v[204:207], v[10:13]
	v_mfma_f32_16x16x32_bf16 v[14:17], v[18:21], v[200:203], 0
	v_mfma_f32_16x16x32_bf16 v[14:17], v[22:25], v[204:207], v[14:17]
	v_mfma_f32_16x16x32_bf16 v[30:33], v[26:29], v[184:187], 0
	v_mfma_f32_16x16x32_bf16 v[70:73], v[38:41], v[188:191], v[30:33]
	v_mfma_f32_16x16x32_bf16 v[30:33], v[50:53], v[184:187], 0
	v_mfma_f32_16x16x32_bf16 v[66:69], v[54:57], v[188:191], v[30:33]
	v_mfma_f32_16x16x32_bf16 v[30:33], v[26:29], v[192:195], 0
	v_mfma_f32_16x16x32_bf16 v[46:49], v[38:41], v[196:199], v[30:33]
	v_mfma_f32_16x16x32_bf16 v[30:33], v[50:53], v[192:195], 0
	v_mfma_f32_16x16x32_bf16 v[42:45], v[54:57], v[196:199], v[30:33]
	v_mfma_f32_16x16x32_bf16 v[6:9], v[26:29], v[200:203], 0
	v_mfma_f32_16x16x32_bf16 v[6:9], v[38:41], v[204:207], v[6:9]
	v_mfma_f32_16x16x32_bf16 v[2:5], v[50:53], v[200:203], 0
	v_mfma_f32_16x16x32_bf16 v[2:5], v[54:57], v[204:207], v[2:5]
	v_mfma_f32_16x16x32_bf16 v[18:21], v[26:29], v[172:175], 0
	v_mfma_f32_16x16x32_bf16 v[18:21], v[38:41], v[176:179], v[18:21]
	v_mfma_f32_16x16x32_bf16 v[22:25], v[50:53], v[172:175], 0
	v_mfma_f32_16x16x32_bf16 v[22:25], v[54:57], v[176:179], v[22:25]
	s_barrier
	s_setprio 0
	s_branch .Lin_mid

; #define PG8_STAGE(bufoff, gbase, voff) do { _Pragma("unroll") for (int _i = 0; _i < 2; ++_i) \
;         __builtin_amdgcn_global_load_lds((const unsigned*)((const char*)(gbase) + (voff)[_i]), (PG8_LAS unsigned*)(lds + (bufoff) + ldsw + _i * 8192), 16, 0, 0); } while (0)
; #define PG8_LDA(dst, b, h) do { _Pragma("unroll") for (int m = 0; m < 4; ++m) _Pragma("unroll") for (int k = 0; k < 2; ++k) dst[m][k] = *(const PG8_LAS bf16x8*)(lds + PG8_SA(b, h) + aoff + m * 2048 + k * 1024); } while (0)
; #define PG8_LDB(dst, b, h) do { _Pragma("unroll") for (int n = 0; n < 2; ++n) _Pragma("unroll") for (int k = 0; k < 2; ++k) dst[n][k] = *(const PG8_LAS bf16x8*)(lds + PG8_SB(b, h) + boff + n * 2048 + k * 1024); } while (0)
; #define PG8_MMA(ai, bj, At, Bt) do { __builtin_amdgcn_s_setprio(1); _Pragma("unroll") for (int m = 0; m < 4; ++m) _Pragma("unroll") for (int n = 0; n < 2; ++n) _Pragma("unroll") for (int k = 0; k < 2; ++k) \
;         acc[ai][bj][m][n] = __builtin_amdgcn_mfma_f32_16x16x32_bf16(Bt[n][k], At[m][k], acc[ai][bj][m][n], 0, 0, 0); __builtin_amdgcn_s_setprio(0); } while (0)
; #define PG8_WAIT_V(n) asm volatile("s_waitcnt vmcnt(" #n ")" ::: "memory")
; #define PG8_WAIT_L(n) asm volatile("s_waitcnt lgkmcnt(" #n ")" ::: "memory")
; #define PG8_BAR __builtin_amdgcn_s_barrier()
; #define PG8_SCHED __builtin_amdgcn_sched_barrier(0)
;     ...
;         for (int t = 0; t < nt; t += 2) {
;             const bool last = (t == nt - 2);
;             const char* a1 = cA + (ptrdiff_t)(t + 1) * kstepA;
;             const char* a2 = last ? nA : cA + (ptrdiff_t)(t + 2) * kstepA; const char* b2 = last ? nB : cB + (ptrdiff_t)(t + 2) * kstep;
;             const char* a3 = a2 + kstepA; const char* b3 = b2 + kstep;
;             if (last && has_next) S.a_ready(nxt);
;             if constexpr (SP2) {
;             PG8_LDB(B0, 0, 0); PG8_LDB(B1, 0, 1); PG8_SCHED; PG8_LDA(At, 0, 0); PG8_STAGE(PG8_SA(1, 1), a1 + hstepA, voffA);
;             PG8_WAIT_V(8); PG8_WAIT_L(0); PG8_BAR; PG8_MMA(0, 0, At, B0); PG8_MMA(0, 1, At, B1); PG8_BAR; PG8_SCHED;
;             PG8_LDA(At, 0, 1); PG8_STAGE(PG8_SB(0, 0), b2, voffB); PG8_STAGE(PG8_SB(0, 1), b2 + hstepB, voffB); PG8_STAGE(PG8_SA(0, 0), a2, voffA);
;             PG8_WAIT_V(8); PG8_WAIT_L(0); PG8_BAR; PG8_MMA(1, 0, At, B0); PG8_MMA(1, 1, At, B1); PG8_BAR; PG8_SCHED;
.LBB0_328:
	s_add_u32 s65, s6, 0x4000
	s_addc_u32 s66, s7, 0
	s_cmp_eq_u32 vcc_lo, 28
	s_cselect_b32 s90, s54, s65
	s_cselect_b32 s91, s29, s66
	s_cselect_b32 s88, s55, s56
	s_cselect_b32 s89, s31, s57
	s_add_u32 s86, s90, 0x8000
	s_addc_u32 s87, s91, 0
	s_add_i32 s65, 0, 0x10000
	s_add_i32 s66, 0, 0x14000
	v_add_u32_e32 v22, s65, v182
	v_add_u32_e32 v54, s66, v182
	ds_read_b128 v[10:13], v22
	ds_read_b128 v[14:17], v22 offset:1024
	ds_read_b128 v[18:21], v22 offset:2048
	ds_read_b128 v[22:25], v22 offset:3072
	ds_read_b128 v[26:29], v54
	ds_read_b128 v[38:41], v54 offset:1024
	ds_read_b128 v[50:53], v54 offset:2048
	ds_read_b128 v[54:57], v54 offset:3072
	s_add_i32 m0, s51, 0xc000
	ds_read_b128 v[172:175], v183
	ds_read_b128 v[176:179], v183 offset:1024
	ds_read_b128 v[184:187], v183 offset:2048
	ds_read_b128 v[188:191], v183 offset:3072
	ds_read_b128 v[192:195], v183 offset:4096
	ds_read_b128 v[196:199], v183 offset:5120
	ds_read_b128 v[200:203], v183 offset:6144
	ds_read_b128 v[204:207], v183 offset:7168
	global_load_lds_dwordx4 v168, s[6:7]
	s_add_i32 m0, s51, 0xe000
	s_nop 0
	global_load_lds_dwordx4 v170, s[6:7]
	s_waitcnt vmcnt(8)
	s_waitcnt lgkmcnt(0)
	s_barrier
	s_setprio 1
	v_mfma_f32_16x16x32_bf16 v[158:161], v[10:13], v[172:175], v[158:161]
	v_mfma_f32_16x16x32_bf16 v[158:161], v[14:17], v[176:179], v[158:161]
	v_mfma_f32_16x16x32_bf16 v[154:157], v[22:25], v[176:179], v[154:157]
	v_mfma_f32_16x16x32_bf16 v[154:157], v[18:21], v[172:175], v[154:157]
	v_mfma_f32_16x16x32_bf16 v[138:141], v[18:21], v[184:187], v[138:141]
	v_mfma_f32_16x16x32_bf16 v[138:141], v[22:25], v[188:191], v[138:141]
	v_mfma_f32_16x16x32_bf16 v[142:145], v[14:17], v[188:191], v[142:145]
	v_mfma_f32_16x16x32_bf16 v[142:145], v[10:13], v[184:187], v[142:145]
	v_mfma_f32_16x16x32_bf16 v[126:129], v[10:13], v[192:195], v[126:129]
	v_mfma_f32_16x16x32_bf16 v[126:129], v[14:17], v[196:199], v[126:129]
	v_mfma_f32_16x16x32_bf16 v[122:125], v[22:25], v[196:199], v[122:125]
	v_mfma_f32_16x16x32_bf16 v[122:125], v[18:21], v[192:195], v[122:125]
	v_mfma_f32_16x16x32_bf16 v[106:109], v[18:21], v[200:203], v[106:109]
	v_mfma_f32_16x16x32_bf16 v[106:109], v[22:25], v[204:207], v[106:109]
	v_mfma_f32_16x16x32_bf16 v[110:113], v[14:17], v[204:207], v[110:113]
	v_mfma_f32_16x16x32_bf16 v[110:113], v[10:13], v[200:203], v[110:113]
	v_mfma_f32_16x16x32_bf16 v[150:153], v[26:29], v[172:175], v[150:153]
	v_mfma_f32_16x16x32_bf16 v[150:153], v[38:41], v[176:179], v[150:153]
	v_mfma_f32_16x16x32_bf16 v[146:149], v[54:57], v[176:179], v[146:149]
	v_mfma_f32_16x16x32_bf16 v[146:149], v[50:53], v[172:175], v[146:149]
	v_mfma_f32_16x16x32_bf16 v[130:133], v[50:53], v[184:187], v[130:133]
	v_mfma_f32_16x16x32_bf16 v[130:133], v[54:57], v[188:191], v[130:133]
	v_mfma_f32_16x16x32_bf16 v[134:137], v[38:41], v[188:191], v[134:137]
	v_mfma_f32_16x16x32_bf16 v[134:137], v[26:29], v[184:187], v[134:137]
	v_mfma_f32_16x16x32_bf16 v[118:121], v[26:29], v[192:195], v[118:121]
	v_mfma_f32_16x16x32_bf16 v[118:121], v[38:41], v[196:199], v[118:121]
	v_mfma_f32_16x16x32_bf16 v[114:117], v[54:57], v[196:199], v[114:117]
	v_mfma_f32_16x16x32_bf16 v[114:117], v[50:53], v[192:195], v[114:117]
	v_mfma_f32_16x16x32_bf16 v[98:101], v[50:53], v[200:203], v[98:101]
	v_mfma_f32_16x16x32_bf16 v[98:101], v[54:57], v[204:207], v[98:101]
	v_mfma_f32_16x16x32_bf16 v[102:105], v[38:41], v[204:207], v[102:105]
	v_mfma_f32_16x16x32_bf16 v[102:105], v[26:29], v[200:203], v[102:105]
	s_barrier
	s_setprio 0
	s_add_i32 s65, s65, s2
	s_mov_b32 m0, s65
	ds_read_b128 v[172:175], v183 offset:16384
	ds_read_b128 v[176:179], v183 offset:17408
	ds_read_b128 v[184:187], v183 offset:18432
	ds_read_b128 v[188:191], v183 offset:19456
	ds_read_b128 v[192:195], v183 offset:20480
	ds_read_b128 v[196:199], v183 offset:21504
	ds_read_b128 v[200:203], v183 offset:22528
	ds_read_b128 v[204:207], v183 offset:23552
	global_load_lds_dwordx4 v0, s[88:89]
	s_add_i32 m0, s65, 0x2000
	s_add_u32 s96, s88, 0x4000
	s_addc_u32 s97, s89, 0
	s_add_i32 s65, s66, s2
	global_load_lds_dwordx4 v162, s[88:89]
	s_mov_b32 m0, s65
	s_nop 0
	global_load_lds_dwordx4 v0, s[96:97]
	s_add_i32 m0, s65, 0x2000
	s_nop 0
	global_load_lds_dwordx4 v162, s[96:97]
	s_mov_b32 m0, s51
	s_nop 0
	global_load_lds_dwordx4 v166, s[90:91]
	s_mov_b32 m0, s92
	s_nop 0
	global_load_lds_dwordx4 v164, s[90:91]
	s_waitcnt vmcnt(8)
	s_waitcnt lgkmcnt(0)
	s_barrier
	s_setprio 1
	v_mfma_f32_16x16x32_bf16 v[94:97], v[10:13], v[172:175], v[94:97]
	v_mfma_f32_16x16x32_bf16 v[94:97], v[14:17], v[176:179], v[94:97]
	v_mfma_f32_16x16x32_bf16 v[90:93], v[18:21], v[172:175], v[90:93]
	v_mfma_f32_16x16x32_bf16 v[90:93], v[22:25], v[176:179], v[90:93]
	v_mfma_f32_16x16x32_bf16 v[78:81], v[10:13], v[184:187], v[78:81]
	v_mfma_f32_16x16x32_bf16 v[78:81], v[14:17], v[188:191], v[78:81]
	v_mfma_f32_16x16x32_bf16 v[74:77], v[18:21], v[184:187], v[74:77]
	v_mfma_f32_16x16x32_bf16 v[74:77], v[22:25], v[188:191], v[74:77]
	v_mfma_f32_16x16x32_bf16 v[62:65], v[10:13], v[192:195], v[62:65]
	v_mfma_f32_16x16x32_bf16 v[62:65], v[14:17], v[196:199], v[62:65]
	v_mfma_f32_16x16x32_bf16 v[58:61], v[18:21], v[192:195], v[58:61]
	v_mfma_f32_16x16x32_bf16 v[58:61], v[22:25], v[196:199], v[58:61]
	v_mfma_f32_16x16x32_bf16 v[10:13], v[10:13], v[200:203], v[34:37]
	v_mfma_f32_16x16x32_bf16 v[10:13], v[14:17], v[204:207], v[10:13]
	v_mfma_f32_16x16x32_bf16 v[14:17], v[18:21], v[200:203], v[30:33]
	v_mfma_f32_16x16x32_bf16 v[14:17], v[22:25], v[204:207], v[14:17]
	v_mfma_f32_16x16x32_bf16 v[30:33], v[26:29], v[184:187], v[70:73]
	v_mfma_f32_16x16x32_bf16 v[70:73], v[38:41], v[188:191], v[30:33]
	v_mfma_f32_16x16x32_bf16 v[30:33], v[50:53], v[184:187], v[66:69]
	v_mfma_f32_16x16x32_bf16 v[66:69], v[54:57], v[188:191], v[30:33]
	v_mfma_f32_16x16x32_bf16 v[30:33], v[26:29], v[192:195], v[46:49]
	v_mfma_f32_16x16x32_bf16 v[46:49], v[38:41], v[196:199], v[30:33]
	v_mfma_f32_16x16x32_bf16 v[30:33], v[50:53], v[192:195], v[42:45]
	v_mfma_f32_16x16x32_bf16 v[42:45], v[54:57], v[196:199], v[30:33]
	v_mfma_f32_16x16x32_bf16 v[6:9], v[26:29], v[200:203], v[6:9]
	v_mfma_f32_16x16x32_bf16 v[6:9], v[38:41], v[204:207], v[6:9]
	v_mfma_f32_16x16x32_bf16 v[2:5], v[50:53], v[200:203], v[2:5]
	v_mfma_f32_16x16x32_bf16 v[2:5], v[54:57], v[204:207], v[2:5]
	v_mfma_f32_16x16x32_bf16 v[18:21], v[26:29], v[172:175], v[86:89]
	v_mfma_f32_16x16x32_bf16 v[18:21], v[38:41], v[176:179], v[18:21]
	v_mfma_f32_16x16x32_bf16 v[22:25], v[50:53], v[172:175], v[82:85]
	v_mfma_f32_16x16x32_bf16 v[22:25], v[54:57], v[176:179], v[22:25]
	s_barrier
	s_setprio 0
; #define PG8_STAGE(bufoff, gbase, voff) do { _Pragma("unroll") for (int _i = 0; _i < 2; ++_i) \
;         __builtin_amdgcn_global_load_lds((const unsigned*)((const char*)(gbase) + (voff)[_i]), (PG8_LAS unsigned*)(lds + (bufoff) + ldsw + _i * 8192), 16, 0, 0); } while (0)
; #define PG8_LDA(dst, b, h) do { _Pragma("unroll") for (int m = 0; m < 4; ++m) _Pragma("unroll") for (int k = 0; k < 2; ++k) dst[m][k] = *(const PG8_LAS bf16x8*)(lds + PG8_SA(b, h) + aoff + m * 2048 + k * 1024); } while (0)
; #define PG8_LDB(dst, b, h) do { _Pragma("unroll") for (int n = 0; n < 2; ++n) _Pragma("unroll") for (int k = 0; k < 2; ++k) dst[n][k] = *(const PG8_LAS bf16x8*)(lds + PG8_SB(b, h) + boff + n * 2048 + k * 1024); } while (0)
; #define PG8_MMA(ai, bj, At, Bt) do { __builtin_amdgcn_s_setprio(1); _Pragma("unroll") for (int m = 0; m < 4; ++m) _Pragma("unroll") for (int n = 0; n < 2; ++n) _Pragma("unroll") for (int k = 0; k < 2; ++k) \
;         acc[ai][bj][m][n] = __builtin_amdgcn_mfma_f32_16x16x32_bf16(Bt[n][k], At[m][k], acc[ai][bj][m][n], 0, 0, 0); __builtin_amdgcn_s_setprio(0); } while (0)
; #define PG8_WAIT_V(n) asm volatile("s_waitcnt vmcnt(" #n ")" ::: "memory")
; #define PG8_WAIT_L(n) asm volatile("s_waitcnt lgkmcnt(" #n ")" ::: "memory")
; #define PG8_BAR __builtin_amdgcn_s_barrier()
; #define PG8_SCHED __builtin_amdgcn_sched_barrier(0)
;     ...
;         for (int t = 0; t < nt; t += 2) {
;     ...
;             PG8_LDB(B0, 1, 0); PG8_LDB(B1, 1, 1); PG8_SCHED; PG8_LDA(At, 1, 0); PG8_STAGE(PG8_SA(0, 1), a2 + hstepA, voffA);
;             PG8_WAIT_V(8); PG8_WAIT_L(0); PG8_BAR; PG8_MMA(0, 0, At, B0); PG8_MMA(0, 1, At, B1); PG8_BAR; PG8_SCHED;
;             PG8_LDA(At, 1, 1); PG8_STAGE(PG8_SB(1, 0), b3, voffB); PG8_STAGE(PG8_SB(1, 1), b3 + hstepB, voffB); PG8_STAGE(PG8_SA(1, 0), a3, voffA);
;             PG8_WAIT_V(8); PG8_WAIT_L(0); PG8_BAR; PG8_MMA(1, 0, At, B0); PG8_MMA(1, 1, At, B1); PG8_BAR; PG8_SCHED;
.Lin_mid:
	s_add_i32 s65, 0, 0x18000
	v_add_u32_e32 v34, s65, v182
	s_add_i32 s66, 0, 0x1c000
	ds_read_b128 v[26:29], v34
	ds_read_b128 v[30:33], v34 offset:1024
	ds_read_b128 v[38:41], v34 offset:2048
	ds_read_b128 v[50:53], v34 offset:3072
	v_add_u32_e32 v34, s66, v182
	ds_read_b128 v[54:57], v34
	ds_read_b128 v[172:175], v34 offset:1024
	ds_read_b128 v[176:179], v34 offset:2048
	ds_read_b128 v[184:187], v34 offset:3072
	s_add_u32 s90, s90, 0x4000
	s_addc_u32 s91, s91, 0
	s_mov_b32 m0, s14
	ds_read_b128 v[34:37], v183 offset:32768
	ds_read_b128 v[82:85], v183 offset:33792
	ds_read_b128 v[86:89], v183 offset:34816
	ds_read_b128 v[188:191], v183 offset:35840
	ds_read_b128 v[192:195], v183 offset:36864
	ds_read_b128 v[196:199], v183 offset:37888
	ds_read_b128 v[200:203], v183 offset:38912
	ds_read_b128 v[204:207], v183 offset:39936
	global_load_lds_dwordx4 v166, s[90:91]
	v_lshl_add_u64 v[208:209], s[90:91], 0, v[164:165]
	s_mov_b32 m0, s15
	s_nop 0
	global_load_lds_dwordx4 v[208:209], off
	s_waitcnt vmcnt(8)
	s_waitcnt lgkmcnt(0)
	s_barrier
	s_setprio 1
	v_mfma_f32_16x16x32_bf16 v[158:161], v[26:29], v[34:37], v[158:161]
	v_mfma_f32_16x16x32_bf16 v[158:161], v[30:33], v[82:85], v[158:161]
	v_mfma_f32_16x16x32_bf16 v[154:157], v[50:53], v[82:85], v[154:157]
	v_mfma_f32_16x16x32_bf16 v[154:157], v[38:41], v[34:37], v[154:157]
	v_mfma_f32_16x16x32_bf16 v[138:141], v[38:41], v[86:89], v[138:141]
	v_mfma_f32_16x16x32_bf16 v[138:141], v[50:53], v[188:191], v[138:141]
	v_mfma_f32_16x16x32_bf16 v[142:145], v[30:33], v[188:191], v[142:145]
	v_mfma_f32_16x16x32_bf16 v[142:145], v[26:29], v[86:89], v[142:145]
	v_mfma_f32_16x16x32_bf16 v[126:129], v[26:29], v[192:195], v[126:129]
	v_mfma_f32_16x16x32_bf16 v[126:129], v[30:33], v[196:199], v[126:129]
	v_mfma_f32_16x16x32_bf16 v[122:125], v[50:53], v[196:199], v[122:125]
	v_mfma_f32_16x16x32_bf16 v[122:125], v[38:41], v[192:195], v[122:125]
	v_mfma_f32_16x16x32_bf16 v[106:109], v[38:41], v[200:203], v[106:109]
	v_mfma_f32_16x16x32_bf16 v[106:109], v[50:53], v[204:207], v[106:109]
	v_mfma_f32_16x16x32_bf16 v[110:113], v[30:33], v[204:207], v[110:113]
	v_mfma_f32_16x16x32_bf16 v[110:113], v[26:29], v[200:203], v[110:113]
	v_mfma_f32_16x16x32_bf16 v[150:153], v[54:57], v[34:37], v[150:153]
	v_mfma_f32_16x16x32_bf16 v[150:153], v[172:175], v[82:85], v[150:153]
	v_mfma_f32_16x16x32_bf16 v[34:37], v[176:179], v[34:37], v[146:149]
	v_mfma_f32_16x16x32_bf16 v[146:149], v[184:187], v[82:85], v[34:37]
	v_mfma_f32_16x16x32_bf16 v[34:37], v[54:57], v[86:89], v[134:137]
	v_mfma_f32_16x16x32_bf16 v[134:137], v[172:175], v[188:191], v[34:37]
	v_mfma_f32_16x16x32_bf16 v[34:37], v[176:179], v[86:89], v[130:133]
	v_mfma_f32_16x16x32_bf16 v[130:133], v[184:187], v[188:191], v[34:37]
	v_mfma_f32_16x16x32_bf16 v[34:37], v[54:57], v[192:195], v[118:121]
	v_mfma_f32_16x16x32_bf16 v[118:121], v[172:175], v[196:199], v[34:37]
	v_mfma_f32_16x16x32_bf16 v[34:37], v[176:179], v[192:195], v[114:117]
	v_mfma_f32_16x16x32_bf16 v[114:117], v[184:187], v[196:199], v[34:37]
	v_mfma_f32_16x16x32_bf16 v[34:37], v[54:57], v[200:203], v[102:105]
	v_mfma_f32_16x16x32_bf16 v[102:105], v[172:175], v[204:207], v[34:37]
	v_mfma_f32_16x16x32_bf16 v[34:37], v[176:179], v[200:203], v[98:101]
	v_mfma_f32_16x16x32_bf16 v[98:101], v[184:187], v[204:207], v[34:37]
	s_barrier
	s_setprio 0
	s_add_u32 s90, s88, 0x8000
	s_addc_u32 s91, s89, 0
	s_add_i32 s65, s65, s2
	s_nop 0
	s_mov_b32 m0, s65
	ds_read_b128 v[82:85], v183 offset:49152
	ds_read_b128 v[188:191], v183 offset:50176
	ds_read_b128 v[192:195], v183 offset:51200
	ds_read_b128 v[196:199], v183 offset:52224
	ds_read_b128 v[200:203], v183 offset:53248
	ds_read_b128 v[204:207], v183 offset:54272
	ds_read_b128 v[208:211], v183 offset:55296
	ds_read_b128 v[216:219], v183 offset:56320
	global_load_lds_dwordx4 v0, s[90:91]
	s_add_i32 m0, s65, 0x2000
	s_add_u32 s88, s88, 0xc000
	s_addc_u32 s89, s89, 0
	s_add_i32 s65, s66, s2
	global_load_lds_dwordx4 v162, s[90:91]
	s_mov_b32 m0, s65
	s_nop 0
	global_load_lds_dwordx4 v0, s[88:89]
	s_add_i32 m0, s65, 0x2000
	s_nop 0
	global_load_lds_dwordx4 v162, s[88:89]
	s_mov_b32 m0, s71
	s_nop 0
	global_load_lds_dwordx4 v166, s[86:87]
	v_lshl_add_u64 v[34:35], s[86:87], 0, v[164:165]
	s_mov_b32 m0, s80
	s_nop 0
	global_load_lds_dwordx4 v[34:35], off
	s_waitcnt vmcnt(8)
	s_waitcnt lgkmcnt(0)
	s_barrier
	s_setprio 1
	v_mfma_f32_16x16x32_bf16 v[34:37], v[26:29], v[82:85], v[94:97]
	v_mfma_f32_16x16x32_bf16 v[94:97], v[30:33], v[188:191], v[34:37]
	v_mfma_f32_16x16x32_bf16 v[34:37], v[38:41], v[82:85], v[90:93]
	v_mfma_f32_16x16x32_bf16 v[90:93], v[50:53], v[188:191], v[34:37]
	v_mfma_f32_16x16x32_bf16 v[34:37], v[26:29], v[192:195], v[78:81]
	v_mfma_f32_16x16x32_bf16 v[78:81], v[30:33], v[196:199], v[34:37]
	v_mfma_f32_16x16x32_bf16 v[34:37], v[38:41], v[192:195], v[74:77]
	v_mfma_f32_16x16x32_bf16 v[74:77], v[50:53], v[196:199], v[34:37]
	v_mfma_f32_16x16x32_bf16 v[34:37], v[26:29], v[200:203], v[62:65]
	v_mfma_f32_16x16x32_bf16 v[62:65], v[30:33], v[204:207], v[34:37]
	v_mfma_f32_16x16x32_bf16 v[34:37], v[38:41], v[200:203], v[58:61]
	v_mfma_f32_16x16x32_bf16 v[58:61], v[50:53], v[204:207], v[34:37]
	v_mfma_f32_16x16x32_bf16 v[10:13], v[26:29], v[208:211], v[10:13]
	v_mfma_f32_16x16x32_bf16 v[34:37], v[30:33], v[216:219], v[10:13]
	v_mfma_f32_16x16x32_bf16 v[10:13], v[38:41], v[208:211], v[14:17]
	v_mfma_f32_16x16x32_bf16 v[30:33], v[50:53], v[216:219], v[10:13]
	v_mfma_f32_16x16x32_bf16 v[10:13], v[54:57], v[82:85], v[18:21]
	v_mfma_f32_16x16x32_bf16 v[86:89], v[172:175], v[188:191], v[10:13]
	v_mfma_f32_16x16x32_bf16 v[10:13], v[176:179], v[82:85], v[22:25]
	v_mfma_f32_16x16x32_bf16 v[82:85], v[184:187], v[188:191], v[10:13]
	v_mfma_f32_16x16x32_bf16 v[10:13], v[54:57], v[192:195], v[70:73]
	v_mfma_f32_16x16x32_bf16 v[70:73], v[172:175], v[196:199], v[10:13]
	v_mfma_f32_16x16x32_bf16 v[10:13], v[176:179], v[192:195], v[66:69]
	v_mfma_f32_16x16x32_bf16 v[66:69], v[184:187], v[196:199], v[10:13]
	v_mfma_f32_16x16x32_bf16 v[10:13], v[54:57], v[200:203], v[46:49]
	v_mfma_f32_16x16x32_bf16 v[46:49], v[172:175], v[204:207], v[10:13]
	v_mfma_f32_16x16x32_bf16 v[10:13], v[176:179], v[200:203], v[42:45]
	v_mfma_f32_16x16x32_bf16 v[42:45], v[184:187], v[204:207], v[10:13]
	v_mfma_f32_16x16x32_bf16 v[6:9], v[54:57], v[208:211], v[6:9]
	v_mfma_f32_16x16x32_bf16 v[6:9], v[172:175], v[216:219], v[6:9]
	v_mfma_f32_16x16x32_bf16 v[2:5], v[176:179], v[208:211], v[2:5]
	v_mfma_f32_16x16x32_bf16 v[2:5], v[184:187], v[216:219], v[2:5]
	s_barrier
	s_setprio 0
	s_add_i32 vcc_lo, vcc_lo, 2
	s_add_u32 s6, s6, 0x10000
	s_addc_u32 s7, s7, 0
	s_add_u32 s56, s56, 0x10000
	s_addc_u32 s57, s57, 0
	s_cmp_gt_u32 vcc_lo, 29
	s_cbranch_scc0 .LBB0_328
	s_and_b64 vcc, exec, s[26:27]
	s_cbranch_vccz .LBB0_331
	s_barrier

; #define PG8_STAGE(bufoff, gbase, voff) do { _Pragma("unroll") for (int _i = 0; _i < 2; ++_i) \
;         __builtin_amdgcn_global_load_lds((const unsigned*)((const char*)(gbase) + (voff)[_i]), (PG8_LAS unsigned*)(lds + (bufoff) + ldsw + _i * 8192), 16, 0, 0); } while (0)
; #define PG8_LDA(dst, b, h) do { _Pragma("unroll") for (int m = 0; m < 4; ++m) _Pragma("unroll") for (int k = 0; k < 2; ++k) dst[m][k] = *(const PG8_LAS bf16x8*)(lds + PG8_SA(b, h) + aoff + m * 2048 + k * 1024); } while (0)
; #define PG8_LDB(dst, b, h) do { _Pragma("unroll") for (int n = 0; n < 2; ++n) _Pragma("unroll") for (int k = 0; k < 2; ++k) dst[n][k] = *(const PG8_LAS bf16x8*)(lds + PG8_SB(b, h) + boff + n * 2048 + k * 1024); } while (0)
; #define PG8_MMA(ai, bj, At, Bt) do { __builtin_amdgcn_s_setprio(1); _Pragma("unroll") for (int m = 0; m < 4; ++m) _Pragma("unroll") for (int n = 0; n < 2; ++n) _Pragma("unroll") for (int k = 0; k < 2; ++k) \
;         acc[ai][bj][m][n] = __builtin_amdgcn_mfma_f32_16x16x32_bf16(Bt[n][k], At[m][k], acc[ai][bj][m][n], 0, 0, 0); __builtin_amdgcn_s_setprio(0); } while (0)
; #define PG8_WAIT_V(n) asm volatile("s_waitcnt vmcnt(" #n ")" ::: "memory")
; #define PG8_WAIT_L(n) asm volatile("s_waitcnt lgkmcnt(" #n ")" ::: "memory")
; #define PG8_BAR __builtin_amdgcn_s_barrier()
; #define PG8_SCHED __builtin_amdgcn_sched_barrier(0)
;     ...
;             PG8_LDB(B0, 0, 0); PG8_LDB(B1, 0, 1); PG8_SCHED; PG8_LDA(At, 0, 0); PG8_STAGE(PG8_SA(1, 1), a1 + hstepA, voffA);
;             PG8_WAIT_V(8); PG8_WAIT_L(0); PG8_BAR; PG8_MMA(0, 0, At, B0); PG8_MMA(0, 1, At, B1); PG8_BAR; PG8_SCHED;
;             PG8_LDA(At, 0, 1); PG8_STAGE(PG8_SB(0, 0), b2, voffB); PG8_STAGE(PG8_SB(0, 1), b2 + hstepB, voffB); PG8_STAGE(PG8_SA(0, 0), a2, voffA);
;             PG8_WAIT_V(8); PG8_WAIT_L(0); PG8_BAR; PG8_MMA(1, 0, At, B0); PG8_MMA(1, 1, At, B1); PG8_BAR; PG8_SCHED;
.Lout_nostg:
	s_add_u32 s36, s34, 0x4000
	s_addc_u32 s37, s35, 0
	s_cmp_eq_u32 s57, 28
	s_cselect_b32 s86, s29, s36
	s_cselect_b32 s87, s23, s37
	s_cselect_b32 s46, s31, s44
	s_cselect_b32 s47, s21, s56
	s_add_u32 s36, s86, 0x8000
	s_addc_u32 s37, s87, 0
	s_add_i32 s65, 0, 0x10000
	v_add_u32_e32 v0, s65, v242
	s_add_i32 s66, 0, 0x14000
	s_waitcnt lgkmcnt(0)
	ds_read_b128 v[130:133], v0
	ds_read_b128 v[134:137], v0 offset:1024
	ds_read_b128 v[138:141], v0 offset:2048
	ds_read_b128 v[142:145], v0 offset:3072
	v_add_u32_e32 v0, s66, v242
	ds_read_b128 v[146:149], v0
	ds_read_b128 v[150:153], v0 offset:1024
	ds_read_b128 v[154:157], v0 offset:2048
	ds_read_b128 v[158:161], v0 offset:3072
	s_add_i32 m0, s51, 0xc000
	ds_read_b128 v[162:165], v243
	ds_read_b128 v[166:169], v243 offset:1024
	ds_read_b128 v[170:173], v243 offset:2048
	ds_read_b128 v[174:177], v243 offset:3072
	ds_read_b128 v[178:181], v243 offset:4096
	ds_read_b128 v[182:185], v243 offset:5120
	ds_read_b128 v[198:201], v243 offset:6144
	ds_read_b128 v[202:205], v243 offset:7168
	global_load_lds_dwordx4 v194, s[34:35]
	s_add_i32 m0, s51, 0xe000
	s_nop 0
	global_load_lds_dwordx4 v196, s[34:35]
	s_waitcnt vmcnt(8)
	s_waitcnt lgkmcnt(0)
	s_barrier
	s_setprio 1
	v_mfma_f32_16x16x32_bf16 v[126:129], v[130:133], v[162:165], 0
	v_mfma_f32_16x16x32_bf16 v[126:129], v[134:137], v[166:169], v[126:129]
	v_mfma_f32_16x16x32_bf16 v[122:125], v[142:145], v[166:169], 0
	v_mfma_f32_16x16x32_bf16 v[122:125], v[138:141], v[162:165], v[122:125]
	v_mfma_f32_16x16x32_bf16 v[106:109], v[138:141], v[170:173], 0
	v_mfma_f32_16x16x32_bf16 v[106:109], v[142:145], v[174:177], v[106:109]
	v_mfma_f32_16x16x32_bf16 v[110:113], v[134:137], v[174:177], 0
	v_mfma_f32_16x16x32_bf16 v[110:113], v[130:133], v[170:173], v[110:113]
	v_mfma_f32_16x16x32_bf16 v[94:97], v[130:133], v[178:181], 0
	v_mfma_f32_16x16x32_bf16 v[94:97], v[134:137], v[182:185], v[94:97]
	v_mfma_f32_16x16x32_bf16 v[90:93], v[142:145], v[182:185], 0
	v_mfma_f32_16x16x32_bf16 v[90:93], v[138:141], v[178:181], v[90:93]
	v_mfma_f32_16x16x32_bf16 v[74:77], v[138:141], v[198:201], 0
	v_mfma_f32_16x16x32_bf16 v[74:77], v[142:145], v[202:205], v[74:77]
	v_mfma_f32_16x16x32_bf16 v[78:81], v[134:137], v[202:205], 0
	v_mfma_f32_16x16x32_bf16 v[78:81], v[130:133], v[198:201], v[78:81]
	v_mfma_f32_16x16x32_bf16 v[118:121], v[146:149], v[162:165], 0
	v_mfma_f32_16x16x32_bf16 v[118:121], v[150:153], v[166:169], v[118:121]
	v_mfma_f32_16x16x32_bf16 v[114:117], v[158:161], v[166:169], 0
	v_mfma_f32_16x16x32_bf16 v[114:117], v[154:157], v[162:165], v[114:117]
	v_mfma_f32_16x16x32_bf16 v[98:101], v[154:157], v[170:173], 0
	v_mfma_f32_16x16x32_bf16 v[98:101], v[158:161], v[174:177], v[98:101]
	v_mfma_f32_16x16x32_bf16 v[102:105], v[150:153], v[174:177], 0
	v_mfma_f32_16x16x32_bf16 v[102:105], v[146:149], v[170:173], v[102:105]
	v_mfma_f32_16x16x32_bf16 v[86:89], v[146:149], v[178:181], 0
	v_mfma_f32_16x16x32_bf16 v[86:89], v[150:153], v[182:185], v[86:89]
	v_mfma_f32_16x16x32_bf16 v[82:85], v[158:161], v[182:185], 0
	v_mfma_f32_16x16x32_bf16 v[82:85], v[154:157], v[178:181], v[82:85]
	v_mfma_f32_16x16x32_bf16 v[66:69], v[154:157], v[198:201], 0
	v_mfma_f32_16x16x32_bf16 v[66:69], v[158:161], v[202:205], v[66:69]
	v_mfma_f32_16x16x32_bf16 v[70:73], v[150:153], v[202:205], 0
	v_mfma_f32_16x16x32_bf16 v[70:73], v[146:149], v[198:201], v[70:73]
	s_barrier
	s_setprio 0
	s_add_i32 s65, s65, s49
	s_mov_b32 m0, s65
	ds_read_b128 v[162:165], v243 offset:16384
	ds_read_b128 v[166:169], v243 offset:17408
	ds_read_b128 v[170:173], v243 offset:18432
	ds_read_b128 v[174:177], v243 offset:19456
	ds_read_b128 v[178:181], v243 offset:20480
	ds_read_b128 v[182:185], v243 offset:21504
	ds_read_b128 v[198:201], v243 offset:22528
	ds_read_b128 v[202:205], v243 offset:23552
	global_load_lds_dwordx4 v188, s[46:47]
	s_add_i32 m0, s65, 0x2000
	s_add_u32 s90, s46, 0x4000
	s_addc_u32 s91, s47, 0
	s_add_i32 s65, s66, s49
	global_load_lds_dwordx4 v192, s[46:47]
	s_mov_b32 m0, s65
	s_nop 0
	global_load_lds_dwordx4 v188, s[90:91]
	s_add_i32 m0, s65, 0x2000
	s_nop 0
	global_load_lds_dwordx4 v192, s[90:91]
	s_mov_b32 m0, s51
	s_nop 0
	global_load_lds_dwordx4 v186, s[86:87]
	s_mov_b32 m0, s54
	s_nop 0
	global_load_lds_dwordx4 v190, s[86:87]
	s_waitcnt vmcnt(8)
	s_waitcnt lgkmcnt(0)
	s_barrier
	s_setprio 1
	v_mfma_f32_16x16x32_bf16 v[62:65], v[130:133], v[162:165], 0
	v_mfma_f32_16x16x32_bf16 v[62:65], v[134:137], v[166:169], v[62:65]
	v_mfma_f32_16x16x32_bf16 v[58:61], v[142:145], v[166:169], 0
	v_mfma_f32_16x16x32_bf16 v[58:61], v[138:141], v[162:165], v[58:61]
	v_mfma_f32_16x16x32_bf16 v[42:45], v[138:141], v[170:173], 0
	v_mfma_f32_16x16x32_bf16 v[42:45], v[142:145], v[174:177], v[42:45]
	v_mfma_f32_16x16x32_bf16 v[46:49], v[134:137], v[174:177], 0
	v_mfma_f32_16x16x32_bf16 v[46:49], v[130:133], v[170:173], v[46:49]
	v_mfma_f32_16x16x32_bf16 v[30:33], v[130:133], v[178:181], 0
	v_mfma_f32_16x16x32_bf16 v[30:33], v[134:137], v[182:185], v[30:33]
	v_mfma_f32_16x16x32_bf16 v[26:29], v[142:145], v[182:185], 0
	v_mfma_f32_16x16x32_bf16 v[26:29], v[138:141], v[178:181], v[26:29]
	v_mfma_f32_16x16x32_bf16 v[10:13], v[138:141], v[198:201], 0
	v_mfma_f32_16x16x32_bf16 v[10:13], v[142:145], v[202:205], v[10:13]
	v_mfma_f32_16x16x32_bf16 v[14:17], v[134:137], v[202:205], 0
	v_mfma_f32_16x16x32_bf16 v[14:17], v[130:133], v[198:201], v[14:17]
	v_mfma_f32_16x16x32_bf16 v[54:57], v[146:149], v[162:165], 0
	v_mfma_f32_16x16x32_bf16 v[54:57], v[150:153], v[166:169], v[54:57]
	v_mfma_f32_16x16x32_bf16 v[50:53], v[158:161], v[166:169], 0
	v_mfma_f32_16x16x32_bf16 v[50:53], v[154:157], v[162:165], v[50:53]
	v_mfma_f32_16x16x32_bf16 v[34:37], v[154:157], v[170:173], 0
	v_mfma_f32_16x16x32_bf16 v[34:37], v[158:161], v[174:177], v[34:37]
	v_mfma_f32_16x16x32_bf16 v[38:41], v[150:153], v[174:177], 0
	v_mfma_f32_16x16x32_bf16 v[38:41], v[146:149], v[170:173], v[38:41]
	v_mfma_f32_16x16x32_bf16 v[22:25], v[146:149], v[178:181], 0
	v_mfma_f32_16x16x32_bf16 v[22:25], v[150:153], v[182:185], v[22:25]
	v_mfma_f32_16x16x32_bf16 v[18:21], v[158:161], v[182:185], 0
	v_mfma_f32_16x16x32_bf16 v[18:21], v[154:157], v[178:181], v[18:21]
	v_mfma_f32_16x16x32_bf16 v[2:5], v[154:157], v[198:201], 0
	v_mfma_f32_16x16x32_bf16 v[2:5], v[158:161], v[202:205], v[2:5]
	v_mfma_f32_16x16x32_bf16 v[6:9], v[150:153], v[202:205], 0
	v_mfma_f32_16x16x32_bf16 v[6:9], v[146:149], v[198:201], v[6:9]
	s_barrier
	s_setprio 0
	s_branch .Lout_mid

; #define PG8_STAGE(bufoff, gbase, voff) do { _Pragma("unroll") for (int _i = 0; _i < 2; ++_i) \
;         __builtin_amdgcn_global_load_lds((const unsigned*)((const char*)(gbase) + (voff)[_i]), (PG8_LAS unsigned*)(lds + (bufoff) + ldsw + _i * 8192), 16, 0, 0); } while (0)
; #define PG8_LDA(dst, b, h) do { _Pragma("unroll") for (int m = 0; m < 4; ++m) _Pragma("unroll") for (int k = 0; k < 2; ++k) dst[m][k] = *(const PG8_LAS bf16x8*)(lds + PG8_SA(b, h) + aoff + m * 2048 + k * 1024); } while (0)
; #define PG8_LDB(dst, b, h) do { _Pragma("unroll") for (int n = 0; n < 2; ++n) _Pragma("unroll") for (int k = 0; k < 2; ++k) dst[n][k] = *(const PG8_LAS bf16x8*)(lds + PG8_SB(b, h) + boff + n * 2048 + k * 1024); } while (0)
; #define PG8_MMA(ai, bj, At, Bt) do { __builtin_amdgcn_s_setprio(1); _Pragma("unroll") for (int m = 0; m < 4; ++m) _Pragma("unroll") for (int n = 0; n < 2; ++n) _Pragma("unroll") for (int k = 0; k < 2; ++k) \
;         acc[ai][bj][m][n] = __builtin_amdgcn_mfma_f32_16x16x32_bf16(Bt[n][k], At[m][k], acc[ai][bj][m][n], 0, 0, 0); __builtin_amdgcn_s_setprio(0); } while (0)
; #define PG8_WAIT_V(n) asm volatile("s_waitcnt vmcnt(" #n ")" ::: "memory")
; #define PG8_WAIT_L(n) asm volatile("s_waitcnt lgkmcnt(" #n ")" ::: "memory")
; #define PG8_BAR __builtin_amdgcn_s_barrier()
; #define PG8_SCHED __builtin_amdgcn_sched_barrier(0)
;     ...
;         for (int t = 0; t < nt; t += 2) {
;             const bool last = (t == nt - 2);
;             const char* a1 = cA + (ptrdiff_t)(t + 1) * kstepA;
;             const char* a2 = last ? nA : cA + (ptrdiff_t)(t + 2) * kstepA; const char* b2 = last ? nB : cB + (ptrdiff_t)(t + 2) * kstep;
;             const char* a3 = a2 + kstepA; const char* b3 = b2 + kstep;
;             if (last && has_next) S.a_ready(nxt);
;             if constexpr (SP2) {
;             PG8_LDB(B0, 0, 0); PG8_LDB(B1, 0, 1); PG8_SCHED; PG8_LDA(At, 0, 0); PG8_STAGE(PG8_SA(1, 1), a1 + hstepA, voffA);
;             PG8_WAIT_V(8); PG8_WAIT_L(0); PG8_BAR; PG8_MMA(0, 0, At, B0); PG8_MMA(0, 1, At, B1); PG8_BAR; PG8_SCHED;
;             PG8_LDA(At, 0, 1); PG8_STAGE(PG8_SB(0, 0), b2, voffB); PG8_STAGE(PG8_SB(0, 1), b2 + hstepB, voffB); PG8_STAGE(PG8_SA(0, 0), a2, voffA);
;             PG8_WAIT_V(8); PG8_WAIT_L(0); PG8_BAR; PG8_MMA(1, 0, At, B0); PG8_MMA(1, 1, At, B1); PG8_BAR; PG8_SCHED;
.LBB0_1128:
	s_add_u32 s36, s34, 0x4000
	s_addc_u32 s37, s35, 0
	s_cmp_eq_u32 s57, 28
	s_cselect_b32 s86, s29, s36
	s_cselect_b32 s87, s23, s37
	s_cselect_b32 s46, s31, s44
	s_cselect_b32 s47, s21, s56
	s_add_u32 s36, s86, 0x8000
	s_addc_u32 s37, s87, 0
	s_add_i32 s65, 0, 0x10000
	v_add_u32_e32 v0, s65, v242
	s_add_i32 s66, 0, 0x14000
	s_waitcnt lgkmcnt(0)
	ds_read_b128 v[130:133], v0
	ds_read_b128 v[134:137], v0 offset:1024
	ds_read_b128 v[138:141], v0 offset:2048
	ds_read_b128 v[142:145], v0 offset:3072
	v_add_u32_e32 v0, s66, v242
	ds_read_b128 v[146:149], v0
	ds_read_b128 v[150:153], v0 offset:1024
	ds_read_b128 v[154:157], v0 offset:2048
	ds_read_b128 v[158:161], v0 offset:3072
	s_add_i32 m0, s51, 0xc000
	ds_read_b128 v[162:165], v243
	ds_read_b128 v[166:169], v243 offset:1024
	ds_read_b128 v[170:173], v243 offset:2048
	ds_read_b128 v[174:177], v243 offset:3072
	ds_read_b128 v[178:181], v243 offset:4096
	ds_read_b128 v[182:185], v243 offset:5120
	ds_read_b128 v[198:201], v243 offset:6144
	ds_read_b128 v[202:205], v243 offset:7168
	global_load_lds_dwordx4 v194, s[34:35]
	s_add_i32 m0, s51, 0xe000
	s_nop 0
	global_load_lds_dwordx4 v196, s[34:35]
	s_waitcnt vmcnt(8)
	s_waitcnt lgkmcnt(0)
	s_barrier
	s_setprio 1
	v_mfma_f32_16x16x32_bf16 v[126:129], v[130:133], v[162:165], v[126:129]
	v_mfma_f32_16x16x32_bf16 v[126:129], v[134:137], v[166:169], v[126:129]
	v_mfma_f32_16x16x32_bf16 v[122:125], v[142:145], v[166:169], v[122:125]
	v_mfma_f32_16x16x32_bf16 v[122:125], v[138:141], v[162:165], v[122:125]
	v_mfma_f32_16x16x32_bf16 v[106:109], v[138:141], v[170:173], v[106:109]
	v_mfma_f32_16x16x32_bf16 v[106:109], v[142:145], v[174:177], v[106:109]
	v_mfma_f32_16x16x32_bf16 v[110:113], v[134:137], v[174:177], v[110:113]
	v_mfma_f32_16x16x32_bf16 v[110:113], v[130:133], v[170:173], v[110:113]
	v_mfma_f32_16x16x32_bf16 v[94:97], v[130:133], v[178:181], v[94:97]
	v_mfma_f32_16x16x32_bf16 v[94:97], v[134:137], v[182:185], v[94:97]
	v_mfma_f32_16x16x32_bf16 v[90:93], v[142:145], v[182:185], v[90:93]
	v_mfma_f32_16x16x32_bf16 v[90:93], v[138:141], v[178:181], v[90:93]
	v_mfma_f32_16x16x32_bf16 v[74:77], v[138:141], v[198:201], v[74:77]
	v_mfma_f32_16x16x32_bf16 v[74:77], v[142:145], v[202:205], v[74:77]
	v_mfma_f32_16x16x32_bf16 v[78:81], v[134:137], v[202:205], v[78:81]
	v_mfma_f32_16x16x32_bf16 v[78:81], v[130:133], v[198:201], v[78:81]
	v_mfma_f32_16x16x32_bf16 v[118:121], v[146:149], v[162:165], v[118:121]
	v_mfma_f32_16x16x32_bf16 v[118:121], v[150:153], v[166:169], v[118:121]
	v_mfma_f32_16x16x32_bf16 v[114:117], v[158:161], v[166:169], v[114:117]
	v_mfma_f32_16x16x32_bf16 v[114:117], v[154:157], v[162:165], v[114:117]
	v_mfma_f32_16x16x32_bf16 v[98:101], v[154:157], v[170:173], v[98:101]
	v_mfma_f32_16x16x32_bf16 v[98:101], v[158:161], v[174:177], v[98:101]
	v_mfma_f32_16x16x32_bf16 v[102:105], v[150:153], v[174:177], v[102:105]
	v_mfma_f32_16x16x32_bf16 v[102:105], v[146:149], v[170:173], v[102:105]
	v_mfma_f32_16x16x32_bf16 v[86:89], v[146:149], v[178:181], v[86:89]
	v_mfma_f32_16x16x32_bf16 v[86:89], v[150:153], v[182:185], v[86:89]
	v_mfma_f32_16x16x32_bf16 v[82:85], v[158:161], v[182:185], v[82:85]
	v_mfma_f32_16x16x32_bf16 v[82:85], v[154:157], v[178:181], v[82:85]
	v_mfma_f32_16x16x32_bf16 v[66:69], v[154:157], v[198:201], v[66:69]
	v_mfma_f32_16x16x32_bf16 v[66:69], v[158:161], v[202:205], v[66:69]
	v_mfma_f32_16x16x32_bf16 v[70:73], v[150:153], v[202:205], v[70:73]
	v_mfma_f32_16x16x32_bf16 v[70:73], v[146:149], v[198:201], v[70:73]
	s_barrier
	s_setprio 0
	s_add_i32 s65, s65, s49
	s_mov_b32 m0, s65
	ds_read_b128 v[162:165], v243 offset:16384
	ds_read_b128 v[166:169], v243 offset:17408
	ds_read_b128 v[170:173], v243 offset:18432
	ds_read_b128 v[174:177], v243 offset:19456
	ds_read_b128 v[178:181], v243 offset:20480
	ds_read_b128 v[182:185], v243 offset:21504
	ds_read_b128 v[198:201], v243 offset:22528
	ds_read_b128 v[202:205], v243 offset:23552
	global_load_lds_dwordx4 v188, s[46:47]
	s_add_i32 m0, s65, 0x2000
	s_add_u32 s90, s46, 0x4000
	s_addc_u32 s91, s47, 0
	s_add_i32 s65, s66, s49
	global_load_lds_dwordx4 v192, s[46:47]
	s_mov_b32 m0, s65
	s_nop 0
	global_load_lds_dwordx4 v188, s[90:91]
	s_add_i32 m0, s65, 0x2000
	s_nop 0
	global_load_lds_dwordx4 v192, s[90:91]
	s_mov_b32 m0, s51
	s_nop 0
	global_load_lds_dwordx4 v186, s[86:87]
	s_mov_b32 m0, s54
	s_nop 0
	global_load_lds_dwordx4 v190, s[86:87]
	s_waitcnt vmcnt(8)
	s_waitcnt lgkmcnt(0)
	s_barrier
	s_setprio 1
	v_mfma_f32_16x16x32_bf16 v[62:65], v[130:133], v[162:165], v[62:65]
	v_mfma_f32_16x16x32_bf16 v[62:65], v[134:137], v[166:169], v[62:65]
	v_mfma_f32_16x16x32_bf16 v[58:61], v[142:145], v[166:169], v[58:61]
	v_mfma_f32_16x16x32_bf16 v[58:61], v[138:141], v[162:165], v[58:61]
	v_mfma_f32_16x16x32_bf16 v[42:45], v[138:141], v[170:173], v[42:45]
	v_mfma_f32_16x16x32_bf16 v[42:45], v[142:145], v[174:177], v[42:45]
	v_mfma_f32_16x16x32_bf16 v[46:49], v[134:137], v[174:177], v[46:49]
	v_mfma_f32_16x16x32_bf16 v[46:49], v[130:133], v[170:173], v[46:49]
	v_mfma_f32_16x16x32_bf16 v[30:33], v[130:133], v[178:181], v[30:33]
	v_mfma_f32_16x16x32_bf16 v[30:33], v[134:137], v[182:185], v[30:33]
	v_mfma_f32_16x16x32_bf16 v[26:29], v[142:145], v[182:185], v[26:29]
	v_mfma_f32_16x16x32_bf16 v[26:29], v[138:141], v[178:181], v[26:29]
	v_mfma_f32_16x16x32_bf16 v[10:13], v[138:141], v[198:201], v[10:13]
	v_mfma_f32_16x16x32_bf16 v[10:13], v[142:145], v[202:205], v[10:13]
	v_mfma_f32_16x16x32_bf16 v[14:17], v[134:137], v[202:205], v[14:17]
	v_mfma_f32_16x16x32_bf16 v[14:17], v[130:133], v[198:201], v[14:17]
	v_mfma_f32_16x16x32_bf16 v[54:57], v[146:149], v[162:165], v[54:57]
	v_mfma_f32_16x16x32_bf16 v[54:57], v[150:153], v[166:169], v[54:57]
	v_mfma_f32_16x16x32_bf16 v[50:53], v[158:161], v[166:169], v[50:53]
	v_mfma_f32_16x16x32_bf16 v[50:53], v[154:157], v[162:165], v[50:53]
	v_mfma_f32_16x16x32_bf16 v[34:37], v[154:157], v[170:173], v[34:37]
	v_mfma_f32_16x16x32_bf16 v[34:37], v[158:161], v[174:177], v[34:37]
	v_mfma_f32_16x16x32_bf16 v[38:41], v[150:153], v[174:177], v[38:41]
	v_mfma_f32_16x16x32_bf16 v[38:41], v[146:149], v[170:173], v[38:41]
	v_mfma_f32_16x16x32_bf16 v[22:25], v[146:149], v[178:181], v[22:25]
	v_mfma_f32_16x16x32_bf16 v[22:25], v[150:153], v[182:185], v[22:25]
	v_mfma_f32_16x16x32_bf16 v[18:21], v[158:161], v[182:185], v[18:21]
	v_mfma_f32_16x16x32_bf16 v[18:21], v[154:157], v[178:181], v[18:21]
	v_mfma_f32_16x16x32_bf16 v[2:5], v[154:157], v[198:201], v[2:5]
	v_mfma_f32_16x16x32_bf16 v[2:5], v[158:161], v[202:205], v[2:5]
	v_mfma_f32_16x16x32_bf16 v[6:9], v[150:153], v[202:205], v[6:9]
	v_mfma_f32_16x16x32_bf16 v[6:9], v[146:149], v[198:201], v[6:9]
	s_barrier
	s_setprio 0
; #define PG8_STAGE(bufoff, gbase, voff) do { _Pragma("unroll") for (int _i = 0; _i < 2; ++_i) \
;         __builtin_amdgcn_global_load_lds((const unsigned*)((const char*)(gbase) + (voff)[_i]), (PG8_LAS unsigned*)(lds + (bufoff) + ldsw + _i * 8192), 16, 0, 0); } while (0)
; #define PG8_LDA(dst, b, h) do { _Pragma("unroll") for (int m = 0; m < 4; ++m) _Pragma("unroll") for (int k = 0; k < 2; ++k) dst[m][k] = *(const PG8_LAS bf16x8*)(lds + PG8_SA(b, h) + aoff + m * 2048 + k * 1024); } while (0)
; #define PG8_LDB(dst, b, h) do { _Pragma("unroll") for (int n = 0; n < 2; ++n) _Pragma("unroll") for (int k = 0; k < 2; ++k) dst[n][k] = *(const PG8_LAS bf16x8*)(lds + PG8_SB(b, h) + boff + n * 2048 + k * 1024); } while (0)
; #define PG8_MMA(ai, bj, At, Bt) do { __builtin_amdgcn_s_setprio(1); _Pragma("unroll") for (int m = 0; m < 4; ++m) _Pragma("unroll") for (int n = 0; n < 2; ++n) _Pragma("unroll") for (int k = 0; k < 2; ++k) \
;         acc[ai][bj][m][n] = __builtin_amdgcn_mfma_f32_16x16x32_bf16(Bt[n][k], At[m][k], acc[ai][bj][m][n], 0, 0, 0); __builtin_amdgcn_s_setprio(0); } while (0)
; #define PG8_WAIT_V(n) asm volatile("s_waitcnt vmcnt(" #n ")" ::: "memory")
; #define PG8_WAIT_L(n) asm volatile("s_waitcnt lgkmcnt(" #n ")" ::: "memory")
; #define PG8_BAR __builtin_amdgcn_s_barrier()
; #define PG8_SCHED __builtin_amdgcn_sched_barrier(0)
;     ...
;         for (int t = 0; t < nt; t += 2) {
;     ...
;             PG8_LDB(B0, 1, 0); PG8_LDB(B1, 1, 1); PG8_SCHED; PG8_LDA(At, 1, 0); PG8_STAGE(PG8_SA(0, 1), a2 + hstepA, voffA);
;             PG8_WAIT_V(8); PG8_WAIT_L(0); PG8_BAR; PG8_MMA(0, 0, At, B0); PG8_MMA(0, 1, At, B1); PG8_BAR; PG8_SCHED;
;             PG8_LDA(At, 1, 1); PG8_STAGE(PG8_SB(1, 0), b3, voffB); PG8_STAGE(PG8_SB(1, 1), b3 + hstepB, voffB); PG8_STAGE(PG8_SA(1, 0), a3, voffA);
;             PG8_WAIT_V(8); PG8_WAIT_L(0); PG8_BAR; PG8_MMA(1, 0, At, B0); PG8_MMA(1, 1, At, B1); PG8_BAR; PG8_SCHED;
.Lout_mid:
	s_add_i32 s65, 0, 0x18000
	v_add_u32_e32 v0, s65, v242
	s_add_i32 s66, 0, 0x1c000
	ds_read_b128 v[130:133], v0
	ds_read_b128 v[134:137], v0 offset:1024
	ds_read_b128 v[138:141], v0 offset:2048
	ds_read_b128 v[142:145], v0 offset:3072
	v_add_u32_e32 v0, s66, v242
	ds_read_b128 v[146:149], v0
	ds_read_b128 v[150:153], v0 offset:1024
	ds_read_b128 v[154:157], v0 offset:2048
	ds_read_b128 v[158:161], v0 offset:3072
	s_add_u32 s86, s86, 0x4000
	s_addc_u32 s87, s87, 0
	s_mov_b32 m0, s55
	ds_read_b128 v[162:165], v243 offset:32768
	ds_read_b128 v[166:169], v243 offset:33792
	ds_read_b128 v[170:173], v243 offset:34816
	ds_read_b128 v[174:177], v243 offset:35840
	ds_read_b128 v[178:181], v243 offset:36864
	ds_read_b128 v[182:185], v243 offset:37888
	ds_read_b128 v[198:201], v243 offset:38912
	ds_read_b128 v[202:205], v243 offset:39936
	global_load_lds_dwordx4 v186, s[86:87]
	s_mov_b32 m0, s61
	s_nop 0
	global_load_lds_dwordx4 v190, s[86:87]
	s_waitcnt vmcnt(8)
	s_waitcnt lgkmcnt(0)
	s_barrier
	s_setprio 1
	v_mfma_f32_16x16x32_bf16 v[126:129], v[130:133], v[162:165], v[126:129]
	v_mfma_f32_16x16x32_bf16 v[126:129], v[134:137], v[166:169], v[126:129]
	v_mfma_f32_16x16x32_bf16 v[122:125], v[142:145], v[166:169], v[122:125]
	v_mfma_f32_16x16x32_bf16 v[122:125], v[138:141], v[162:165], v[122:125]
	v_mfma_f32_16x16x32_bf16 v[106:109], v[138:141], v[170:173], v[106:109]
	v_mfma_f32_16x16x32_bf16 v[106:109], v[142:145], v[174:177], v[106:109]
	v_mfma_f32_16x16x32_bf16 v[110:113], v[134:137], v[174:177], v[110:113]
	v_mfma_f32_16x16x32_bf16 v[110:113], v[130:133], v[170:173], v[110:113]
	v_mfma_f32_16x16x32_bf16 v[94:97], v[130:133], v[178:181], v[94:97]
	v_mfma_f32_16x16x32_bf16 v[94:97], v[134:137], v[182:185], v[94:97]
	v_mfma_f32_16x16x32_bf16 v[90:93], v[142:145], v[182:185], v[90:93]
	v_mfma_f32_16x16x32_bf16 v[90:93], v[138:141], v[178:181], v[90:93]
	v_mfma_f32_16x16x32_bf16 v[74:77], v[138:141], v[198:201], v[74:77]
	v_mfma_f32_16x16x32_bf16 v[74:77], v[142:145], v[202:205], v[74:77]
	v_mfma_f32_16x16x32_bf16 v[78:81], v[134:137], v[202:205], v[78:81]
	v_mfma_f32_16x16x32_bf16 v[78:81], v[130:133], v[198:201], v[78:81]
	v_mfma_f32_16x16x32_bf16 v[118:121], v[146:149], v[162:165], v[118:121]
	v_mfma_f32_16x16x32_bf16 v[118:121], v[150:153], v[166:169], v[118:121]
	v_mfma_f32_16x16x32_bf16 v[114:117], v[158:161], v[166:169], v[114:117]
	v_mfma_f32_16x16x32_bf16 v[114:117], v[154:157], v[162:165], v[114:117]
	v_mfma_f32_16x16x32_bf16 v[98:101], v[154:157], v[170:173], v[98:101]
	v_mfma_f32_16x16x32_bf16 v[98:101], v[158:161], v[174:177], v[98:101]
	v_mfma_f32_16x16x32_bf16 v[102:105], v[150:153], v[174:177], v[102:105]
	v_mfma_f32_16x16x32_bf16 v[102:105], v[146:149], v[170:173], v[102:105]
	v_mfma_f32_16x16x32_bf16 v[86:89], v[146:149], v[178:181], v[86:89]
	v_mfma_f32_16x16x32_bf16 v[86:89], v[150:153], v[182:185], v[86:89]
	v_mfma_f32_16x16x32_bf16 v[82:85], v[158:161], v[182:185], v[82:85]
	v_mfma_f32_16x16x32_bf16 v[82:85], v[154:157], v[178:181], v[82:85]
	v_mfma_f32_16x16x32_bf16 v[66:69], v[154:157], v[198:201], v[66:69]
	v_mfma_f32_16x16x32_bf16 v[66:69], v[158:161], v[202:205], v[66:69]
	v_mfma_f32_16x16x32_bf16 v[70:73], v[150:153], v[202:205], v[70:73]
	v_mfma_f32_16x16x32_bf16 v[70:73], v[146:149], v[198:201], v[70:73]
	s_barrier
	s_setprio 0
	s_add_u32 s86, s46, 0x8000
	s_addc_u32 s87, s47, 0
	s_add_i32 s65, s65, s49
	s_mov_b32 m0, s65
	ds_read_b128 v[162:165], v243 offset:49152
	ds_read_b128 v[166:169], v243 offset:50176
	ds_read_b128 v[170:173], v243 offset:51200
	ds_read_b128 v[174:177], v243 offset:52224
	ds_read_b128 v[178:181], v243 offset:53248
	ds_read_b128 v[182:185], v243 offset:54272
	ds_read_b128 v[198:201], v243 offset:55296
	ds_read_b128 v[202:205], v243 offset:56320
	global_load_lds_dwordx4 v188, s[86:87]
	s_add_i32 m0, s65, 0x2000
	s_add_u32 s46, s46, 0xc000
	s_addc_u32 s47, s47, 0
	s_add_i32 s65, s66, s49
	global_load_lds_dwordx4 v192, s[86:87]
	s_mov_b32 m0, s65
	s_nop 0
	global_load_lds_dwordx4 v188, s[46:47]
	s_add_i32 m0, s65, 0x2000
	s_nop 0
	global_load_lds_dwordx4 v192, s[46:47]
	s_mov_b32 m0, s83
	s_nop 0
	global_load_lds_dwordx4 v186, s[36:37]
	v_lshl_add_u64 v[206:207], s[36:37], 0, v[190:191]
	s_mov_b32 m0, s85
	s_nop 0
	global_load_lds_dwordx4 v[206:207], off
	s_waitcnt vmcnt(8)
	s_waitcnt lgkmcnt(0)
	s_barrier
	s_setprio 1
	v_mfma_f32_16x16x32_bf16 v[62:65], v[130:133], v[162:165], v[62:65]
	v_mfma_f32_16x16x32_bf16 v[62:65], v[134:137], v[166:169], v[62:65]
	v_mfma_f32_16x16x32_bf16 v[58:61], v[142:145], v[166:169], v[58:61]
	v_mfma_f32_16x16x32_bf16 v[58:61], v[138:141], v[162:165], v[58:61]
	v_mfma_f32_16x16x32_bf16 v[42:45], v[138:141], v[170:173], v[42:45]
	v_mfma_f32_16x16x32_bf16 v[42:45], v[142:145], v[174:177], v[42:45]
	v_mfma_f32_16x16x32_bf16 v[46:49], v[134:137], v[174:177], v[46:49]
	v_mfma_f32_16x16x32_bf16 v[46:49], v[130:133], v[170:173], v[46:49]
	v_mfma_f32_16x16x32_bf16 v[30:33], v[130:133], v[178:181], v[30:33]
	v_mfma_f32_16x16x32_bf16 v[30:33], v[134:137], v[182:185], v[30:33]
	v_mfma_f32_16x16x32_bf16 v[26:29], v[142:145], v[182:185], v[26:29]
	v_mfma_f32_16x16x32_bf16 v[26:29], v[138:141], v[178:181], v[26:29]
	v_mfma_f32_16x16x32_bf16 v[10:13], v[138:141], v[198:201], v[10:13]
	v_mfma_f32_16x16x32_bf16 v[10:13], v[142:145], v[202:205], v[10:13]
	v_mfma_f32_16x16x32_bf16 v[14:17], v[134:137], v[202:205], v[14:17]
	v_mfma_f32_16x16x32_bf16 v[14:17], v[130:133], v[198:201], v[14:17]
	v_mfma_f32_16x16x32_bf16 v[54:57], v[146:149], v[162:165], v[54:57]
	v_mfma_f32_16x16x32_bf16 v[54:57], v[150:153], v[166:169], v[54:57]
	v_mfma_f32_16x16x32_bf16 v[50:53], v[158:161], v[166:169], v[50:53]
	v_mfma_f32_16x16x32_bf16 v[50:53], v[154:157], v[162:165], v[50:53]
	v_mfma_f32_16x16x32_bf16 v[34:37], v[154:157], v[170:173], v[34:37]
	v_mfma_f32_16x16x32_bf16 v[34:37], v[158:161], v[174:177], v[34:37]
	v_mfma_f32_16x16x32_bf16 v[38:41], v[150:153], v[174:177], v[38:41]
	v_mfma_f32_16x16x32_bf16 v[38:41], v[146:149], v[170:173], v[38:41]
	v_mfma_f32_16x16x32_bf16 v[22:25], v[146:149], v[178:181], v[22:25]
	v_mfma_f32_16x16x32_bf16 v[22:25], v[150:153], v[182:185], v[22:25]
	v_mfma_f32_16x16x32_bf16 v[18:21], v[158:161], v[182:185], v[18:21]
	v_mfma_f32_16x16x32_bf16 v[18:21], v[154:157], v[178:181], v[18:21]
	v_mfma_f32_16x16x32_bf16 v[2:5], v[154:157], v[198:201], v[2:5]
	v_mfma_f32_16x16x32_bf16 v[2:5], v[158:161], v[202:205], v[2:5]
	v_mfma_f32_16x16x32_bf16 v[6:9], v[150:153], v[202:205], v[6:9]
	v_mfma_f32_16x16x32_bf16 v[6:9], v[146:149], v[198:201], v[6:9]
	s_barrier
	s_setprio 0
	s_add_i32 s57, s57, 2
	s_add_u32 s34, s34, 0x10000
	s_addc_u32 s35, s35, 0
	s_add_u32 s44, s44, 0x10000
	s_addc_u32 s56, s56, 0
	s_cmp_gt_u32 s57, 29
	s_cbranch_scc0 .LBB0_1128
	s_and_b64 vcc, exec, s[92:93]
	s_cbranch_vccz .LBB0_1131
	s_barrier

; #define PG8_STAGE(bufoff, gbase, voff) do { _Pragma("unroll") for (int _i = 0; _i < 2; ++_i) \
;         __builtin_amdgcn_global_load_lds((const unsigned*)((const char*)(gbase) + (voff)[_i]), (PG8_LAS unsigned*)(lds + (bufoff) + ldsw + _i * 8192), 16, 0, 0); } while (0)
; #define PG8_LDA(dst, b, h) do { _Pragma("unroll") for (int m = 0; m < 4; ++m) _Pragma("unroll") for (int k = 0; k < 2; ++k) dst[m][k] = *(const PG8_LAS bf16x8*)(lds + PG8_SA(b, h) + aoff + m * 2048 + k * 1024); } while (0)
; #define PG8_LDB(dst, b, h) do { _Pragma("unroll") for (int n = 0; n < 2; ++n) _Pragma("unroll") for (int k = 0; k < 2; ++k) dst[n][k] = *(const PG8_LAS bf16x8*)(lds + PG8_SB(b, h) + boff + n * 2048 + k * 1024); } while (0)
; #define PG8_MMA(ai, bj, At, Bt) do { __builtin_amdgcn_s_setprio(1); _Pragma("unroll") for (int m = 0; m < 4; ++m) _Pragma("unroll") for (int n = 0; n < 2; ++n) _Pragma("unroll") for (int k = 0; k < 2; ++k) \
;         acc[ai][bj][m][n] = __builtin_amdgcn_mfma_f32_16x16x32_bf16(Bt[n][k], At[m][k], acc[ai][bj][m][n], 0, 0, 0); __builtin_amdgcn_s_setprio(0); } while (0)
; #define PG8_WAIT_V(n) asm volatile("s_waitcnt vmcnt(" #n ")" ::: "memory")
; #define PG8_WAIT_L(n) asm volatile("s_waitcnt lgkmcnt(" #n ")" ::: "memory")
; #define PG8_BAR __builtin_amdgcn_s_barrier()
; #define PG8_SCHED __builtin_amdgcn_sched_barrier(0)
;     ...
;         const int Ra = ROWP ? (128 * (R >> 6) + 8 * (R & 15) + ((R >> 4) & 3)) : R;
;     ...
;             PG8_LDB(B0, 0, 0); PG8_LDB(B1, 0, 1); PG8_SCHED; PG8_LDA(At, 0, 0); PG8_STAGE(PG8_SA(1, 1), a1 + hstepA, voffA);
;             PG8_WAIT_V(8); PG8_WAIT_L(0); PG8_BAR; PG8_MMA(0, 0, At, B0); PG8_MMA(0, 1, At, B1); PG8_BAR; PG8_SCHED;
;             PG8_LDA(At, 0, 1); PG8_STAGE(PG8_SB(0, 0), b2, voffB); PG8_STAGE(PG8_SB(0, 1), b2 + hstepB, voffB); PG8_STAGE(PG8_SA(0, 0), a2, voffA);
;             PG8_WAIT_V(8); PG8_WAIT_L(0); PG8_BAR; PG8_MMA(1, 0, At, B0); PG8_MMA(1, 1, At, B1); PG8_BAR; PG8_SCHED;
.Lup_nostg:
	s_add_u32 s36, s34, 0x10000
	s_addc_u32 s37, s35, 0
	s_cmp_eq_u32 s66, 28
	s_cselect_b32 s88, s57, s36
	s_cselect_b32 s89, s27, s37
	s_cselect_b32 s86, vcc_lo, vcc_hi
	s_cselect_b32 s87, s25, s65
	s_add_u32 s46, s88, 0x8000
	s_addc_u32 s47, s89, 0
	s_add_i32 s96, 0, 0x10000
	v_add_u32_e32 v0, s96, v192
	s_add_i32 s97, 0, 0x14000
	ds_read_b128 v[130:133], v0
	ds_read_b128 v[134:137], v0 offset:1024
	ds_read_b128 v[138:141], v0 offset:2048
	ds_read_b128 v[142:145], v0 offset:3072
	v_add_u32_e32 v0, s97, v192
	ds_read_b128 v[146:149], v0
	ds_read_b128 v[150:153], v0 offset:1024
	ds_read_b128 v[154:157], v0 offset:2048
	ds_read_b128 v[170:173], v0 offset:3072
	s_add_i32 m0, s48, 0xc000
	ds_read_b128 v[174:177], v193
	ds_read_b128 v[178:181], v193 offset:1024
	ds_read_b128 v[182:185], v193 offset:2048
	ds_read_b128 v[186:189], v193 offset:3072
	ds_read_b128 v[194:197], v193 offset:4096
	ds_read_b128 v[198:201], v193 offset:5120
	ds_read_b128 v[202:205], v193 offset:6144
	ds_read_b128 v[206:209], v193 offset:7168
	global_load_lds_dwordx4 v166, s[34:35]
	s_add_i32 m0, s48, 0xe000
	s_nop 0
	global_load_lds_dwordx4 v168, s[34:35]
	s_waitcnt vmcnt(8)
	s_waitcnt lgkmcnt(0)
	s_barrier
	s_setprio 1
	v_mfma_f32_16x16x32_bf16 v[126:129], v[130:133], v[174:177], 0
	v_mfma_f32_16x16x32_bf16 v[126:129], v[134:137], v[178:181], v[126:129]
	v_mfma_f32_16x16x32_bf16 v[122:125], v[142:145], v[178:181], 0
	v_mfma_f32_16x16x32_bf16 v[122:125], v[138:141], v[174:177], v[122:125]
	v_mfma_f32_16x16x32_bf16 v[114:117], v[138:141], v[182:185], 0
	v_mfma_f32_16x16x32_bf16 v[114:117], v[142:145], v[186:189], v[114:117]
	v_mfma_f32_16x16x32_bf16 v[118:121], v[134:137], v[186:189], 0
	v_mfma_f32_16x16x32_bf16 v[118:121], v[130:133], v[182:185], v[118:121]
	v_mfma_f32_16x16x32_bf16 v[110:113], v[130:133], v[194:197], 0
	v_mfma_f32_16x16x32_bf16 v[110:113], v[134:137], v[198:201], v[110:113]
	v_mfma_f32_16x16x32_bf16 v[106:109], v[142:145], v[198:201], 0
	v_mfma_f32_16x16x32_bf16 v[106:109], v[138:141], v[194:197], v[106:109]
	v_mfma_f32_16x16x32_bf16 v[98:101], v[138:141], v[202:205], 0
	v_mfma_f32_16x16x32_bf16 v[98:101], v[142:145], v[206:209], v[98:101]
	v_mfma_f32_16x16x32_bf16 v[102:105], v[134:137], v[206:209], 0
	v_mfma_f32_16x16x32_bf16 v[102:105], v[130:133], v[202:205], v[102:105]
	v_mfma_f32_16x16x32_bf16 v[30:33], v[146:149], v[174:177], 0
	v_mfma_f32_16x16x32_bf16 v[30:33], v[150:153], v[178:181], v[30:33]
	v_mfma_f32_16x16x32_bf16 v[46:49], v[170:173], v[178:181], 0
	v_mfma_f32_16x16x32_bf16 v[46:49], v[154:157], v[174:177], v[46:49]
	v_mfma_f32_16x16x32_bf16 v[34:37], v[154:157], v[182:185], 0
	v_mfma_f32_16x16x32_bf16 v[34:37], v[170:173], v[186:189], v[34:37]
	v_mfma_f32_16x16x32_bf16 v[26:29], v[150:153], v[186:189], 0
	v_mfma_f32_16x16x32_bf16 v[26:29], v[146:149], v[182:185], v[26:29]
	v_mfma_f32_16x16x32_bf16 v[94:97], v[146:149], v[194:197], 0
	v_mfma_f32_16x16x32_bf16 v[94:97], v[150:153], v[198:201], v[94:97]
	v_mfma_f32_16x16x32_bf16 v[90:93], v[170:173], v[198:201], 0
	v_mfma_f32_16x16x32_bf16 v[90:93], v[154:157], v[194:197], v[90:93]
	v_mfma_f32_16x16x32_bf16 v[82:85], v[154:157], v[202:205], 0
	v_mfma_f32_16x16x32_bf16 v[82:85], v[170:173], v[206:209], v[82:85]
	v_mfma_f32_16x16x32_bf16 v[86:89], v[150:153], v[206:209], 0
	v_mfma_f32_16x16x32_bf16 v[86:89], v[146:149], v[202:205], v[86:89]
	s_barrier
	s_setprio 0
	s_add_i32 s34, s96, s44
	s_mov_b32 m0, s34
	ds_read_b128 v[174:177], v193 offset:16384
	ds_read_b128 v[178:181], v193 offset:17408
	ds_read_b128 v[182:185], v193 offset:18432
	ds_read_b128 v[186:189], v193 offset:19456
	ds_read_b128 v[194:197], v193 offset:20480
	ds_read_b128 v[198:201], v193 offset:21504
	ds_read_b128 v[202:205], v193 offset:22528
	ds_read_b128 v[206:209], v193 offset:23552
	global_load_lds_dwordx4 v162, s[86:87]
	s_add_i32 m0, s34, 0x2000
	s_add_u32 s34, s86, 0x4000
	s_addc_u32 s35, s87, 0
	s_add_i32 s96, s97, s44
	global_load_lds_dwordx4 v158, s[86:87]
	s_mov_b32 m0, s96
	v_lshl_add_u64 v[210:211], s[88:89], 0, v[160:161]
	global_load_lds_dwordx4 v162, s[34:35]
	s_add_i32 m0, s96, 0x2000
	s_nop 0
	global_load_lds_dwordx4 v158, s[34:35]
	v_lshl_add_u64 v[190:191], s[88:89], 0, v[164:165]
	s_mov_b32 m0, s48
	s_nop 0
	global_load_lds_dwordx4 v[190:191], off
	s_mov_b32 m0, s49
	s_nop 0
	global_load_lds_dwordx4 v[210:211], off
	s_waitcnt vmcnt(8)
	s_waitcnt lgkmcnt(0)
	s_barrier
	s_setprio 1
	v_mfma_f32_16x16x32_bf16 v[78:81], v[130:133], v[174:177], 0
	v_mfma_f32_16x16x32_bf16 v[78:81], v[134:137], v[178:181], v[78:81]
	v_mfma_f32_16x16x32_bf16 v[74:77], v[142:145], v[178:181], 0
	v_mfma_f32_16x16x32_bf16 v[74:77], v[138:141], v[174:177], v[74:77]
	v_mfma_f32_16x16x32_bf16 v[66:69], v[138:141], v[182:185], 0
	v_mfma_f32_16x16x32_bf16 v[66:69], v[142:145], v[186:189], v[66:69]
	v_mfma_f32_16x16x32_bf16 v[70:73], v[134:137], v[186:189], 0
	v_mfma_f32_16x16x32_bf16 v[70:73], v[130:133], v[182:185], v[70:73]
	v_mfma_f32_16x16x32_bf16 v[42:45], v[130:133], v[194:197], 0
	v_mfma_f32_16x16x32_bf16 v[42:45], v[134:137], v[198:201], v[42:45]
	v_mfma_f32_16x16x32_bf16 v[6:9], v[142:145], v[198:201], 0
	v_mfma_f32_16x16x32_bf16 v[6:9], v[138:141], v[194:197], v[6:9]
	v_mfma_f32_16x16x32_bf16 v[2:5], v[138:141], v[202:205], 0
	v_mfma_f32_16x16x32_bf16 v[2:5], v[142:145], v[206:209], v[2:5]
	v_mfma_f32_16x16x32_bf16 v[38:41], v[134:137], v[206:209], 0
	v_mfma_f32_16x16x32_bf16 v[38:41], v[130:133], v[202:205], v[38:41]
	v_mfma_f32_16x16x32_bf16 v[62:65], v[146:149], v[174:177], 0
	v_mfma_f32_16x16x32_bf16 v[62:65], v[150:153], v[178:181], v[62:65]
	v_mfma_f32_16x16x32_bf16 v[58:61], v[170:173], v[178:181], 0
	v_mfma_f32_16x16x32_bf16 v[58:61], v[154:157], v[174:177], v[58:61]
	v_mfma_f32_16x16x32_bf16 v[50:53], v[154:157], v[182:185], 0
	v_mfma_f32_16x16x32_bf16 v[50:53], v[170:173], v[186:189], v[50:53]
	v_mfma_f32_16x16x32_bf16 v[54:57], v[150:153], v[186:189], 0
	v_mfma_f32_16x16x32_bf16 v[54:57], v[146:149], v[182:185], v[54:57]
	v_mfma_f32_16x16x32_bf16 v[22:25], v[146:149], v[194:197], 0
	v_mfma_f32_16x16x32_bf16 v[22:25], v[150:153], v[198:201], v[22:25]
	v_mfma_f32_16x16x32_bf16 v[18:21], v[170:173], v[198:201], 0
	v_mfma_f32_16x16x32_bf16 v[18:21], v[154:157], v[194:197], v[18:21]
	v_mfma_f32_16x16x32_bf16 v[10:13], v[154:157], v[202:205], 0
	v_mfma_f32_16x16x32_bf16 v[10:13], v[170:173], v[206:209], v[10:13]
	v_mfma_f32_16x16x32_bf16 v[14:17], v[150:153], v[206:209], 0
	v_mfma_f32_16x16x32_bf16 v[14:17], v[146:149], v[202:205], v[14:17]
	s_barrier
	s_setprio 0
	s_branch .Lup_mid

; #define PG8_STAGE(bufoff, gbase, voff) do { _Pragma("unroll") for (int _i = 0; _i < 2; ++_i) \
;         __builtin_amdgcn_global_load_lds((const unsigned*)((const char*)(gbase) + (voff)[_i]), (PG8_LAS unsigned*)(lds + (bufoff) + ldsw + _i * 8192), 16, 0, 0); } while (0)
; #define PG8_LDA(dst, b, h) do { _Pragma("unroll") for (int m = 0; m < 4; ++m) _Pragma("unroll") for (int k = 0; k < 2; ++k) dst[m][k] = *(const PG8_LAS bf16x8*)(lds + PG8_SA(b, h) + aoff + m * 2048 + k * 1024); } while (0)
; #define PG8_LDB(dst, b, h) do { _Pragma("unroll") for (int n = 0; n < 2; ++n) _Pragma("unroll") for (int k = 0; k < 2; ++k) dst[n][k] = *(const PG8_LAS bf16x8*)(lds + PG8_SB(b, h) + boff + n * 2048 + k * 1024); } while (0)
; #define PG8_MMA(ai, bj, At, Bt) do { __builtin_amdgcn_s_setprio(1); _Pragma("unroll") for (int m = 0; m < 4; ++m) _Pragma("unroll") for (int n = 0; n < 2; ++n) _Pragma("unroll") for (int k = 0; k < 2; ++k) \
;         acc[ai][bj][m][n] = __builtin_amdgcn_mfma_f32_16x16x32_bf16(Bt[n][k], At[m][k], acc[ai][bj][m][n], 0, 0, 0); __builtin_amdgcn_s_setprio(0); } while (0)
; #define PG8_WAIT_V(n) asm volatile("s_waitcnt vmcnt(" #n ")" ::: "memory")
; #define PG8_WAIT_L(n) asm volatile("s_waitcnt lgkmcnt(" #n ")" ::: "memory")
; #define PG8_BAR __builtin_amdgcn_s_barrier()
; #define PG8_SCHED __builtin_amdgcn_sched_barrier(0)
;     ...
;         for (int t = 0; t < nt; t += 2) {
;             const bool last = (t == nt - 2);
;             const char* a1 = cA + (ptrdiff_t)(t + 1) * kstepA;
;             const char* a2 = last ? nA : cA + (ptrdiff_t)(t + 2) * kstepA; const char* b2 = last ? nB : cB + (ptrdiff_t)(t + 2) * kstep;
;             const char* a3 = a2 + kstepA; const char* b3 = b2 + kstep;
;             if (last && has_next) S.a_ready(nxt);
;             if constexpr (SP2) {
;             PG8_LDB(B0, 0, 0); PG8_LDB(B1, 0, 1); PG8_SCHED; PG8_LDA(At, 0, 0); PG8_STAGE(PG8_SA(1, 1), a1 + hstepA, voffA);
;             PG8_WAIT_V(8); PG8_WAIT_L(0); PG8_BAR; PG8_MMA(0, 0, At, B0); PG8_MMA(0, 1, At, B1); PG8_BAR; PG8_SCHED;
;             PG8_LDA(At, 0, 1); PG8_STAGE(PG8_SB(0, 0), b2, voffB); PG8_STAGE(PG8_SB(0, 1), b2 + hstepB, voffB); PG8_STAGE(PG8_SA(0, 0), a2, voffA);
;             PG8_WAIT_V(8); PG8_WAIT_L(0); PG8_BAR; PG8_MMA(1, 0, At, B0); PG8_MMA(1, 1, At, B1); PG8_BAR; PG8_SCHED;
.LBB0_1256:
	s_add_u32 s36, s34, 0x10000
	s_addc_u32 s37, s35, 0
	s_cmp_eq_u32 s66, 28
	s_cselect_b32 s88, s57, s36
	s_cselect_b32 s89, s27, s37
	s_cselect_b32 s86, vcc_lo, vcc_hi
	s_cselect_b32 s87, s25, s65
	s_add_u32 s46, s88, 0x8000
	s_addc_u32 s47, s89, 0
	s_add_i32 s96, 0, 0x10000
	v_add_u32_e32 v0, s96, v192
	s_add_i32 s97, 0, 0x14000
	ds_read_b128 v[130:133], v0
	ds_read_b128 v[134:137], v0 offset:1024
	ds_read_b128 v[138:141], v0 offset:2048
	ds_read_b128 v[142:145], v0 offset:3072
	v_add_u32_e32 v0, s97, v192
	ds_read_b128 v[146:149], v0
	ds_read_b128 v[150:153], v0 offset:1024
	ds_read_b128 v[154:157], v0 offset:2048
	ds_read_b128 v[170:173], v0 offset:3072
	s_add_i32 m0, s48, 0xc000
	ds_read_b128 v[174:177], v193
	ds_read_b128 v[178:181], v193 offset:1024
	ds_read_b128 v[182:185], v193 offset:2048
	ds_read_b128 v[186:189], v193 offset:3072
	ds_read_b128 v[194:197], v193 offset:4096
	ds_read_b128 v[198:201], v193 offset:5120
	ds_read_b128 v[202:205], v193 offset:6144
	ds_read_b128 v[206:209], v193 offset:7168
	global_load_lds_dwordx4 v166, s[34:35]
	s_add_i32 m0, s48, 0xe000
	s_nop 0
	global_load_lds_dwordx4 v168, s[34:35]
	s_waitcnt vmcnt(8)
	s_waitcnt lgkmcnt(0)
	s_barrier
	s_setprio 1
	v_mfma_f32_16x16x32_bf16 v[126:129], v[130:133], v[174:177], v[126:129]
	v_mfma_f32_16x16x32_bf16 v[126:129], v[134:137], v[178:181], v[126:129]
	v_mfma_f32_16x16x32_bf16 v[122:125], v[142:145], v[178:181], v[122:125]
	v_mfma_f32_16x16x32_bf16 v[122:125], v[138:141], v[174:177], v[122:125]
	v_mfma_f32_16x16x32_bf16 v[114:117], v[138:141], v[182:185], v[114:117]
	v_mfma_f32_16x16x32_bf16 v[114:117], v[142:145], v[186:189], v[114:117]
	v_mfma_f32_16x16x32_bf16 v[118:121], v[134:137], v[186:189], v[118:121]
	v_mfma_f32_16x16x32_bf16 v[118:121], v[130:133], v[182:185], v[118:121]
	v_mfma_f32_16x16x32_bf16 v[110:113], v[130:133], v[194:197], v[110:113]
	v_mfma_f32_16x16x32_bf16 v[110:113], v[134:137], v[198:201], v[110:113]
	v_mfma_f32_16x16x32_bf16 v[106:109], v[142:145], v[198:201], v[106:109]
	v_mfma_f32_16x16x32_bf16 v[106:109], v[138:141], v[194:197], v[106:109]
	v_mfma_f32_16x16x32_bf16 v[98:101], v[138:141], v[202:205], v[98:101]
	v_mfma_f32_16x16x32_bf16 v[98:101], v[142:145], v[206:209], v[98:101]
	v_mfma_f32_16x16x32_bf16 v[102:105], v[134:137], v[206:209], v[102:105]
	v_mfma_f32_16x16x32_bf16 v[102:105], v[130:133], v[202:205], v[102:105]
	v_mfma_f32_16x16x32_bf16 v[30:33], v[146:149], v[174:177], v[30:33]
	v_mfma_f32_16x16x32_bf16 v[30:33], v[150:153], v[178:181], v[30:33]
	v_mfma_f32_16x16x32_bf16 v[46:49], v[170:173], v[178:181], v[46:49]
	v_mfma_f32_16x16x32_bf16 v[46:49], v[154:157], v[174:177], v[46:49]
	v_mfma_f32_16x16x32_bf16 v[34:37], v[154:157], v[182:185], v[34:37]
	v_mfma_f32_16x16x32_bf16 v[34:37], v[170:173], v[186:189], v[34:37]
	v_mfma_f32_16x16x32_bf16 v[26:29], v[150:153], v[186:189], v[26:29]
	v_mfma_f32_16x16x32_bf16 v[26:29], v[146:149], v[182:185], v[26:29]
	v_mfma_f32_16x16x32_bf16 v[94:97], v[146:149], v[194:197], v[94:97]
	v_mfma_f32_16x16x32_bf16 v[94:97], v[150:153], v[198:201], v[94:97]
	v_mfma_f32_16x16x32_bf16 v[90:93], v[170:173], v[198:201], v[90:93]
	v_mfma_f32_16x16x32_bf16 v[90:93], v[154:157], v[194:197], v[90:93]
	v_mfma_f32_16x16x32_bf16 v[82:85], v[154:157], v[202:205], v[82:85]
	v_mfma_f32_16x16x32_bf16 v[82:85], v[170:173], v[206:209], v[82:85]
	v_mfma_f32_16x16x32_bf16 v[86:89], v[150:153], v[206:209], v[86:89]
	v_mfma_f32_16x16x32_bf16 v[86:89], v[146:149], v[202:205], v[86:89]
	s_barrier
	s_setprio 0
	s_add_i32 s34, s96, s44
	s_mov_b32 m0, s34
	ds_read_b128 v[174:177], v193 offset:16384
	ds_read_b128 v[178:181], v193 offset:17408
	ds_read_b128 v[182:185], v193 offset:18432
	ds_read_b128 v[186:189], v193 offset:19456
	ds_read_b128 v[194:197], v193 offset:20480
	ds_read_b128 v[198:201], v193 offset:21504
	ds_read_b128 v[202:205], v193 offset:22528
	ds_read_b128 v[206:209], v193 offset:23552
	global_load_lds_dwordx4 v162, s[86:87]
	s_add_i32 m0, s34, 0x2000
	s_add_u32 s34, s86, 0x4000
	s_addc_u32 s35, s87, 0
	s_add_i32 s96, s97, s44
	global_load_lds_dwordx4 v158, s[86:87]
	s_mov_b32 m0, s96
	v_lshl_add_u64 v[210:211], s[88:89], 0, v[160:161]
	global_load_lds_dwordx4 v162, s[34:35]
	s_add_i32 m0, s96, 0x2000
	s_nop 0
	global_load_lds_dwordx4 v158, s[34:35]
	v_lshl_add_u64 v[190:191], s[88:89], 0, v[164:165]
	s_mov_b32 m0, s48
	s_nop 0
	global_load_lds_dwordx4 v[190:191], off
	s_mov_b32 m0, s49
	s_nop 0
	global_load_lds_dwordx4 v[210:211], off
	s_waitcnt vmcnt(8)
	s_waitcnt lgkmcnt(0)
	s_barrier
	s_setprio 1
	v_mfma_f32_16x16x32_bf16 v[78:81], v[130:133], v[174:177], v[78:81]
	v_mfma_f32_16x16x32_bf16 v[78:81], v[134:137], v[178:181], v[78:81]
	v_mfma_f32_16x16x32_bf16 v[74:77], v[142:145], v[178:181], v[74:77]
	v_mfma_f32_16x16x32_bf16 v[74:77], v[138:141], v[174:177], v[74:77]
	v_mfma_f32_16x16x32_bf16 v[66:69], v[138:141], v[182:185], v[66:69]
	v_mfma_f32_16x16x32_bf16 v[66:69], v[142:145], v[186:189], v[66:69]
	v_mfma_f32_16x16x32_bf16 v[70:73], v[134:137], v[186:189], v[70:73]
	v_mfma_f32_16x16x32_bf16 v[70:73], v[130:133], v[182:185], v[70:73]
	v_mfma_f32_16x16x32_bf16 v[42:45], v[130:133], v[194:197], v[42:45]
	v_mfma_f32_16x16x32_bf16 v[42:45], v[134:137], v[198:201], v[42:45]
	v_mfma_f32_16x16x32_bf16 v[6:9], v[142:145], v[198:201], v[6:9]
	v_mfma_f32_16x16x32_bf16 v[6:9], v[138:141], v[194:197], v[6:9]
	v_mfma_f32_16x16x32_bf16 v[2:5], v[138:141], v[202:205], v[2:5]
	v_mfma_f32_16x16x32_bf16 v[2:5], v[142:145], v[206:209], v[2:5]
	v_mfma_f32_16x16x32_bf16 v[38:41], v[134:137], v[206:209], v[38:41]
	v_mfma_f32_16x16x32_bf16 v[38:41], v[130:133], v[202:205], v[38:41]
	v_mfma_f32_16x16x32_bf16 v[62:65], v[146:149], v[174:177], v[62:65]
	v_mfma_f32_16x16x32_bf16 v[62:65], v[150:153], v[178:181], v[62:65]
	v_mfma_f32_16x16x32_bf16 v[58:61], v[170:173], v[178:181], v[58:61]
	v_mfma_f32_16x16x32_bf16 v[58:61], v[154:157], v[174:177], v[58:61]
	v_mfma_f32_16x16x32_bf16 v[50:53], v[154:157], v[182:185], v[50:53]
	v_mfma_f32_16x16x32_bf16 v[50:53], v[170:173], v[186:189], v[50:53]
	v_mfma_f32_16x16x32_bf16 v[54:57], v[150:153], v[186:189], v[54:57]
	v_mfma_f32_16x16x32_bf16 v[54:57], v[146:149], v[182:185], v[54:57]
	v_mfma_f32_16x16x32_bf16 v[22:25], v[146:149], v[194:197], v[22:25]
	v_mfma_f32_16x16x32_bf16 v[22:25], v[150:153], v[198:201], v[22:25]
	v_mfma_f32_16x16x32_bf16 v[18:21], v[170:173], v[198:201], v[18:21]
	v_mfma_f32_16x16x32_bf16 v[18:21], v[154:157], v[194:197], v[18:21]
	v_mfma_f32_16x16x32_bf16 v[10:13], v[154:157], v[202:205], v[10:13]
	v_mfma_f32_16x16x32_bf16 v[10:13], v[170:173], v[206:209], v[10:13]
	v_mfma_f32_16x16x32_bf16 v[14:17], v[150:153], v[206:209], v[14:17]
	v_mfma_f32_16x16x32_bf16 v[14:17], v[146:149], v[202:205], v[14:17]
	s_barrier
	s_setprio 0
; #define PG8_STAGE(bufoff, gbase, voff) do { _Pragma("unroll") for (int _i = 0; _i < 2; ++_i) \
;         __builtin_amdgcn_global_load_lds((const unsigned*)((const char*)(gbase) + (voff)[_i]), (PG8_LAS unsigned*)(lds + (bufoff) + ldsw + _i * 8192), 16, 0, 0); } while (0)
; #define PG8_LDA(dst, b, h) do { _Pragma("unroll") for (int m = 0; m < 4; ++m) _Pragma("unroll") for (int k = 0; k < 2; ++k) dst[m][k] = *(const PG8_LAS bf16x8*)(lds + PG8_SA(b, h) + aoff + m * 2048 + k * 1024); } while (0)
; #define PG8_LDB(dst, b, h) do { _Pragma("unroll") for (int n = 0; n < 2; ++n) _Pragma("unroll") for (int k = 0; k < 2; ++k) dst[n][k] = *(const PG8_LAS bf16x8*)(lds + PG8_SB(b, h) + boff + n * 2048 + k * 1024); } while (0)
; #define PG8_MMA(ai, bj, At, Bt) do { __builtin_amdgcn_s_setprio(1); _Pragma("unroll") for (int m = 0; m < 4; ++m) _Pragma("unroll") for (int n = 0; n < 2; ++n) _Pragma("unroll") for (int k = 0; k < 2; ++k) \
;         acc[ai][bj][m][n] = __builtin_amdgcn_mfma_f32_16x16x32_bf16(Bt[n][k], At[m][k], acc[ai][bj][m][n], 0, 0, 0); __builtin_amdgcn_s_setprio(0); } while (0)
; #define PG8_WAIT_V(n) asm volatile("s_waitcnt vmcnt(" #n ")" ::: "memory")
; #define PG8_WAIT_L(n) asm volatile("s_waitcnt lgkmcnt(" #n ")" ::: "memory")
; #define PG8_BAR __builtin_amdgcn_s_barrier()
; #define PG8_SCHED __builtin_amdgcn_sched_barrier(0)
;     ...
;         for (int t = 0; t < nt; t += 2) {
;     ...
;             PG8_LDB(B0, 1, 0); PG8_LDB(B1, 1, 1); PG8_SCHED; PG8_LDA(At, 1, 0); PG8_STAGE(PG8_SA(0, 1), a2 + hstepA, voffA);
;             PG8_WAIT_V(8); PG8_WAIT_L(0); PG8_BAR; PG8_MMA(0, 0, At, B0); PG8_MMA(0, 1, At, B1); PG8_BAR; PG8_SCHED;
;             PG8_LDA(At, 1, 1); PG8_STAGE(PG8_SB(1, 0), b3, voffB); PG8_STAGE(PG8_SB(1, 1), b3 + hstepB, voffB); PG8_STAGE(PG8_SA(1, 0), a3, voffA);
;             PG8_WAIT_V(8); PG8_WAIT_L(0); PG8_BAR; PG8_MMA(1, 0, At, B0); PG8_MMA(1, 1, At, B1); PG8_BAR; PG8_SCHED;
.Lup_mid:
	s_add_i32 s88, 0, 0x18000
	v_add_u32_e32 v0, s88, v192
	s_add_i32 s89, 0, 0x1c000
	ds_read_b128 v[130:133], v0
	ds_read_b128 v[134:137], v0 offset:1024
	ds_read_b128 v[138:141], v0 offset:2048
	ds_read_b128 v[142:145], v0 offset:3072
	v_add_u32_e32 v0, s89, v192
	ds_read_b128 v[146:149], v0
	ds_read_b128 v[150:153], v0 offset:1024
	ds_read_b128 v[154:157], v0 offset:2048
	ds_read_b128 v[170:173], v0 offset:3072
	s_mov_b32 m0, s51
	v_lshl_add_u64 v[190:191], v[190:191], 0, s[58:59]
	ds_read_b128 v[174:177], v193 offset:32768
	ds_read_b128 v[178:181], v193 offset:33792
	ds_read_b128 v[182:185], v193 offset:34816
	ds_read_b128 v[186:189], v193 offset:35840
	ds_read_b128 v[194:197], v193 offset:36864
	ds_read_b128 v[198:201], v193 offset:37888
	ds_read_b128 v[202:205], v193 offset:38912
	ds_read_b128 v[206:209], v193 offset:39936
	global_load_lds_dwordx4 v[190:191], off
	v_lshl_add_u64 v[190:191], v[210:211], 0, s[58:59]
	s_mov_b32 m0, s54
	s_nop 0
	global_load_lds_dwordx4 v[190:191], off
	s_waitcnt vmcnt(8)
	s_waitcnt lgkmcnt(0)
	s_barrier
	s_setprio 1
	v_mfma_f32_16x16x32_bf16 v[126:129], v[130:133], v[174:177], v[126:129]
	v_mfma_f32_16x16x32_bf16 v[126:129], v[134:137], v[178:181], v[126:129]
	v_mfma_f32_16x16x32_bf16 v[122:125], v[142:145], v[178:181], v[122:125]
	v_mfma_f32_16x16x32_bf16 v[122:125], v[138:141], v[174:177], v[122:125]
	v_mfma_f32_16x16x32_bf16 v[114:117], v[138:141], v[182:185], v[114:117]
	v_mfma_f32_16x16x32_bf16 v[114:117], v[142:145], v[186:189], v[114:117]
	v_mfma_f32_16x16x32_bf16 v[118:121], v[134:137], v[186:189], v[118:121]
	v_mfma_f32_16x16x32_bf16 v[118:121], v[130:133], v[182:185], v[118:121]
	v_mfma_f32_16x16x32_bf16 v[110:113], v[130:133], v[194:197], v[110:113]
	v_mfma_f32_16x16x32_bf16 v[110:113], v[134:137], v[198:201], v[110:113]
	v_mfma_f32_16x16x32_bf16 v[106:109], v[142:145], v[198:201], v[106:109]
	v_mfma_f32_16x16x32_bf16 v[106:109], v[138:141], v[194:197], v[106:109]
	v_mfma_f32_16x16x32_bf16 v[98:101], v[138:141], v[202:205], v[98:101]
	v_mfma_f32_16x16x32_bf16 v[98:101], v[142:145], v[206:209], v[98:101]
	v_mfma_f32_16x16x32_bf16 v[102:105], v[134:137], v[206:209], v[102:105]
	v_mfma_f32_16x16x32_bf16 v[102:105], v[130:133], v[202:205], v[102:105]
	v_mfma_f32_16x16x32_bf16 v[30:33], v[146:149], v[174:177], v[30:33]
	v_mfma_f32_16x16x32_bf16 v[30:33], v[150:153], v[178:181], v[30:33]
	v_mfma_f32_16x16x32_bf16 v[46:49], v[170:173], v[178:181], v[46:49]
	v_mfma_f32_16x16x32_bf16 v[46:49], v[154:157], v[174:177], v[46:49]
	v_mfma_f32_16x16x32_bf16 v[34:37], v[154:157], v[182:185], v[34:37]
	v_mfma_f32_16x16x32_bf16 v[34:37], v[170:173], v[186:189], v[34:37]
	v_mfma_f32_16x16x32_bf16 v[26:29], v[150:153], v[186:189], v[26:29]
	v_mfma_f32_16x16x32_bf16 v[26:29], v[146:149], v[182:185], v[26:29]
	v_mfma_f32_16x16x32_bf16 v[94:97], v[146:149], v[194:197], v[94:97]
	v_mfma_f32_16x16x32_bf16 v[94:97], v[150:153], v[198:201], v[94:97]
	v_mfma_f32_16x16x32_bf16 v[90:93], v[170:173], v[198:201], v[90:93]
	v_mfma_f32_16x16x32_bf16 v[90:93], v[154:157], v[194:197], v[90:93]
	v_mfma_f32_16x16x32_bf16 v[82:85], v[154:157], v[202:205], v[82:85]
	v_mfma_f32_16x16x32_bf16 v[82:85], v[170:173], v[206:209], v[82:85]
	v_mfma_f32_16x16x32_bf16 v[86:89], v[150:153], v[206:209], v[86:89]
	v_mfma_f32_16x16x32_bf16 v[86:89], v[146:149], v[202:205], v[86:89]
	s_barrier
	s_setprio 0
	s_add_u32 s34, s86, 0x8000
	s_addc_u32 s35, s87, 0
	s_add_i32 s88, s88, s44
	s_mov_b32 m0, s88
	ds_read_b128 v[174:177], v193 offset:49152
	ds_read_b128 v[178:181], v193 offset:50176
	ds_read_b128 v[182:185], v193 offset:51200
	ds_read_b128 v[186:189], v193 offset:52224
	ds_read_b128 v[194:197], v193 offset:53248
	ds_read_b128 v[198:201], v193 offset:54272
	ds_read_b128 v[202:205], v193 offset:55296
	ds_read_b128 v[206:209], v193 offset:56320
	global_load_lds_dwordx4 v162, s[34:35]
	s_add_i32 m0, s88, 0x2000
	v_lshl_add_u64 v[190:191], s[34:35], 0, v[158:159]
	s_add_u32 s34, s86, 0xc000
	s_addc_u32 s35, s87, 0
	s_add_i32 s86, s89, s44
	global_load_lds_dwordx4 v[190:191], off
	s_mov_b32 m0, s86
	s_nop 0
	global_load_lds_dwordx4 v162, s[34:35]
	s_add_i32 m0, s86, 0x2000
	s_nop 0
	global_load_lds_dwordx4 v158, s[34:35]
	s_mov_b32 m0, s85
	s_nop 0
	global_load_lds_dwordx4 v164, s[46:47]
	v_lshl_add_u64 v[190:191], s[46:47], 0, v[160:161]
	s_mov_b32 m0, s90
	s_nop 0
	global_load_lds_dwordx4 v[190:191], off
	s_waitcnt vmcnt(8)
	s_waitcnt lgkmcnt(0)
	s_barrier
	s_setprio 1
	v_mfma_f32_16x16x32_bf16 v[78:81], v[130:133], v[174:177], v[78:81]
	v_mfma_f32_16x16x32_bf16 v[78:81], v[134:137], v[178:181], v[78:81]
	v_mfma_f32_16x16x32_bf16 v[74:77], v[142:145], v[178:181], v[74:77]
	v_mfma_f32_16x16x32_bf16 v[74:77], v[138:141], v[174:177], v[74:77]
	v_mfma_f32_16x16x32_bf16 v[66:69], v[138:141], v[182:185], v[66:69]
	v_mfma_f32_16x16x32_bf16 v[66:69], v[142:145], v[186:189], v[66:69]
	v_mfma_f32_16x16x32_bf16 v[70:73], v[134:137], v[186:189], v[70:73]
	v_mfma_f32_16x16x32_bf16 v[70:73], v[130:133], v[182:185], v[70:73]
	v_mfma_f32_16x16x32_bf16 v[42:45], v[130:133], v[194:197], v[42:45]
	v_mfma_f32_16x16x32_bf16 v[42:45], v[134:137], v[198:201], v[42:45]
	v_mfma_f32_16x16x32_bf16 v[6:9], v[142:145], v[198:201], v[6:9]
	v_mfma_f32_16x16x32_bf16 v[6:9], v[138:141], v[194:197], v[6:9]
	v_mfma_f32_16x16x32_bf16 v[2:5], v[138:141], v[202:205], v[2:5]
	v_mfma_f32_16x16x32_bf16 v[2:5], v[142:145], v[206:209], v[2:5]
	v_mfma_f32_16x16x32_bf16 v[38:41], v[134:137], v[206:209], v[38:41]
	v_mfma_f32_16x16x32_bf16 v[38:41], v[130:133], v[202:205], v[38:41]
	v_mfma_f32_16x16x32_bf16 v[62:65], v[146:149], v[174:177], v[62:65]
	v_mfma_f32_16x16x32_bf16 v[62:65], v[150:153], v[178:181], v[62:65]
	v_mfma_f32_16x16x32_bf16 v[58:61], v[170:173], v[178:181], v[58:61]
	v_mfma_f32_16x16x32_bf16 v[58:61], v[154:157], v[174:177], v[58:61]
	v_mfma_f32_16x16x32_bf16 v[50:53], v[154:157], v[182:185], v[50:53]
	v_mfma_f32_16x16x32_bf16 v[50:53], v[170:173], v[186:189], v[50:53]
	v_mfma_f32_16x16x32_bf16 v[54:57], v[150:153], v[186:189], v[54:57]
	v_mfma_f32_16x16x32_bf16 v[54:57], v[146:149], v[182:185], v[54:57]
	v_mfma_f32_16x16x32_bf16 v[22:25], v[146:149], v[194:197], v[22:25]
	v_mfma_f32_16x16x32_bf16 v[22:25], v[150:153], v[198:201], v[22:25]
	v_mfma_f32_16x16x32_bf16 v[18:21], v[170:173], v[198:201], v[18:21]
	v_mfma_f32_16x16x32_bf16 v[18:21], v[154:157], v[194:197], v[18:21]
	v_mfma_f32_16x16x32_bf16 v[10:13], v[154:157], v[202:205], v[10:13]
	v_mfma_f32_16x16x32_bf16 v[10:13], v[170:173], v[206:209], v[10:13]
	v_mfma_f32_16x16x32_bf16 v[14:17], v[150:153], v[206:209], v[14:17]
	v_mfma_f32_16x16x32_bf16 v[14:17], v[146:149], v[202:205], v[14:17]
	s_barrier
	s_setprio 0
	s_add_i32 s66, s66, 2
	s_add_u32 vcc_hi, vcc_hi, 0x10000
	s_addc_u32 s65, s65, 0
	s_cmp_gt_u32 s66, 29
	s_mov_b64 s[34:35], s[36:37]
	s_cbranch_scc0 .LBB0_1256
	s_and_b64 vcc, exec, s[18:19]
	s_cbranch_vccz .LBB0_1259
	s_barrier

; #define PG8_STAGE(bufoff, gbase, voff) do { _Pragma("unroll") for (int _i = 0; _i < 2; ++_i) \
;         __builtin_amdgcn_global_load_lds((const unsigned*)((const char*)(gbase) + (voff)[_i]), (PG8_LAS unsigned*)(lds + (bufoff) + ldsw + _i * 8192), 16, 0, 0); } while (0)
; #define PG8_LDA(dst, b, h) do { _Pragma("unroll") for (int m = 0; m < 4; ++m) _Pragma("unroll") for (int k = 0; k < 2; ++k) dst[m][k] = *(const PG8_LAS bf16x8*)(lds + PG8_SA(b, h) + aoff + m * 2048 + k * 1024); } while (0)
; #define PG8_LDB(dst, b, h) do { _Pragma("unroll") for (int n = 0; n < 2; ++n) _Pragma("unroll") for (int k = 0; k < 2; ++k) dst[n][k] = *(const PG8_LAS bf16x8*)(lds + PG8_SB(b, h) + boff + n * 2048 + k * 1024); } while (0)
; #define PG8_MMA(ai, bj, At, Bt) do { __builtin_amdgcn_s_setprio(1); _Pragma("unroll") for (int m = 0; m < 4; ++m) _Pragma("unroll") for (int n = 0; n < 2; ++n) _Pragma("unroll") for (int k = 0; k < 2; ++k) \
;         acc[ai][bj][m][n] = __builtin_amdgcn_mfma_f32_16x16x32_bf16(Bt[n][k], At[m][k], acc[ai][bj][m][n], 0, 0, 0); __builtin_amdgcn_s_setprio(0); } while (0)
; #define PG8_WAIT_V(n) asm volatile("s_waitcnt vmcnt(" #n ")" ::: "memory")
; #define PG8_WAIT_L(n) asm volatile("s_waitcnt lgkmcnt(" #n ")" ::: "memory")
; #define PG8_BAR __builtin_amdgcn_s_barrier()
; #define PG8_SCHED __builtin_amdgcn_sched_barrier(0)
;     ...
;     constexpr ptrdiff_t kstep0 = KSB ? (ptrdiff_t)KSB : (ptrdiff_t)(BK * 2), kstepA0 = KSA ? (ptrdiff_t)KSA : (ptrdiff_t)(BK * 2), kstep = KREV ? -kstep0 : kstep0, kstepA = KREV ? -kstepA0 : kstepA0;
;     constexpr ptrdiff_t kofB = KREV ? (ptrdiff_t)(KK / BK - 1) * kstep0 : 0, kofA = KREV ? (ptrdiff_t)(KK / BK - 1) * kstepA0 : 0;
;     ...
;             PG8_LDB(B0, 0, 0); PG8_LDB(B1, 0, 1); PG8_SCHED; PG8_LDA(At, 0, 0); PG8_STAGE(PG8_SA(1, 1), a1 + hstepA, voffA);
;             PG8_WAIT_V(8); PG8_WAIT_L(0); PG8_BAR; PG8_MMA(0, 0, At, B0); PG8_MMA(0, 1, At, B1); PG8_BAR; PG8_SCHED;
;             PG8_LDA(At, 0, 1); PG8_STAGE(PG8_SB(0, 0), b2, voffB); PG8_STAGE(PG8_SB(0, 1), b2 + hstepB, voffB); PG8_STAGE(PG8_SA(0, 0), a2, voffA);
;             PG8_WAIT_V(8); PG8_WAIT_L(0); PG8_BAR; PG8_MMA(1, 0, At, B0); PG8_MMA(1, 1, At, B1); PG8_BAR; PG8_SCHED;
.Ldn_nostg:
	s_or_b32 s44, s56, 1
	s_lshl_b64 s[34:35], s[44:45], 15
	s_sub_u32 s34, 0, s34
	s_subb_u32 s35, 0, s35
	s_add_u32 s44, s28, s34
	s_addc_u32 s65, s29, s35
	s_add_u32 s34, s30, 0xffff8000
	s_addc_u32 s35, s31, -1
	s_add_i32 s66, 0, 0x10000
	v_add_u32_e32 v0, s66, v230
	s_add_i32 s90, 0, 0x14000
	s_waitcnt lgkmcnt(0)
	ds_read_b128 v[130:133], v0
	ds_read_b128 v[134:137], v0 offset:1024
	ds_read_b128 v[138:141], v0 offset:2048
	ds_read_b128 v[142:145], v0 offset:3072
	v_add_u32_e32 v0, s90, v230
	ds_read_b128 v[146:149], v0
	ds_read_b128 v[150:153], v0 offset:1024
	ds_read_b128 v[154:157], v0 offset:2048
	ds_read_b128 v[158:161], v0 offset:3072
	s_add_u32 s88, s44, 0x4000
	s_addc_u32 s89, s65, 0
	s_add_i32 m0, s46, 0xc000
	ds_read_b128 v[162:165], v231
	ds_read_b128 v[166:169], v231 offset:1024
	ds_read_b128 v[170:173], v231 offset:2048
	ds_read_b128 v[174:177], v231 offset:3072
	ds_read_b128 v[178:181], v231 offset:4096
	ds_read_b128 v[182:185], v231 offset:5120
	ds_read_b128 v[186:189], v231 offset:6144
	ds_read_b128 v[190:193], v231 offset:7168
	global_load_lds_dwordx4 v194, s[88:89]
	s_add_i32 m0, s46, 0xe000
	s_nop 0
	global_load_lds_dwordx4 v198, s[88:89]
	s_waitcnt vmcnt(8)
	s_waitcnt lgkmcnt(0)
	s_barrier
	s_setprio 1
	v_mfma_f32_16x16x32_bf16 v[126:129], v[130:133], v[162:165], 0
	v_mfma_f32_16x16x32_bf16 v[126:129], v[134:137], v[166:169], v[126:129]
	v_mfma_f32_16x16x32_bf16 v[122:125], v[142:145], v[166:169], 0
	v_mfma_f32_16x16x32_bf16 v[122:125], v[138:141], v[162:165], v[122:125]
	v_mfma_f32_16x16x32_bf16 v[106:109], v[138:141], v[170:173], 0
	v_mfma_f32_16x16x32_bf16 v[106:109], v[142:145], v[174:177], v[106:109]
	v_mfma_f32_16x16x32_bf16 v[110:113], v[134:137], v[174:177], 0
	v_mfma_f32_16x16x32_bf16 v[110:113], v[130:133], v[170:173], v[110:113]
	v_mfma_f32_16x16x32_bf16 v[94:97], v[130:133], v[178:181], 0
	v_mfma_f32_16x16x32_bf16 v[94:97], v[134:137], v[182:185], v[94:97]
	v_mfma_f32_16x16x32_bf16 v[90:93], v[142:145], v[182:185], 0
	v_mfma_f32_16x16x32_bf16 v[90:93], v[138:141], v[178:181], v[90:93]
	v_mfma_f32_16x16x32_bf16 v[74:77], v[138:141], v[186:189], 0
	v_mfma_f32_16x16x32_bf16 v[74:77], v[142:145], v[190:193], v[74:77]
	v_mfma_f32_16x16x32_bf16 v[78:81], v[134:137], v[190:193], 0
	v_mfma_f32_16x16x32_bf16 v[78:81], v[130:133], v[186:189], v[78:81]
	v_mfma_f32_16x16x32_bf16 v[118:121], v[146:149], v[162:165], 0
	v_mfma_f32_16x16x32_bf16 v[118:121], v[150:153], v[166:169], v[118:121]
	v_mfma_f32_16x16x32_bf16 v[114:117], v[158:161], v[166:169], 0
	v_mfma_f32_16x16x32_bf16 v[114:117], v[154:157], v[162:165], v[114:117]
	v_mfma_f32_16x16x32_bf16 v[98:101], v[154:157], v[170:173], 0
	v_mfma_f32_16x16x32_bf16 v[98:101], v[158:161], v[174:177], v[98:101]
	v_mfma_f32_16x16x32_bf16 v[102:105], v[150:153], v[174:177], 0
	v_mfma_f32_16x16x32_bf16 v[102:105], v[146:149], v[170:173], v[102:105]
	v_mfma_f32_16x16x32_bf16 v[86:89], v[146:149], v[178:181], 0
	v_mfma_f32_16x16x32_bf16 v[86:89], v[150:153], v[182:185], v[86:89]
	v_mfma_f32_16x16x32_bf16 v[82:85], v[158:161], v[182:185], 0
	v_mfma_f32_16x16x32_bf16 v[82:85], v[154:157], v[178:181], v[82:85]
	v_mfma_f32_16x16x32_bf16 v[66:69], v[154:157], v[186:189], 0
	v_mfma_f32_16x16x32_bf16 v[66:69], v[158:161], v[190:193], v[66:69]
	v_mfma_f32_16x16x32_bf16 v[70:73], v[150:153], v[190:193], 0
	v_mfma_f32_16x16x32_bf16 v[70:73], v[146:149], v[186:189], v[70:73]
	s_barrier
	s_setprio 0
	s_add_i32 s44, s66, s41
	s_mov_b32 m0, s44
	ds_read_b128 v[162:165], v231 offset:16384
	ds_read_b128 v[166:169], v231 offset:17408
	ds_read_b128 v[170:173], v231 offset:18432
	ds_read_b128 v[174:177], v231 offset:19456
	ds_read_b128 v[178:181], v231 offset:20480
	ds_read_b128 v[182:185], v231 offset:21504
	ds_read_b128 v[186:189], v231 offset:22528
	ds_read_b128 v[190:193], v231 offset:23552
	global_load_lds_dwordx4 v196, s[8:9]
	s_add_i32 m0, s44, 0x2000
	s_add_u32 s88, s8, 0x4000
	s_addc_u32 s89, s9, 0
	s_add_i32 s44, s90, s41
	global_load_lds_dwordx4 v200, s[8:9]
	s_mov_b32 m0, s44
	s_nop 0
	global_load_lds_dwordx4 v196, s[88:89]
	s_add_i32 m0, s44, 0x2000
	s_nop 0
	global_load_lds_dwordx4 v200, s[88:89]
	s_mov_b32 m0, s46
	s_nop 0
	global_load_lds_dwordx4 v194, s[30:31]
	s_mov_b32 m0, s47
	s_nop 0
	global_load_lds_dwordx4 v198, s[30:31]
	s_waitcnt vmcnt(8)
	s_waitcnt lgkmcnt(0)
	s_barrier
	s_setprio 1
	v_mfma_f32_16x16x32_bf16 v[62:65], v[130:133], v[162:165], 0
	v_mfma_f32_16x16x32_bf16 v[62:65], v[134:137], v[166:169], v[62:65]
	v_mfma_f32_16x16x32_bf16 v[58:61], v[142:145], v[166:169], 0
	v_mfma_f32_16x16x32_bf16 v[58:61], v[138:141], v[162:165], v[58:61]
	v_mfma_f32_16x16x32_bf16 v[42:45], v[138:141], v[170:173], 0
	v_mfma_f32_16x16x32_bf16 v[42:45], v[142:145], v[174:177], v[42:45]
	v_mfma_f32_16x16x32_bf16 v[46:49], v[134:137], v[174:177], 0
	v_mfma_f32_16x16x32_bf16 v[46:49], v[130:133], v[170:173], v[46:49]
	v_mfma_f32_16x16x32_bf16 v[30:33], v[130:133], v[178:181], 0
	v_mfma_f32_16x16x32_bf16 v[30:33], v[134:137], v[182:185], v[30:33]
	v_mfma_f32_16x16x32_bf16 v[26:29], v[142:145], v[182:185], 0
	v_mfma_f32_16x16x32_bf16 v[26:29], v[138:141], v[178:181], v[26:29]
	v_mfma_f32_16x16x32_bf16 v[10:13], v[138:141], v[186:189], 0
	v_mfma_f32_16x16x32_bf16 v[10:13], v[142:145], v[190:193], v[10:13]
	v_mfma_f32_16x16x32_bf16 v[14:17], v[134:137], v[190:193], 0
	v_mfma_f32_16x16x32_bf16 v[14:17], v[130:133], v[186:189], v[14:17]
	v_mfma_f32_16x16x32_bf16 v[54:57], v[146:149], v[162:165], 0
	v_mfma_f32_16x16x32_bf16 v[54:57], v[150:153], v[166:169], v[54:57]
	v_mfma_f32_16x16x32_bf16 v[50:53], v[158:161], v[166:169], 0
	v_mfma_f32_16x16x32_bf16 v[50:53], v[154:157], v[162:165], v[50:53]
	v_mfma_f32_16x16x32_bf16 v[34:37], v[154:157], v[170:173], 0
	v_mfma_f32_16x16x32_bf16 v[34:37], v[158:161], v[174:177], v[34:37]
	v_mfma_f32_16x16x32_bf16 v[38:41], v[150:153], v[174:177], 0
	v_mfma_f32_16x16x32_bf16 v[38:41], v[146:149], v[170:173], v[38:41]
	v_mfma_f32_16x16x32_bf16 v[22:25], v[146:149], v[178:181], 0
	v_mfma_f32_16x16x32_bf16 v[22:25], v[150:153], v[182:185], v[22:25]
	v_mfma_f32_16x16x32_bf16 v[18:21], v[158:161], v[182:185], 0
	v_mfma_f32_16x16x32_bf16 v[18:21], v[154:157], v[178:181], v[18:21]
	v_mfma_f32_16x16x32_bf16 v[2:5], v[154:157], v[186:189], 0
	v_mfma_f32_16x16x32_bf16 v[2:5], v[158:161], v[190:193], v[2:5]
	v_mfma_f32_16x16x32_bf16 v[6:9], v[150:153], v[190:193], 0
	v_mfma_f32_16x16x32_bf16 v[6:9], v[146:149], v[186:189], v[6:9]
	s_barrier
	s_setprio 0
	s_branch .Ldn_mid

; #define PG8_STAGE(bufoff, gbase, voff) do { _Pragma("unroll") for (int _i = 0; _i < 2; ++_i) \
;         __builtin_amdgcn_global_load_lds((const unsigned*)((const char*)(gbase) + (voff)[_i]), (PG8_LAS unsigned*)(lds + (bufoff) + ldsw + _i * 8192), 16, 0, 0); } while (0)
; #define PG8_LDA(dst, b, h) do { _Pragma("unroll") for (int m = 0; m < 4; ++m) _Pragma("unroll") for (int k = 0; k < 2; ++k) dst[m][k] = *(const PG8_LAS bf16x8*)(lds + PG8_SA(b, h) + aoff + m * 2048 + k * 1024); } while (0)
; #define PG8_LDB(dst, b, h) do { _Pragma("unroll") for (int n = 0; n < 2; ++n) _Pragma("unroll") for (int k = 0; k < 2; ++k) dst[n][k] = *(const PG8_LAS bf16x8*)(lds + PG8_SB(b, h) + boff + n * 2048 + k * 1024); } while (0)
; #define PG8_MMA(ai, bj, At, Bt) do { __builtin_amdgcn_s_setprio(1); _Pragma("unroll") for (int m = 0; m < 4; ++m) _Pragma("unroll") for (int n = 0; n < 2; ++n) _Pragma("unroll") for (int k = 0; k < 2; ++k) \
;         acc[ai][bj][m][n] = __builtin_amdgcn_mfma_f32_16x16x32_bf16(Bt[n][k], At[m][k], acc[ai][bj][m][n], 0, 0, 0); __builtin_amdgcn_s_setprio(0); } while (0)
; #define PG8_WAIT_V(n) asm volatile("s_waitcnt vmcnt(" #n ")" ::: "memory")
; #define PG8_WAIT_L(n) asm volatile("s_waitcnt lgkmcnt(" #n ")" ::: "memory")
; #define PG8_BAR __builtin_amdgcn_s_barrier()
; #define PG8_SCHED __builtin_amdgcn_sched_barrier(0)
;     ...
;         for (int t = 0; t < nt; t += 2) {
;             const bool last = (t == nt - 2);
;             const char* a1 = cA + (ptrdiff_t)(t + 1) * kstepA;
;             const char* a2 = last ? nA : cA + (ptrdiff_t)(t + 2) * kstepA; const char* b2 = last ? nB : cB + (ptrdiff_t)(t + 2) * kstep;
;             const char* a3 = a2 + kstepA; const char* b3 = b2 + kstep;
;             if (last && has_next) S.a_ready(nxt);
;             if constexpr (SP2) {
;             PG8_LDB(B0, 0, 0); PG8_LDB(B1, 0, 1); PG8_SCHED; PG8_LDA(At, 0, 0); PG8_STAGE(PG8_SA(1, 1), a1 + hstepA, voffA);
;             PG8_WAIT_V(8); PG8_WAIT_L(0); PG8_BAR; PG8_MMA(0, 0, At, B0); PG8_MMA(0, 1, At, B1); PG8_BAR; PG8_SCHED;
;             PG8_LDA(At, 0, 1); PG8_STAGE(PG8_SB(0, 0), b2, voffB); PG8_STAGE(PG8_SB(0, 1), b2 + hstepB, voffB); PG8_STAGE(PG8_SA(0, 0), a2, voffA);
;             PG8_WAIT_V(8); PG8_WAIT_L(0); PG8_BAR; PG8_MMA(1, 0, At, B0); PG8_MMA(1, 1, At, B1); PG8_BAR; PG8_SCHED;
.LBB0_1444:
	s_or_b32 s44, s56, 1
	s_lshl_b64 s[34:35], s[44:45], 15
	s_sub_u32 s34, 0, s34
	s_subb_u32 s35, 0, s35
	s_add_u32 s44, s28, s34
	s_addc_u32 s65, s29, s35
	s_add_u32 s34, s30, 0xffff8000
	s_addc_u32 s35, s31, -1
	s_add_i32 s66, 0, 0x10000
	v_add_u32_e32 v0, s66, v230
	s_add_i32 s90, 0, 0x14000
	s_waitcnt lgkmcnt(0)
	ds_read_b128 v[130:133], v0
	ds_read_b128 v[134:137], v0 offset:1024
	ds_read_b128 v[138:141], v0 offset:2048
	ds_read_b128 v[142:145], v0 offset:3072
	v_add_u32_e32 v0, s90, v230
	ds_read_b128 v[146:149], v0
	ds_read_b128 v[150:153], v0 offset:1024
	ds_read_b128 v[154:157], v0 offset:2048
	ds_read_b128 v[158:161], v0 offset:3072
	s_add_u32 s88, s44, 0x4000
	s_addc_u32 s89, s65, 0
	s_add_i32 m0, s46, 0xc000
	ds_read_b128 v[162:165], v231
	ds_read_b128 v[166:169], v231 offset:1024
	ds_read_b128 v[170:173], v231 offset:2048
	ds_read_b128 v[174:177], v231 offset:3072
	ds_read_b128 v[178:181], v231 offset:4096
	ds_read_b128 v[182:185], v231 offset:5120
	ds_read_b128 v[186:189], v231 offset:6144
	ds_read_b128 v[190:193], v231 offset:7168
	global_load_lds_dwordx4 v194, s[88:89]
	s_add_i32 m0, s46, 0xe000
	s_nop 0
	global_load_lds_dwordx4 v198, s[88:89]
	s_waitcnt vmcnt(8)
	s_waitcnt lgkmcnt(0)
	s_barrier
	s_setprio 1
	v_mfma_f32_16x16x32_bf16 v[126:129], v[130:133], v[162:165], v[126:129]
	v_mfma_f32_16x16x32_bf16 v[126:129], v[134:137], v[166:169], v[126:129]
	v_mfma_f32_16x16x32_bf16 v[122:125], v[142:145], v[166:169], v[122:125]
	v_mfma_f32_16x16x32_bf16 v[122:125], v[138:141], v[162:165], v[122:125]
	v_mfma_f32_16x16x32_bf16 v[106:109], v[138:141], v[170:173], v[106:109]
	v_mfma_f32_16x16x32_bf16 v[106:109], v[142:145], v[174:177], v[106:109]
	v_mfma_f32_16x16x32_bf16 v[110:113], v[134:137], v[174:177], v[110:113]
	v_mfma_f32_16x16x32_bf16 v[110:113], v[130:133], v[170:173], v[110:113]
	v_mfma_f32_16x16x32_bf16 v[94:97], v[130:133], v[178:181], v[94:97]
	v_mfma_f32_16x16x32_bf16 v[94:97], v[134:137], v[182:185], v[94:97]
	v_mfma_f32_16x16x32_bf16 v[90:93], v[142:145], v[182:185], v[90:93]
	v_mfma_f32_16x16x32_bf16 v[90:93], v[138:141], v[178:181], v[90:93]
	v_mfma_f32_16x16x32_bf16 v[74:77], v[138:141], v[186:189], v[74:77]
	v_mfma_f32_16x16x32_bf16 v[74:77], v[142:145], v[190:193], v[74:77]
	v_mfma_f32_16x16x32_bf16 v[78:81], v[134:137], v[190:193], v[78:81]
	v_mfma_f32_16x16x32_bf16 v[78:81], v[130:133], v[186:189], v[78:81]
	v_mfma_f32_16x16x32_bf16 v[118:121], v[146:149], v[162:165], v[118:121]
	v_mfma_f32_16x16x32_bf16 v[118:121], v[150:153], v[166:169], v[118:121]
	v_mfma_f32_16x16x32_bf16 v[114:117], v[158:161], v[166:169], v[114:117]
	v_mfma_f32_16x16x32_bf16 v[114:117], v[154:157], v[162:165], v[114:117]
	v_mfma_f32_16x16x32_bf16 v[98:101], v[154:157], v[170:173], v[98:101]
	v_mfma_f32_16x16x32_bf16 v[98:101], v[158:161], v[174:177], v[98:101]
	v_mfma_f32_16x16x32_bf16 v[102:105], v[150:153], v[174:177], v[102:105]
	v_mfma_f32_16x16x32_bf16 v[102:105], v[146:149], v[170:173], v[102:105]
	v_mfma_f32_16x16x32_bf16 v[86:89], v[146:149], v[178:181], v[86:89]
	v_mfma_f32_16x16x32_bf16 v[86:89], v[150:153], v[182:185], v[86:89]
	v_mfma_f32_16x16x32_bf16 v[82:85], v[158:161], v[182:185], v[82:85]
	v_mfma_f32_16x16x32_bf16 v[82:85], v[154:157], v[178:181], v[82:85]
	v_mfma_f32_16x16x32_bf16 v[66:69], v[154:157], v[186:189], v[66:69]
	v_mfma_f32_16x16x32_bf16 v[66:69], v[158:161], v[190:193], v[66:69]
	v_mfma_f32_16x16x32_bf16 v[70:73], v[150:153], v[190:193], v[70:73]
	v_mfma_f32_16x16x32_bf16 v[70:73], v[146:149], v[186:189], v[70:73]
	s_barrier
	s_setprio 0
	s_add_i32 s44, s66, s41
	s_mov_b32 m0, s44
	ds_read_b128 v[162:165], v231 offset:16384
	ds_read_b128 v[166:169], v231 offset:17408
	ds_read_b128 v[170:173], v231 offset:18432
	ds_read_b128 v[174:177], v231 offset:19456
	ds_read_b128 v[178:181], v231 offset:20480
	ds_read_b128 v[182:185], v231 offset:21504
	ds_read_b128 v[186:189], v231 offset:22528
	ds_read_b128 v[190:193], v231 offset:23552
	global_load_lds_dwordx4 v196, s[8:9]
	s_add_i32 m0, s44, 0x2000
	s_add_u32 s88, s8, 0x4000
	s_addc_u32 s89, s9, 0
	s_add_i32 s44, s90, s41
	global_load_lds_dwordx4 v200, s[8:9]
	s_mov_b32 m0, s44
	s_nop 0
	global_load_lds_dwordx4 v196, s[88:89]
	s_add_i32 m0, s44, 0x2000
	s_nop 0
	global_load_lds_dwordx4 v200, s[88:89]
	s_mov_b32 m0, s46
	s_nop 0
	global_load_lds_dwordx4 v194, s[30:31]
	s_mov_b32 m0, s47
	s_nop 0
	global_load_lds_dwordx4 v198, s[30:31]
	s_waitcnt vmcnt(8)
	s_waitcnt lgkmcnt(0)
	s_barrier
	s_setprio 1
	v_mfma_f32_16x16x32_bf16 v[62:65], v[130:133], v[162:165], v[62:65]
	v_mfma_f32_16x16x32_bf16 v[62:65], v[134:137], v[166:169], v[62:65]
	v_mfma_f32_16x16x32_bf16 v[58:61], v[142:145], v[166:169], v[58:61]
	v_mfma_f32_16x16x32_bf16 v[58:61], v[138:141], v[162:165], v[58:61]
	v_mfma_f32_16x16x32_bf16 v[42:45], v[138:141], v[170:173], v[42:45]
	v_mfma_f32_16x16x32_bf16 v[42:45], v[142:145], v[174:177], v[42:45]
	v_mfma_f32_16x16x32_bf16 v[46:49], v[134:137], v[174:177], v[46:49]
	v_mfma_f32_16x16x32_bf16 v[46:49], v[130:133], v[170:173], v[46:49]
	v_mfma_f32_16x16x32_bf16 v[30:33], v[130:133], v[178:181], v[30:33]
	v_mfma_f32_16x16x32_bf16 v[30:33], v[134:137], v[182:185], v[30:33]
	v_mfma_f32_16x16x32_bf16 v[26:29], v[142:145], v[182:185], v[26:29]
	v_mfma_f32_16x16x32_bf16 v[26:29], v[138:141], v[178:181], v[26:29]
	v_mfma_f32_16x16x32_bf16 v[10:13], v[138:141], v[186:189], v[10:13]
	v_mfma_f32_16x16x32_bf16 v[10:13], v[142:145], v[190:193], v[10:13]
	v_mfma_f32_16x16x32_bf16 v[14:17], v[134:137], v[190:193], v[14:17]
	v_mfma_f32_16x16x32_bf16 v[14:17], v[130:133], v[186:189], v[14:17]
	v_mfma_f32_16x16x32_bf16 v[54:57], v[146:149], v[162:165], v[54:57]
	v_mfma_f32_16x16x32_bf16 v[54:57], v[150:153], v[166:169], v[54:57]
	v_mfma_f32_16x16x32_bf16 v[50:53], v[158:161], v[166:169], v[50:53]
	v_mfma_f32_16x16x32_bf16 v[50:53], v[154:157], v[162:165], v[50:53]
	v_mfma_f32_16x16x32_bf16 v[34:37], v[154:157], v[170:173], v[34:37]
	v_mfma_f32_16x16x32_bf16 v[34:37], v[158:161], v[174:177], v[34:37]
	v_mfma_f32_16x16x32_bf16 v[38:41], v[150:153], v[174:177], v[38:41]
	v_mfma_f32_16x16x32_bf16 v[38:41], v[146:149], v[170:173], v[38:41]
	v_mfma_f32_16x16x32_bf16 v[22:25], v[146:149], v[178:181], v[22:25]
	v_mfma_f32_16x16x32_bf16 v[22:25], v[150:153], v[182:185], v[22:25]
	v_mfma_f32_16x16x32_bf16 v[18:21], v[158:161], v[182:185], v[18:21]
	v_mfma_f32_16x16x32_bf16 v[18:21], v[154:157], v[178:181], v[18:21]
	v_mfma_f32_16x16x32_bf16 v[2:5], v[154:157], v[186:189], v[2:5]
	v_mfma_f32_16x16x32_bf16 v[2:5], v[158:161], v[190:193], v[2:5]
	v_mfma_f32_16x16x32_bf16 v[6:9], v[150:153], v[190:193], v[6:9]
	v_mfma_f32_16x16x32_bf16 v[6:9], v[146:149], v[186:189], v[6:9]
	s_barrier
	s_setprio 0
; #define PG8_STAGE(bufoff, gbase, voff) do { _Pragma("unroll") for (int _i = 0; _i < 2; ++_i) \
;         __builtin_amdgcn_global_load_lds((const unsigned*)((const char*)(gbase) + (voff)[_i]), (PG8_LAS unsigned*)(lds + (bufoff) + ldsw + _i * 8192), 16, 0, 0); } while (0)
; #define PG8_LDA(dst, b, h) do { _Pragma("unroll") for (int m = 0; m < 4; ++m) _Pragma("unroll") for (int k = 0; k < 2; ++k) dst[m][k] = *(const PG8_LAS bf16x8*)(lds + PG8_SA(b, h) + aoff + m * 2048 + k * 1024); } while (0)
; #define PG8_LDB(dst, b, h) do { _Pragma("unroll") for (int n = 0; n < 2; ++n) _Pragma("unroll") for (int k = 0; k < 2; ++k) dst[n][k] = *(const PG8_LAS bf16x8*)(lds + PG8_SB(b, h) + boff + n * 2048 + k * 1024); } while (0)
; #define PG8_MMA(ai, bj, At, Bt) do { __builtin_amdgcn_s_setprio(1); _Pragma("unroll") for (int m = 0; m < 4; ++m) _Pragma("unroll") for (int n = 0; n < 2; ++n) _Pragma("unroll") for (int k = 0; k < 2; ++k) \
;         acc[ai][bj][m][n] = __builtin_amdgcn_mfma_f32_16x16x32_bf16(Bt[n][k], At[m][k], acc[ai][bj][m][n], 0, 0, 0); __builtin_amdgcn_s_setprio(0); } while (0)
; #define PG8_WAIT_V(n) asm volatile("s_waitcnt vmcnt(" #n ")" ::: "memory")
; #define PG8_WAIT_L(n) asm volatile("s_waitcnt lgkmcnt(" #n ")" ::: "memory")
; #define PG8_BAR __builtin_amdgcn_s_barrier()
; #define PG8_SCHED __builtin_amdgcn_sched_barrier(0)
;     ...
;         for (int t = 0; t < nt; t += 2) {
;     ...
;             PG8_LDB(B0, 1, 0); PG8_LDB(B1, 1, 1); PG8_SCHED; PG8_LDA(At, 1, 0); PG8_STAGE(PG8_SA(0, 1), a2 + hstepA, voffA);
;             PG8_WAIT_V(8); PG8_WAIT_L(0); PG8_BAR; PG8_MMA(0, 0, At, B0); PG8_MMA(0, 1, At, B1); PG8_BAR; PG8_SCHED;
;             PG8_LDA(At, 1, 1); PG8_STAGE(PG8_SB(1, 0), b3, voffB); PG8_STAGE(PG8_SB(1, 1), b3 + hstepB, voffB); PG8_STAGE(PG8_SA(1, 0), a3, voffA);
;             PG8_WAIT_V(8); PG8_WAIT_L(0); PG8_BAR; PG8_MMA(1, 0, At, B0); PG8_MMA(1, 1, At, B1); PG8_BAR; PG8_SCHED;
.Ldn_mid:
	s_add_i32 s44, 0, 0x18000
	v_add_u32_e32 v0, s44, v230
	s_add_i32 s65, 0, 0x1c000
	ds_read_b128 v[130:133], v0
	ds_read_b128 v[134:137], v0 offset:1024
	ds_read_b128 v[138:141], v0 offset:2048
	ds_read_b128 v[142:145], v0 offset:3072
	v_add_u32_e32 v0, s65, v230
	ds_read_b128 v[146:149], v0
	ds_read_b128 v[150:153], v0 offset:1024
	ds_read_b128 v[154:157], v0 offset:2048
	ds_read_b128 v[158:161], v0 offset:3072
	s_add_u32 s30, s30, 0x4000
	s_addc_u32 s31, s31, 0
	s_mov_b32 m0, s48
	ds_read_b128 v[162:165], v231 offset:32768
	ds_read_b128 v[166:169], v231 offset:33792
	ds_read_b128 v[170:173], v231 offset:34816
	ds_read_b128 v[174:177], v231 offset:35840
	ds_read_b128 v[178:181], v231 offset:36864
	ds_read_b128 v[182:185], v231 offset:37888
	ds_read_b128 v[186:189], v231 offset:38912
	ds_read_b128 v[190:193], v231 offset:39936
	global_load_lds_dwordx4 v194, s[30:31]
	s_mov_b32 m0, s49
	s_nop 0
	global_load_lds_dwordx4 v198, s[30:31]
	s_waitcnt vmcnt(8)
	s_waitcnt lgkmcnt(0)
	s_barrier
	s_setprio 1
	v_mfma_f32_16x16x32_bf16 v[126:129], v[130:133], v[162:165], v[126:129]
	v_mfma_f32_16x16x32_bf16 v[126:129], v[134:137], v[166:169], v[126:129]
	v_mfma_f32_16x16x32_bf16 v[122:125], v[142:145], v[166:169], v[122:125]
	v_mfma_f32_16x16x32_bf16 v[122:125], v[138:141], v[162:165], v[122:125]
	v_mfma_f32_16x16x32_bf16 v[106:109], v[138:141], v[170:173], v[106:109]
	v_mfma_f32_16x16x32_bf16 v[106:109], v[142:145], v[174:177], v[106:109]
	v_mfma_f32_16x16x32_bf16 v[110:113], v[134:137], v[174:177], v[110:113]
	v_mfma_f32_16x16x32_bf16 v[110:113], v[130:133], v[170:173], v[110:113]
	v_mfma_f32_16x16x32_bf16 v[94:97], v[130:133], v[178:181], v[94:97]
	v_mfma_f32_16x16x32_bf16 v[94:97], v[134:137], v[182:185], v[94:97]
	v_mfma_f32_16x16x32_bf16 v[90:93], v[142:145], v[182:185], v[90:93]
	v_mfma_f32_16x16x32_bf16 v[90:93], v[138:141], v[178:181], v[90:93]
	v_mfma_f32_16x16x32_bf16 v[74:77], v[138:141], v[186:189], v[74:77]
	v_mfma_f32_16x16x32_bf16 v[74:77], v[142:145], v[190:193], v[74:77]
	v_mfma_f32_16x16x32_bf16 v[78:81], v[134:137], v[190:193], v[78:81]
	v_mfma_f32_16x16x32_bf16 v[78:81], v[130:133], v[186:189], v[78:81]
	v_mfma_f32_16x16x32_bf16 v[118:121], v[146:149], v[162:165], v[118:121]
	v_mfma_f32_16x16x32_bf16 v[118:121], v[150:153], v[166:169], v[118:121]
	v_mfma_f32_16x16x32_bf16 v[114:117], v[158:161], v[166:169], v[114:117]
	v_mfma_f32_16x16x32_bf16 v[114:117], v[154:157], v[162:165], v[114:117]
	v_mfma_f32_16x16x32_bf16 v[98:101], v[154:157], v[170:173], v[98:101]
	v_mfma_f32_16x16x32_bf16 v[98:101], v[158:161], v[174:177], v[98:101]
	v_mfma_f32_16x16x32_bf16 v[102:105], v[150:153], v[174:177], v[102:105]
	v_mfma_f32_16x16x32_bf16 v[102:105], v[146:149], v[170:173], v[102:105]
	v_mfma_f32_16x16x32_bf16 v[86:89], v[146:149], v[178:181], v[86:89]
	v_mfma_f32_16x16x32_bf16 v[86:89], v[150:153], v[182:185], v[86:89]
	v_mfma_f32_16x16x32_bf16 v[82:85], v[158:161], v[182:185], v[82:85]
	v_mfma_f32_16x16x32_bf16 v[82:85], v[154:157], v[178:181], v[82:85]
	v_mfma_f32_16x16x32_bf16 v[66:69], v[154:157], v[186:189], v[66:69]
	v_mfma_f32_16x16x32_bf16 v[66:69], v[158:161], v[190:193], v[66:69]
	v_mfma_f32_16x16x32_bf16 v[70:73], v[150:153], v[190:193], v[70:73]
	v_mfma_f32_16x16x32_bf16 v[70:73], v[146:149], v[186:189], v[70:73]
	s_barrier
	s_setprio 0
	s_add_u32 s30, s8, 0xffff8000
	s_addc_u32 s31, s9, -1
	s_add_i32 s44, s44, s41
	s_mov_b32 m0, s44
	ds_read_b128 v[162:165], v231 offset:49152
	ds_read_b128 v[166:169], v231 offset:50176
	ds_read_b128 v[170:173], v231 offset:51200
	ds_read_b128 v[174:177], v231 offset:52224
	ds_read_b128 v[178:181], v231 offset:53248
	ds_read_b128 v[182:185], v231 offset:54272
	ds_read_b128 v[186:189], v231 offset:55296
	ds_read_b128 v[190:193], v231 offset:56320
	global_load_lds_dwordx4 v196, s[30:31]
	s_add_i32 m0, s44, 0x2000
	s_add_u32 s8, s8, 0xffffc000
	v_lshl_add_u64 v[202:203], s[30:31], 0, v[200:201]
	s_addc_u32 s9, s9, -1
	s_add_i32 s30, s65, s41
	global_load_lds_dwordx4 v[202:203], off
	s_mov_b32 m0, s30
	s_nop 0
	global_load_lds_dwordx4 v196, s[8:9]
	s_add_i32 m0, s30, 0x2000
	s_nop 0
	global_load_lds_dwordx4 v200, s[8:9]
	s_mov_b32 m0, s71
	s_nop 0
	global_load_lds_dwordx4 v194, s[34:35]
	v_lshl_add_u64 v[202:203], s[34:35], 0, v[198:199]
	s_mov_b32 m0, s80
	s_nop 0
	global_load_lds_dwordx4 v[202:203], off
	s_waitcnt vmcnt(8)
	s_waitcnt lgkmcnt(0)
	s_barrier
	s_setprio 1
	v_mfma_f32_16x16x32_bf16 v[62:65], v[130:133], v[162:165], v[62:65]
	v_mfma_f32_16x16x32_bf16 v[62:65], v[134:137], v[166:169], v[62:65]
	v_mfma_f32_16x16x32_bf16 v[58:61], v[142:145], v[166:169], v[58:61]
	v_mfma_f32_16x16x32_bf16 v[58:61], v[138:141], v[162:165], v[58:61]
	v_mfma_f32_16x16x32_bf16 v[42:45], v[138:141], v[170:173], v[42:45]
	v_mfma_f32_16x16x32_bf16 v[42:45], v[142:145], v[174:177], v[42:45]
	v_mfma_f32_16x16x32_bf16 v[46:49], v[134:137], v[174:177], v[46:49]
	v_mfma_f32_16x16x32_bf16 v[46:49], v[130:133], v[170:173], v[46:49]
	v_mfma_f32_16x16x32_bf16 v[30:33], v[130:133], v[178:181], v[30:33]
	v_mfma_f32_16x16x32_bf16 v[30:33], v[134:137], v[182:185], v[30:33]
	v_mfma_f32_16x16x32_bf16 v[26:29], v[142:145], v[182:185], v[26:29]
	v_mfma_f32_16x16x32_bf16 v[26:29], v[138:141], v[178:181], v[26:29]
	v_mfma_f32_16x16x32_bf16 v[10:13], v[138:141], v[186:189], v[10:13]
	v_mfma_f32_16x16x32_bf16 v[10:13], v[142:145], v[190:193], v[10:13]
	v_mfma_f32_16x16x32_bf16 v[14:17], v[134:137], v[190:193], v[14:17]
	v_mfma_f32_16x16x32_bf16 v[14:17], v[130:133], v[186:189], v[14:17]
	v_mfma_f32_16x16x32_bf16 v[54:57], v[146:149], v[162:165], v[54:57]
	v_mfma_f32_16x16x32_bf16 v[54:57], v[150:153], v[166:169], v[54:57]
	v_mfma_f32_16x16x32_bf16 v[50:53], v[158:161], v[166:169], v[50:53]
	v_mfma_f32_16x16x32_bf16 v[50:53], v[154:157], v[162:165], v[50:53]
	v_mfma_f32_16x16x32_bf16 v[34:37], v[154:157], v[170:173], v[34:37]
	v_mfma_f32_16x16x32_bf16 v[34:37], v[158:161], v[174:177], v[34:37]
	v_mfma_f32_16x16x32_bf16 v[38:41], v[150:153], v[174:177], v[38:41]
	v_mfma_f32_16x16x32_bf16 v[38:41], v[146:149], v[170:173], v[38:41]
	v_mfma_f32_16x16x32_bf16 v[22:25], v[146:149], v[178:181], v[22:25]
	v_mfma_f32_16x16x32_bf16 v[22:25], v[150:153], v[182:185], v[22:25]
	v_mfma_f32_16x16x32_bf16 v[18:21], v[158:161], v[182:185], v[18:21]
	v_mfma_f32_16x16x32_bf16 v[18:21], v[154:157], v[178:181], v[18:21]
	v_mfma_f32_16x16x32_bf16 v[2:5], v[154:157], v[186:189], v[2:5]
	v_mfma_f32_16x16x32_bf16 v[2:5], v[158:161], v[190:193], v[2:5]
	v_mfma_f32_16x16x32_bf16 v[6:9], v[150:153], v[190:193], v[6:9]
	v_mfma_f32_16x16x32_bf16 v[6:9], v[146:149], v[186:189], v[6:9]
	s_barrier
	s_setprio 0
	s_cmpk_gt_u32 s56, 0x55
	s_mov_b32 s56, s57
	s_cbranch_scc1 .LBB0_1449
